# MFMA order in GEMM K-loops: accumulate chains visited column-major in a 32-wide snake (first source operand = B fragment shared along each column of 4 row blocks), K order of each pair starts with the
# speedup vs baseline: 1.0189x; 1.0003x over previous
; #define PG8_STAGE(bufoff, gbase, voff) do { _Pragma("unroll") for (int _i = 0; _i < 2; ++_i) \
;         __builtin_amdgcn_global_load_lds((const unsigned*)((const char*)(gbase) + (voff)[_i]), (LAS unsigned*)(lds + (bufoff) + ldsw + _i * 8192), 16, 0, 0); } while (0)
; #define PG8_LDA(dst, b, h) do { _Pragma("unroll") for (int m = 0; m < 4; ++m) _Pragma("unroll") for (int k = 0; k < 2; ++k) dst[m][k] = *(const LAS bf16x8*)(lds + PG8_SA(b, h) + aoff + m * 2048 + k * 1024); } while (0)
; #define PG8_LDB(dst, b, h) do { _Pragma("unroll") for (int n = 0; n < 2; ++n) _Pragma("unroll") for (int k = 0; k < 2; ++k) dst[n][k] = *(const LAS bf16x8*)(lds + PG8_SB(b, h) + boff + n * 2048 + k * 1024); } while (0)
; #define PG8_SCHED __builtin_amdgcn_sched_barrier(0)
; template <class Epi, bool ALIGN_EPI>
; __device__ __forceinline__ void gemm_phase(LAS unsigned char* lds, const Gemm g, const StaticOrder& S, const Epi& E, const int tid) {
;     ...
;             PG8_LDB(B0, 0, 0); PG8_LDB(B1, 0, 1); PG8_SCHED; PG8_LDA(At, 0, 0); PG8_STAGE(PG8_SA(1, 1), a1 + hstepA, voffA);
.LBB0_211:
	s_add_u32 s50, s48, 0x4000
	s_addc_u32 s51, s49, 0
	s_cmp_eq_u32 s89, 28
	s_cselect_b32 s54, s87, s50
	s_cselect_b32 s55, s43, s51
	s_cselect_b32 s52, vcc_lo, vcc_hi
	s_cselect_b32 s53, s35, s88
	s_add_u32 s50, s54, 0x8000
	s_addc_u32 s51, s55, 0
	s_add_i32 s90, 0, 0x10000
	v_add_u32_e32 v0, s90, v160
	s_add_i32 s92, 0, 0x14000
	ds_read_b128 v[132:135], v0
	ds_read_b128 v[136:139], v0 offset:1024
	ds_read_b128 v[152:155], v0 offset:2048
	ds_read_b128 v[156:159], v0 offset:3072
	v_add_u32_e32 v0, s92, v160
	ds_read_b128 v[162:165], v0
	ds_read_b128 v[166:169], v0 offset:1024
	ds_read_b128 v[170:173], v0 offset:2048
	ds_read_b128 v[174:177], v0 offset:3072
	s_add_i32 m0, s72, 0xc000
	ds_read_b128 v[178:181], v161
	ds_read_b128 v[182:185], v161 offset:1024
	ds_read_b128 v[186:189], v161 offset:2048
	ds_read_b128 v[190:193], v161 offset:3072
	ds_read_b128 v[194:197], v161 offset:4096
	ds_read_b128 v[198:201], v161 offset:5120
	ds_read_b128 v[214:217], v161 offset:6144

; #define PG8_STAGE(bufoff, gbase, voff) do { _Pragma("unroll") for (int _i = 0; _i < 2; ++_i) \
;         __builtin_amdgcn_global_load_lds((const unsigned*)((const char*)(gbase) + (voff)[_i]), (LAS unsigned*)(lds + (bufoff) + ldsw + _i * 8192), 16, 0, 0); } while (0)
; #define PG8_LDA(dst, b, h) do { _Pragma("unroll") for (int m = 0; m < 4; ++m) _Pragma("unroll") for (int k = 0; k < 2; ++k) dst[m][k] = *(const LAS bf16x8*)(lds + PG8_SA(b, h) + aoff + m * 2048 + k * 1024); } while (0)
; #define PG8_LDB(dst, b, h) do { _Pragma("unroll") for (int n = 0; n < 2; ++n) _Pragma("unroll") for (int k = 0; k < 2; ++k) dst[n][k] = *(const LAS bf16x8*)(lds + PG8_SB(b, h) + boff + n * 2048 + k * 1024); } while (0)
; #define PG8_MMA(ai, bj, At, Bt) do { __builtin_amdgcn_s_setprio(1); _Pragma("unroll") for (int m = 0; m < 4; ++m) _Pragma("unroll") for (int n = 0; n < 2; ++n) _Pragma("unroll") for (int k = 0; k < 2; ++k) \
;         acc[ai][bj][m][n] = __builtin_amdgcn_mfma_f32_16x16x32_bf16(Bt[n][k], At[m][k], acc[ai][bj][m][n], 0, 0, 0); __builtin_amdgcn_s_setprio(0); } while (0)
; #define PG8_WAIT_V(n) asm volatile("s_waitcnt vmcnt(" #n ")" ::: "memory")
; #define PG8_WAIT_L(n) asm volatile("s_waitcnt lgkmcnt(" #n ")" ::: "memory")
; #define PG8_BAR __builtin_amdgcn_s_barrier()
; #define PG8_SCHED __builtin_amdgcn_sched_barrier(0)
; template <class Epi, bool ALIGN_EPI>
; __device__ __forceinline__ void gemm_phase(LAS unsigned char* lds, const Gemm g, const StaticOrder& S, const Epi& E, const int tid) {
;     ...
;             PG8_LDB(B0, 0, 0); PG8_LDB(B1, 0, 1); PG8_SCHED; PG8_LDA(At, 0, 0); PG8_STAGE(PG8_SA(1, 1), a1 + hstepA, voffA);
;             PG8_WAIT_V(8); PG8_WAIT_L(0); PG8_BAR; PG8_MMA(0, 0, At, B0); PG8_MMA(0, 1, At, B1); PG8_BAR; PG8_SCHED;
	global_load_lds_dwordx4 v148, s[48:49]
	s_add_i32 m0, s72, 0xe000
	ds_read_b128 v[218:221], v161 offset:7168
	global_load_lds_dwordx4 v150, s[48:49]
	s_waitcnt vmcnt(8)
	s_waitcnt lgkmcnt(0)
	s_barrier


; #define PG8_MMA(ai, bj, At, Bt) do { __builtin_amdgcn_s_setprio(1); _Pragma("unroll") for (int m = 0; m < 4; ++m) _Pragma("unroll") for (int n = 0; n < 2; ++n) _Pragma("unroll") for (int k = 0; k < 2; ++k) \
;         acc[ai][bj][m][n] = __builtin_amdgcn_mfma_f32_16x16x32_bf16(Bt[n][k], At[m][k], acc[ai][bj][m][n], 0, 0, 0); __builtin_amdgcn_s_setprio(0); } while (0)
; #define PG8_WAIT_V(n) asm volatile("s_waitcnt vmcnt(" #n ")" ::: "memory")
; #define PG8_WAIT_L(n) asm volatile("s_waitcnt lgkmcnt(" #n ")" ::: "memory")
; #define PG8_BAR __builtin_amdgcn_s_barrier()
; #define PG8_SCHED __builtin_amdgcn_sched_barrier(0)
; template <class Epi, bool ALIGN_EPI>
; __device__ __forceinline__ void gemm_phase(LAS unsigned char* lds, const Gemm g, const StaticOrder& S, const Epi& E, const int tid) {
;     ...
;             PG8_WAIT_V(8); PG8_WAIT_L(0); PG8_BAR; PG8_MMA(0, 0, At, B0); PG8_MMA(0, 1, At, B1); PG8_BAR; PG8_SCHED;
	v_mfma_f32_16x16x32_bf16 v[88:91], v[132:135], v[178:181], v[88:91]
	v_mfma_f32_16x16x32_bf16 v[88:91], v[136:139], v[182:185], v[88:91]
	v_mfma_f32_16x16x32_bf16 v[52:55], v[136:139], v[190:193], v[52:55]
	v_mfma_f32_16x16x32_bf16 v[52:55], v[132:135], v[186:189], v[52:55]
	v_mfma_f32_16x16x32_bf16 v[40:43], v[132:135], v[194:197], v[40:43]
	v_mfma_f32_16x16x32_bf16 v[40:43], v[136:139], v[198:201], v[40:43]
	v_mfma_f32_16x16x32_bf16 v[36:39], v[136:139], v[218:221], v[36:39]
	v_mfma_f32_16x16x32_bf16 v[36:39], v[132:135], v[214:217], v[36:39]
	v_mfma_f32_16x16x32_bf16 v[112:115], v[152:155], v[214:217], v[112:115]
	v_mfma_f32_16x16x32_bf16 v[112:115], v[156:159], v[218:221], v[112:115]
	v_mfma_f32_16x16x32_bf16 v[116:119], v[156:159], v[198:201], v[116:119]
	v_mfma_f32_16x16x32_bf16 v[116:119], v[152:155], v[194:197], v[116:119]
	v_mfma_f32_16x16x32_bf16 v[120:123], v[152:155], v[186:189], v[120:123]
	v_mfma_f32_16x16x32_bf16 v[120:123], v[156:159], v[190:193], v[120:123]
	v_mfma_f32_16x16x32_bf16 v[124:127], v[156:159], v[182:185], v[124:127]
	v_mfma_f32_16x16x32_bf16 v[124:127], v[152:155], v[178:181], v[124:127]


; #define PG8_MMA(ai, bj, At, Bt) do { __builtin_amdgcn_s_setprio(1); _Pragma("unroll") for (int m = 0; m < 4; ++m) _Pragma("unroll") for (int n = 0; n < 2; ++n) _Pragma("unroll") for (int k = 0; k < 2; ++k) \
;         acc[ai][bj][m][n] = __builtin_amdgcn_mfma_f32_16x16x32_bf16(Bt[n][k], At[m][k], acc[ai][bj][m][n], 0, 0, 0); __builtin_amdgcn_s_setprio(0); } while (0)
; #define PG8_WAIT_V(n) asm volatile("s_waitcnt vmcnt(" #n ")" ::: "memory")
; #define PG8_WAIT_L(n) asm volatile("s_waitcnt lgkmcnt(" #n ")" ::: "memory")
; #define PG8_BAR __builtin_amdgcn_s_barrier()
; #define PG8_SCHED __builtin_amdgcn_sched_barrier(0)
; template <class Epi, bool ALIGN_EPI>
; __device__ __forceinline__ void gemm_phase(LAS unsigned char* lds, const Gemm g, const StaticOrder& S, const Epi& E, const int tid) {
;     ...
;             PG8_WAIT_V(8); PG8_WAIT_L(0); PG8_BAR; PG8_MMA(0, 0, At, B0); PG8_MMA(0, 1, At, B1); PG8_BAR; PG8_SCHED;
	v_mfma_f32_16x16x32_bf16 v[128:131], v[170:173], v[178:181], v[128:131]
	v_mfma_f32_16x16x32_bf16 v[128:131], v[174:177], v[182:185], v[128:131]
	v_mfma_f32_16x16x32_bf16 v[108:111], v[174:177], v[190:193], v[108:111]
	v_mfma_f32_16x16x32_bf16 v[108:111], v[170:173], v[186:189], v[108:111]
	v_mfma_f32_16x16x32_bf16 v[104:107], v[170:173], v[194:197], v[104:107]
	v_mfma_f32_16x16x32_bf16 v[104:107], v[174:177], v[198:201], v[104:107]
	v_mfma_f32_16x16x32_bf16 v[100:103], v[174:177], v[218:221], v[100:103]
	v_mfma_f32_16x16x32_bf16 v[100:103], v[170:173], v[214:217], v[100:103]
	v_mfma_f32_16x16x32_bf16 v[48:51], v[162:165], v[214:217], v[48:51]
	v_mfma_f32_16x16x32_bf16 v[48:51], v[166:169], v[218:221], v[48:51]
	v_mfma_f32_16x16x32_bf16 v[60:63], v[166:169], v[198:201], v[60:63]
	v_mfma_f32_16x16x32_bf16 v[60:63], v[162:165], v[194:197], v[60:63]
	v_mfma_f32_16x16x32_bf16 v[68:71], v[162:165], v[186:189], v[68:71]
	v_mfma_f32_16x16x32_bf16 v[68:71], v[166:169], v[190:193], v[68:71]
	v_mfma_f32_16x16x32_bf16 v[80:83], v[166:169], v[182:185], v[80:83]
	v_mfma_f32_16x16x32_bf16 v[80:83], v[162:165], v[178:181], v[80:83]

; #define PG8_STAGE(bufoff, gbase, voff) do { _Pragma("unroll") for (int _i = 0; _i < 2; ++_i) \
;         __builtin_amdgcn_global_load_lds((const unsigned*)((const char*)(gbase) + (voff)[_i]), (LAS unsigned*)(lds + (bufoff) + ldsw + _i * 8192), 16, 0, 0); } while (0)
; #define PG8_LDA(dst, b, h) do { _Pragma("unroll") for (int m = 0; m < 4; ++m) _Pragma("unroll") for (int k = 0; k < 2; ++k) dst[m][k] = *(const LAS bf16x8*)(lds + PG8_SA(b, h) + aoff + m * 2048 + k * 1024); } while (0)
; #define PG8_MMA(ai, bj, At, Bt) do { __builtin_amdgcn_s_setprio(1); _Pragma("unroll") for (int m = 0; m < 4; ++m) _Pragma("unroll") for (int n = 0; n < 2; ++n) _Pragma("unroll") for (int k = 0; k < 2; ++k) \
;         acc[ai][bj][m][n] = __builtin_amdgcn_mfma_f32_16x16x32_bf16(Bt[n][k], At[m][k], acc[ai][bj][m][n], 0, 0, 0); __builtin_amdgcn_s_setprio(0); } while (0)
; #define PG8_WAIT_V(n) asm volatile("s_waitcnt vmcnt(" #n ")" ::: "memory")
; #define PG8_WAIT_L(n) asm volatile("s_waitcnt lgkmcnt(" #n ")" ::: "memory")
; #define PG8_BAR __builtin_amdgcn_s_barrier()
; #define PG8_SCHED __builtin_amdgcn_sched_barrier(0)
; template <class Epi, bool ALIGN_EPI>
; __device__ __forceinline__ void gemm_phase(LAS unsigned char* lds, const Gemm g, const StaticOrder& S, const Epi& E, const int tid) {
;     ...
;             PG8_WAIT_V(8); PG8_WAIT_L(0); PG8_BAR; PG8_MMA(0, 0, At, B0); PG8_MMA(0, 1, At, B1); PG8_BAR; PG8_SCHED;
;             PG8_LDA(At, 0, 1); PG8_STAGE(PG8_SB(0, 0), b2, voffB); PG8_STAGE(PG8_SB(0, 1), b2 + hstepB, voffB); PG8_STAGE(PG8_SA(0, 0), a2, voffA);
	s_barrier
	s_add_i32 s90, s90, s71
	s_mov_b32 m0, s90
	ds_read_b128 v[178:181], v161 offset:16384
	ds_read_b128 v[182:185], v161 offset:17408
	ds_read_b128 v[186:189], v161 offset:18432
	ds_read_b128 v[190:193], v161 offset:19456


; #define PG8_STAGE(bufoff, gbase, voff) do { _Pragma("unroll") for (int _i = 0; _i < 2; ++_i) \
;         __builtin_amdgcn_global_load_lds((const unsigned*)((const char*)(gbase) + (voff)[_i]), (LAS unsigned*)(lds + (bufoff) + ldsw + _i * 8192), 16, 0, 0); } while (0)
; #define PG8_LDA(dst, b, h) do { _Pragma("unroll") for (int m = 0; m < 4; ++m) _Pragma("unroll") for (int k = 0; k < 2; ++k) dst[m][k] = *(const LAS bf16x8*)(lds + PG8_SA(b, h) + aoff + m * 2048 + k * 1024); } while (0)
; #define PG8_MMA(ai, bj, At, Bt) do { __builtin_amdgcn_s_setprio(1); _Pragma("unroll") for (int m = 0; m < 4; ++m) _Pragma("unroll") for (int n = 0; n < 2; ++n) _Pragma("unroll") for (int k = 0; k < 2; ++k) \
;         acc[ai][bj][m][n] = __builtin_amdgcn_mfma_f32_16x16x32_bf16(Bt[n][k], At[m][k], acc[ai][bj][m][n], 0, 0, 0); __builtin_amdgcn_s_setprio(0); } while (0)
; #define PG8_WAIT_V(n) asm volatile("s_waitcnt vmcnt(" #n ")" ::: "memory")
; #define PG8_WAIT_L(n) asm volatile("s_waitcnt lgkmcnt(" #n ")" ::: "memory")
; #define PG8_BAR __builtin_amdgcn_s_barrier()
; #define PG8_SCHED __builtin_amdgcn_sched_barrier(0)
; template <class Epi, bool ALIGN_EPI>
; __device__ __forceinline__ void gemm_phase(LAS unsigned char* lds, const Gemm g, const StaticOrder& S, const Epi& E, const int tid) {
;     ...
;             PG8_LDA(At, 0, 1); PG8_STAGE(PG8_SB(0, 0), b2, voffB); PG8_STAGE(PG8_SB(0, 1), b2 + hstepB, voffB); PG8_STAGE(PG8_SA(0, 0), a2, voffA);
;             PG8_WAIT_V(8); PG8_WAIT_L(0); PG8_BAR; PG8_MMA(1, 0, At, B0); PG8_MMA(1, 1, At, B1); PG8_BAR; PG8_SCHED;
	global_load_lds_dwordx4 v144, s[52:53]
	s_add_i32 m0, s90, 0x2000
	s_add_u32 s90, s52, 0x4000
	s_addc_u32 s91, s53, 0
	s_add_i32 s92, s92, s71
	global_load_lds_dwordx4 v140, s[52:53]
	s_mov_b32 m0, s92
	ds_read_b128 v[218:221], v161 offset:23552
	global_load_lds_dwordx4 v144, s[90:91]
	s_add_i32 m0, s92, 0x2000
	ds_read_b128 v[214:217], v161 offset:22528
	global_load_lds_dwordx4 v140, s[90:91]
	s_mov_b32 m0, s72
	ds_read_b128 v[198:201], v161 offset:21504
	global_load_lds_dwordx4 v146, s[54:55]
	s_mov_b32 m0, s73
	ds_read_b128 v[194:197], v161 offset:20480
	global_load_lds_dwordx4 v142, s[54:55]
	s_waitcnt vmcnt(8)
	s_waitcnt lgkmcnt(0)
	s_barrier


; #define PG8_MMA(ai, bj, At, Bt) do { __builtin_amdgcn_s_setprio(1); _Pragma("unroll") for (int m = 0; m < 4; ++m) _Pragma("unroll") for (int n = 0; n < 2; ++n) _Pragma("unroll") for (int k = 0; k < 2; ++k) \
;         acc[ai][bj][m][n] = __builtin_amdgcn_mfma_f32_16x16x32_bf16(Bt[n][k], At[m][k], acc[ai][bj][m][n], 0, 0, 0); __builtin_amdgcn_s_setprio(0); } while (0)
; #define PG8_WAIT_V(n) asm volatile("s_waitcnt vmcnt(" #n ")" ::: "memory")
; #define PG8_WAIT_L(n) asm volatile("s_waitcnt lgkmcnt(" #n ")" ::: "memory")
; #define PG8_BAR __builtin_amdgcn_s_barrier()
; #define PG8_SCHED __builtin_amdgcn_sched_barrier(0)
; template <class Epi, bool ALIGN_EPI>
; __device__ __forceinline__ void gemm_phase(LAS unsigned char* lds, const Gemm g, const StaticOrder& S, const Epi& E, const int tid) {
;     ...
;             PG8_WAIT_V(8); PG8_WAIT_L(0); PG8_BAR; PG8_MMA(1, 0, At, B0); PG8_MMA(1, 1, At, B1); PG8_BAR; PG8_SCHED;
	v_mfma_f32_16x16x32_bf16 v[24:27], v[132:135], v[178:181], v[24:27]
	v_mfma_f32_16x16x32_bf16 v[24:27], v[136:139], v[182:185], v[24:27]
	v_mfma_f32_16x16x32_bf16 v[16:19], v[136:139], v[190:193], v[16:19]
	v_mfma_f32_16x16x32_bf16 v[16:19], v[132:135], v[186:189], v[16:19]
	v_mfma_f32_16x16x32_bf16 v[8:11], v[132:135], v[194:197], v[8:11]
	v_mfma_f32_16x16x32_bf16 v[8:11], v[136:139], v[198:201], v[8:11]
	v_mfma_f32_16x16x32_bf16 v[2:5], v[132:135], v[214:217], v[4:7]
	v_mfma_f32_16x16x32_bf16 v[2:5], v[136:139], v[218:221], v[2:5]
	v_mfma_f32_16x16x32_bf16 v[64:67], v[156:159], v[218:221], v[64:67]
	v_mfma_f32_16x16x32_bf16 v[64:67], v[152:155], v[214:217], v[64:67]
	v_mfma_f32_16x16x32_bf16 v[76:79], v[152:155], v[194:197], v[76:79]
	v_mfma_f32_16x16x32_bf16 v[76:79], v[156:159], v[198:201], v[76:79]
	v_mfma_f32_16x16x32_bf16 v[84:87], v[156:159], v[190:193], v[84:87]
	v_mfma_f32_16x16x32_bf16 v[84:87], v[152:155], v[186:189], v[84:87]
	v_mfma_f32_16x16x32_bf16 v[92:95], v[152:155], v[178:181], v[92:95]
	v_mfma_f32_16x16x32_bf16 v[92:95], v[156:159], v[182:185], v[92:95]


; #define PG8_MMA(ai, bj, At, Bt) do { __builtin_amdgcn_s_setprio(1); _Pragma("unroll") for (int m = 0; m < 4; ++m) _Pragma("unroll") for (int n = 0; n < 2; ++n) _Pragma("unroll") for (int k = 0; k < 2; ++k) \
;         acc[ai][bj][m][n] = __builtin_amdgcn_mfma_f32_16x16x32_bf16(Bt[n][k], At[m][k], acc[ai][bj][m][n], 0, 0, 0); __builtin_amdgcn_s_setprio(0); } while (0)
; #define PG8_WAIT_V(n) asm volatile("s_waitcnt vmcnt(" #n ")" ::: "memory")
; #define PG8_WAIT_L(n) asm volatile("s_waitcnt lgkmcnt(" #n ")" ::: "memory")
; #define PG8_BAR __builtin_amdgcn_s_barrier()
; #define PG8_SCHED __builtin_amdgcn_sched_barrier(0)
; template <class Epi, bool ALIGN_EPI>
; __device__ __forceinline__ void gemm_phase(LAS unsigned char* lds, const Gemm g, const StaticOrder& S, const Epi& E, const int tid) {
;     ...
;             PG8_WAIT_V(8); PG8_WAIT_L(0); PG8_BAR; PG8_MMA(1, 0, At, B0); PG8_MMA(1, 1, At, B1); PG8_BAR; PG8_SCHED;
	v_mfma_f32_16x16x32_bf16 v[72:75], v[174:177], v[182:185], v[72:75]
	v_mfma_f32_16x16x32_bf16 v[72:75], v[170:173], v[178:181], v[72:75]
	v_mfma_f32_16x16x32_bf16 v[96:99], v[170:173], v[186:189], v[96:99]
	v_mfma_f32_16x16x32_bf16 v[96:99], v[174:177], v[190:193], v[96:99]
	v_mfma_f32_16x16x32_bf16 v[56:59], v[174:177], v[198:201], v[56:59]
	v_mfma_f32_16x16x32_bf16 v[56:59], v[170:173], v[194:197], v[56:59]
	v_mfma_f32_16x16x32_bf16 v[44:47], v[170:173], v[214:217], v[44:47]
	v_mfma_f32_16x16x32_bf16 v[44:47], v[174:177], v[218:221], v[44:47]
	v_mfma_f32_16x16x32_bf16 v[12:15], v[166:169], v[218:221], v[12:15]
	v_mfma_f32_16x16x32_bf16 v[12:15], v[162:165], v[214:217], v[12:15]
	v_mfma_f32_16x16x32_bf16 v[20:23], v[162:165], v[194:197], v[20:23]
	v_mfma_f32_16x16x32_bf16 v[20:23], v[166:169], v[198:201], v[20:23]
	v_mfma_f32_16x16x32_bf16 v[28:31], v[166:169], v[190:193], v[28:31]
	v_mfma_f32_16x16x32_bf16 v[28:31], v[162:165], v[186:189], v[28:31]
	v_mfma_f32_16x16x32_bf16 v[32:35], v[162:165], v[178:181], v[32:35]
	v_mfma_f32_16x16x32_bf16 v[32:35], v[166:169], v[182:185], v[32:35]

; #define PG8_STAGE(bufoff, gbase, voff) do { _Pragma("unroll") for (int _i = 0; _i < 2; ++_i) \
;         __builtin_amdgcn_global_load_lds((const unsigned*)((const char*)(gbase) + (voff)[_i]), (LAS unsigned*)(lds + (bufoff) + ldsw + _i * 8192), 16, 0, 0); } while (0)
; #define PG8_LDA(dst, b, h) do { _Pragma("unroll") for (int m = 0; m < 4; ++m) _Pragma("unroll") for (int k = 0; k < 2; ++k) dst[m][k] = *(const LAS bf16x8*)(lds + PG8_SA(b, h) + aoff + m * 2048 + k * 1024); } while (0)
; #define PG8_LDB(dst, b, h) do { _Pragma("unroll") for (int n = 0; n < 2; ++n) _Pragma("unroll") for (int k = 0; k < 2; ++k) dst[n][k] = *(const LAS bf16x8*)(lds + PG8_SB(b, h) + boff + n * 2048 + k * 1024); } while (0)
; #define PG8_SCHED __builtin_amdgcn_sched_barrier(0)
; template <class Epi, bool ALIGN_EPI>
; __device__ __forceinline__ void gemm_phase(LAS unsigned char* lds, const Gemm g, const StaticOrder& S, const Epi& E, const int tid) {
;     ...
;             PG8_LDB(B0, 1, 0); PG8_LDB(B1, 1, 1); PG8_SCHED; PG8_LDA(At, 1, 0); PG8_STAGE(PG8_SA(0, 1), a2 + hstepA, voffA);
	s_barrier
	s_add_i32 s90, 0, 0x18000
	v_add_u32_e32 v0, s90, v160
	s_add_i32 s91, 0, 0x1c000
	ds_read_b128 v[132:135], v0
	ds_read_b128 v[136:139], v0 offset:1024
	ds_read_b128 v[152:155], v0 offset:2048
	ds_read_b128 v[156:159], v0 offset:3072
	v_add_u32_e32 v0, s91, v160
	ds_read_b128 v[162:165], v0
	ds_read_b128 v[166:169], v0 offset:1024
	ds_read_b128 v[170:173], v0 offset:2048
	ds_read_b128 v[174:177], v0 offset:3072
	s_add_u32 s54, s54, 0x4000
	s_addc_u32 s55, s55, 0
	s_mov_b32 m0, s74
	ds_read_b128 v[178:181], v161 offset:32768
	ds_read_b128 v[182:185], v161 offset:33792
	ds_read_b128 v[186:189], v161 offset:34816
	ds_read_b128 v[190:193], v161 offset:35840
	ds_read_b128 v[194:197], v161 offset:36864
	ds_read_b128 v[198:201], v161 offset:37888
	ds_read_b128 v[214:217], v161 offset:38912

; #define PG8_STAGE(bufoff, gbase, voff) do { _Pragma("unroll") for (int _i = 0; _i < 2; ++_i) \
;         __builtin_amdgcn_global_load_lds((const unsigned*)((const char*)(gbase) + (voff)[_i]), (LAS unsigned*)(lds + (bufoff) + ldsw + _i * 8192), 16, 0, 0); } while (0)
; #define PG8_LDA(dst, b, h) do { _Pragma("unroll") for (int m = 0; m < 4; ++m) _Pragma("unroll") for (int k = 0; k < 2; ++k) dst[m][k] = *(const LAS bf16x8*)(lds + PG8_SA(b, h) + aoff + m * 2048 + k * 1024); } while (0)
; #define PG8_LDB(dst, b, h) do { _Pragma("unroll") for (int n = 0; n < 2; ++n) _Pragma("unroll") for (int k = 0; k < 2; ++k) dst[n][k] = *(const LAS bf16x8*)(lds + PG8_SB(b, h) + boff + n * 2048 + k * 1024); } while (0)
; #define PG8_MMA(ai, bj, At, Bt) do { __builtin_amdgcn_s_setprio(1); _Pragma("unroll") for (int m = 0; m < 4; ++m) _Pragma("unroll") for (int n = 0; n < 2; ++n) _Pragma("unroll") for (int k = 0; k < 2; ++k) \
;         acc[ai][bj][m][n] = __builtin_amdgcn_mfma_f32_16x16x32_bf16(Bt[n][k], At[m][k], acc[ai][bj][m][n], 0, 0, 0); __builtin_amdgcn_s_setprio(0); } while (0)
; #define PG8_WAIT_V(n) asm volatile("s_waitcnt vmcnt(" #n ")" ::: "memory")
; #define PG8_WAIT_L(n) asm volatile("s_waitcnt lgkmcnt(" #n ")" ::: "memory")
; #define PG8_BAR __builtin_amdgcn_s_barrier()
; #define PG8_SCHED __builtin_amdgcn_sched_barrier(0)
; template <class Epi, bool ALIGN_EPI>
; __device__ __forceinline__ void gemm_phase(LAS unsigned char* lds, const Gemm g, const StaticOrder& S, const Epi& E, const int tid) {
;     ...
;             PG8_LDB(B0, 1, 0); PG8_LDB(B1, 1, 1); PG8_SCHED; PG8_LDA(At, 1, 0); PG8_STAGE(PG8_SA(0, 1), a2 + hstepA, voffA);
;             PG8_WAIT_V(8); PG8_WAIT_L(0); PG8_BAR; PG8_MMA(0, 0, At, B0); PG8_MMA(0, 1, At, B1); PG8_BAR; PG8_SCHED;
	global_load_lds_dwordx4 v146, s[54:55]
	s_mov_b32 m0, s75
	ds_read_b128 v[218:221], v161 offset:39936
	global_load_lds_dwordx4 v142, s[54:55]
	s_waitcnt vmcnt(8)
	s_waitcnt lgkmcnt(0)
	s_barrier


; #define PG8_MMA(ai, bj, At, Bt) do { __builtin_amdgcn_s_setprio(1); _Pragma("unroll") for (int m = 0; m < 4; ++m) _Pragma("unroll") for (int n = 0; n < 2; ++n) _Pragma("unroll") for (int k = 0; k < 2; ++k) \
;         acc[ai][bj][m][n] = __builtin_amdgcn_mfma_f32_16x16x32_bf16(Bt[n][k], At[m][k], acc[ai][bj][m][n], 0, 0, 0); __builtin_amdgcn_s_setprio(0); } while (0)
; #define PG8_WAIT_V(n) asm volatile("s_waitcnt vmcnt(" #n ")" ::: "memory")
; #define PG8_WAIT_L(n) asm volatile("s_waitcnt lgkmcnt(" #n ")" ::: "memory")
; #define PG8_BAR __builtin_amdgcn_s_barrier()
; #define PG8_SCHED __builtin_amdgcn_sched_barrier(0)
; template <class Epi, bool ALIGN_EPI>
; __device__ __forceinline__ void gemm_phase(LAS unsigned char* lds, const Gemm g, const StaticOrder& S, const Epi& E, const int tid) {
;     ...
;             PG8_WAIT_V(8); PG8_WAIT_L(0); PG8_BAR; PG8_MMA(0, 0, At, B0); PG8_MMA(0, 1, At, B1); PG8_BAR; PG8_SCHED;
	v_mfma_f32_16x16x32_bf16 v[88:91], v[132:135], v[178:181], v[88:91]
	v_mfma_f32_16x16x32_bf16 v[88:91], v[136:139], v[182:185], v[88:91]
	v_mfma_f32_16x16x32_bf16 v[52:55], v[136:139], v[190:193], v[52:55]
	v_mfma_f32_16x16x32_bf16 v[52:55], v[132:135], v[186:189], v[52:55]
	v_mfma_f32_16x16x32_bf16 v[40:43], v[132:135], v[194:197], v[40:43]
	v_mfma_f32_16x16x32_bf16 v[40:43], v[136:139], v[198:201], v[40:43]
	v_mfma_f32_16x16x32_bf16 v[36:39], v[136:139], v[218:221], v[36:39]
	v_mfma_f32_16x16x32_bf16 v[36:39], v[132:135], v[214:217], v[36:39]
	v_mfma_f32_16x16x32_bf16 v[112:115], v[152:155], v[214:217], v[112:115]
	v_mfma_f32_16x16x32_bf16 v[112:115], v[156:159], v[218:221], v[112:115]
	v_mfma_f32_16x16x32_bf16 v[116:119], v[156:159], v[198:201], v[116:119]
	v_mfma_f32_16x16x32_bf16 v[116:119], v[152:155], v[194:197], v[116:119]
	v_mfma_f32_16x16x32_bf16 v[120:123], v[152:155], v[186:189], v[120:123]
	v_mfma_f32_16x16x32_bf16 v[120:123], v[156:159], v[190:193], v[120:123]
	v_mfma_f32_16x16x32_bf16 v[124:127], v[156:159], v[182:185], v[124:127]
	v_mfma_f32_16x16x32_bf16 v[124:127], v[152:155], v[178:181], v[124:127]


; #define PG8_MMA(ai, bj, At, Bt) do { __builtin_amdgcn_s_setprio(1); _Pragma("unroll") for (int m = 0; m < 4; ++m) _Pragma("unroll") for (int n = 0; n < 2; ++n) _Pragma("unroll") for (int k = 0; k < 2; ++k) \
;         acc[ai][bj][m][n] = __builtin_amdgcn_mfma_f32_16x16x32_bf16(Bt[n][k], At[m][k], acc[ai][bj][m][n], 0, 0, 0); __builtin_amdgcn_s_setprio(0); } while (0)
; #define PG8_WAIT_V(n) asm volatile("s_waitcnt vmcnt(" #n ")" ::: "memory")
; #define PG8_WAIT_L(n) asm volatile("s_waitcnt lgkmcnt(" #n ")" ::: "memory")
; #define PG8_BAR __builtin_amdgcn_s_barrier()
; #define PG8_SCHED __builtin_amdgcn_sched_barrier(0)
; template <class Epi, bool ALIGN_EPI>
; __device__ __forceinline__ void gemm_phase(LAS unsigned char* lds, const Gemm g, const StaticOrder& S, const Epi& E, const int tid) {
;     ...
;             PG8_WAIT_V(8); PG8_WAIT_L(0); PG8_BAR; PG8_MMA(0, 0, At, B0); PG8_MMA(0, 1, At, B1); PG8_BAR; PG8_SCHED;
	v_mfma_f32_16x16x32_bf16 v[128:131], v[170:173], v[178:181], v[128:131]
	v_mfma_f32_16x16x32_bf16 v[128:131], v[174:177], v[182:185], v[128:131]
	v_mfma_f32_16x16x32_bf16 v[108:111], v[174:177], v[190:193], v[108:111]
	v_mfma_f32_16x16x32_bf16 v[108:111], v[170:173], v[186:189], v[108:111]
	v_mfma_f32_16x16x32_bf16 v[104:107], v[170:173], v[194:197], v[104:107]
	v_mfma_f32_16x16x32_bf16 v[104:107], v[174:177], v[198:201], v[104:107]
	v_mfma_f32_16x16x32_bf16 v[100:103], v[174:177], v[218:221], v[100:103]
	v_mfma_f32_16x16x32_bf16 v[100:103], v[170:173], v[214:217], v[100:103]
	v_mfma_f32_16x16x32_bf16 v[48:51], v[162:165], v[214:217], v[48:51]
	v_mfma_f32_16x16x32_bf16 v[48:51], v[166:169], v[218:221], v[48:51]
	v_mfma_f32_16x16x32_bf16 v[60:63], v[166:169], v[198:201], v[60:63]
	v_mfma_f32_16x16x32_bf16 v[60:63], v[162:165], v[194:197], v[60:63]
	v_mfma_f32_16x16x32_bf16 v[68:71], v[162:165], v[186:189], v[68:71]
	v_mfma_f32_16x16x32_bf16 v[68:71], v[166:169], v[190:193], v[68:71]
	v_mfma_f32_16x16x32_bf16 v[80:83], v[166:169], v[182:185], v[80:83]
	v_mfma_f32_16x16x32_bf16 v[80:83], v[162:165], v[178:181], v[80:83]

; #define PG8_STAGE(bufoff, gbase, voff) do { _Pragma("unroll") for (int _i = 0; _i < 2; ++_i) \
;         __builtin_amdgcn_global_load_lds((const unsigned*)((const char*)(gbase) + (voff)[_i]), (LAS unsigned*)(lds + (bufoff) + ldsw + _i * 8192), 16, 0, 0); } while (0)
; #define PG8_LDA(dst, b, h) do { _Pragma("unroll") for (int m = 0; m < 4; ++m) _Pragma("unroll") for (int k = 0; k < 2; ++k) dst[m][k] = *(const LAS bf16x8*)(lds + PG8_SA(b, h) + aoff + m * 2048 + k * 1024); } while (0)
; #define PG8_MMA(ai, bj, At, Bt) do { __builtin_amdgcn_s_setprio(1); _Pragma("unroll") for (int m = 0; m < 4; ++m) _Pragma("unroll") for (int n = 0; n < 2; ++n) _Pragma("unroll") for (int k = 0; k < 2; ++k) \
;         acc[ai][bj][m][n] = __builtin_amdgcn_mfma_f32_16x16x32_bf16(Bt[n][k], At[m][k], acc[ai][bj][m][n], 0, 0, 0); __builtin_amdgcn_s_setprio(0); } while (0)
; #define PG8_WAIT_V(n) asm volatile("s_waitcnt vmcnt(" #n ")" ::: "memory")
; #define PG8_WAIT_L(n) asm volatile("s_waitcnt lgkmcnt(" #n ")" ::: "memory")
; #define PG8_BAR __builtin_amdgcn_s_barrier()
; #define PG8_SCHED __builtin_amdgcn_sched_barrier(0)
; template <class Epi, bool ALIGN_EPI>
; __device__ __forceinline__ void gemm_phase(LAS unsigned char* lds, const Gemm g, const StaticOrder& S, const Epi& E, const int tid) {
;     ...
;             PG8_WAIT_V(8); PG8_WAIT_L(0); PG8_BAR; PG8_MMA(0, 0, At, B0); PG8_MMA(0, 1, At, B1); PG8_BAR; PG8_SCHED;
;             PG8_LDA(At, 1, 1); PG8_STAGE(PG8_SB(1, 0), b3, voffB); PG8_STAGE(PG8_SB(1, 1), b3 + hstepB, voffB); PG8_STAGE(PG8_SA(1, 0), a3, voffA);
	s_barrier
	s_add_u32 s54, s52, 0x8000
	s_addc_u32 s55, s53, 0
	s_add_i32 s90, s90, s71
	s_mov_b32 m0, s90
	ds_read_b128 v[178:181], v161 offset:49152
	ds_read_b128 v[182:185], v161 offset:50176
	ds_read_b128 v[186:189], v161 offset:51200
	ds_read_b128 v[190:193], v161 offset:52224


; #define PG8_STAGE(bufoff, gbase, voff) do { _Pragma("unroll") for (int _i = 0; _i < 2; ++_i) \
;         __builtin_amdgcn_global_load_lds((const unsigned*)((const char*)(gbase) + (voff)[_i]), (LAS unsigned*)(lds + (bufoff) + ldsw + _i * 8192), 16, 0, 0); } while (0)
; #define PG8_LDA(dst, b, h) do { _Pragma("unroll") for (int m = 0; m < 4; ++m) _Pragma("unroll") for (int k = 0; k < 2; ++k) dst[m][k] = *(const LAS bf16x8*)(lds + PG8_SA(b, h) + aoff + m * 2048 + k * 1024); } while (0)
; #define PG8_MMA(ai, bj, At, Bt) do { __builtin_amdgcn_s_setprio(1); _Pragma("unroll") for (int m = 0; m < 4; ++m) _Pragma("unroll") for (int n = 0; n < 2; ++n) _Pragma("unroll") for (int k = 0; k < 2; ++k) \
;         acc[ai][bj][m][n] = __builtin_amdgcn_mfma_f32_16x16x32_bf16(Bt[n][k], At[m][k], acc[ai][bj][m][n], 0, 0, 0); __builtin_amdgcn_s_setprio(0); } while (0)
; #define PG8_WAIT_V(n) asm volatile("s_waitcnt vmcnt(" #n ")" ::: "memory")
; #define PG8_WAIT_L(n) asm volatile("s_waitcnt lgkmcnt(" #n ")" ::: "memory")
; #define PG8_BAR __builtin_amdgcn_s_barrier()
; #define PG8_SCHED __builtin_amdgcn_sched_barrier(0)
; template <class Epi, bool ALIGN_EPI>
; __device__ __forceinline__ void gemm_phase(LAS unsigned char* lds, const Gemm g, const StaticOrder& S, const Epi& E, const int tid) {
;     ...
;             PG8_LDA(At, 1, 1); PG8_STAGE(PG8_SB(1, 0), b3, voffB); PG8_STAGE(PG8_SB(1, 1), b3 + hstepB, voffB); PG8_STAGE(PG8_SA(1, 0), a3, voffA);
;             PG8_WAIT_V(8); PG8_WAIT_L(0); PG8_BAR; PG8_MMA(1, 0, At, B0); PG8_MMA(1, 1, At, B1); PG8_BAR; PG8_SCHED;
	global_load_lds_dwordx4 v144, s[54:55]
	s_add_i32 m0, s90, 0x2000
	s_add_u32 s52, s52, 0xc000
	s_addc_u32 s53, s53, 0
	global_load_lds_dwordx4 v140, s[54:55]
	s_add_i32 s54, s91, s71
	s_mov_b32 m0, s54
	ds_read_b128 v[218:221], v161 offset:56320
	global_load_lds_dwordx4 v144, s[52:53]
	s_add_i32 m0, s54, 0x2000
	ds_read_b128 v[214:217], v161 offset:55296
	global_load_lds_dwordx4 v140, s[52:53]
	s_mov_b32 m0, s79
	ds_read_b128 v[198:201], v161 offset:54272
	global_load_lds_dwordx4 v146, s[50:51]
	s_mov_b32 m0, s80
	ds_read_b128 v[194:197], v161 offset:53248
	global_load_lds_dwordx4 v142, s[50:51]
	s_waitcnt vmcnt(8)
	s_waitcnt lgkmcnt(0)
	s_barrier


; #define PG8_MMA(ai, bj, At, Bt) do { __builtin_amdgcn_s_setprio(1); _Pragma("unroll") for (int m = 0; m < 4; ++m) _Pragma("unroll") for (int n = 0; n < 2; ++n) _Pragma("unroll") for (int k = 0; k < 2; ++k) \
;         acc[ai][bj][m][n] = __builtin_amdgcn_mfma_f32_16x16x32_bf16(Bt[n][k], At[m][k], acc[ai][bj][m][n], 0, 0, 0); __builtin_amdgcn_s_setprio(0); } while (0)
; #define PG8_WAIT_V(n) asm volatile("s_waitcnt vmcnt(" #n ")" ::: "memory")
; #define PG8_WAIT_L(n) asm volatile("s_waitcnt lgkmcnt(" #n ")" ::: "memory")
; #define PG8_BAR __builtin_amdgcn_s_barrier()
; #define PG8_SCHED __builtin_amdgcn_sched_barrier(0)
; template <class Epi, bool ALIGN_EPI>
; __device__ __forceinline__ void gemm_phase(LAS unsigned char* lds, const Gemm g, const StaticOrder& S, const Epi& E, const int tid) {
;     ...
;             PG8_WAIT_V(8); PG8_WAIT_L(0); PG8_BAR; PG8_MMA(1, 0, At, B0); PG8_MMA(1, 1, At, B1); PG8_BAR; PG8_SCHED;
	v_mfma_f32_16x16x32_bf16 v[24:27], v[132:135], v[178:181], v[24:27]
	v_mfma_f32_16x16x32_bf16 v[24:27], v[136:139], v[182:185], v[24:27]
	v_mfma_f32_16x16x32_bf16 v[16:19], v[136:139], v[190:193], v[16:19]
	v_mfma_f32_16x16x32_bf16 v[16:19], v[132:135], v[186:189], v[16:19]
	v_mfma_f32_16x16x32_bf16 v[6:9], v[132:135], v[194:197], v[8:11]
	v_mfma_f32_16x16x32_bf16 v[8:11], v[136:139], v[198:201], v[6:9]
	v_mfma_f32_16x16x32_bf16 v[2:5], v[132:135], v[214:217], v[2:5]
	v_mfma_f32_16x16x32_bf16 v[4:7], v[136:139], v[218:221], v[2:5]
	v_mfma_f32_16x16x32_bf16 v[64:67], v[156:159], v[218:221], v[64:67]
	v_mfma_f32_16x16x32_bf16 v[64:67], v[152:155], v[214:217], v[64:67]
	v_mfma_f32_16x16x32_bf16 v[76:79], v[152:155], v[194:197], v[76:79]
	v_mfma_f32_16x16x32_bf16 v[76:79], v[156:159], v[198:201], v[76:79]
	v_mfma_f32_16x16x32_bf16 v[84:87], v[156:159], v[190:193], v[84:87]
	v_mfma_f32_16x16x32_bf16 v[84:87], v[152:155], v[186:189], v[84:87]
	v_mfma_f32_16x16x32_bf16 v[92:95], v[152:155], v[178:181], v[92:95]
	v_mfma_f32_16x16x32_bf16 v[92:95], v[156:159], v[182:185], v[92:95]


; #define PG8_MMA(ai, bj, At, Bt) do { __builtin_amdgcn_s_setprio(1); _Pragma("unroll") for (int m = 0; m < 4; ++m) _Pragma("unroll") for (int n = 0; n < 2; ++n) _Pragma("unroll") for (int k = 0; k < 2; ++k) \
;         acc[ai][bj][m][n] = __builtin_amdgcn_mfma_f32_16x16x32_bf16(Bt[n][k], At[m][k], acc[ai][bj][m][n], 0, 0, 0); __builtin_amdgcn_s_setprio(0); } while (0)
; #define PG8_WAIT_V(n) asm volatile("s_waitcnt vmcnt(" #n ")" ::: "memory")
; #define PG8_WAIT_L(n) asm volatile("s_waitcnt lgkmcnt(" #n ")" ::: "memory")
; #define PG8_BAR __builtin_amdgcn_s_barrier()
; #define PG8_SCHED __builtin_amdgcn_sched_barrier(0)
; template <class Epi, bool ALIGN_EPI>
; __device__ __forceinline__ void gemm_phase(LAS unsigned char* lds, const Gemm g, const StaticOrder& S, const Epi& E, const int tid) {
;     ...
;             PG8_WAIT_V(8); PG8_WAIT_L(0); PG8_BAR; PG8_MMA(1, 0, At, B0); PG8_MMA(1, 1, At, B1); PG8_BAR; PG8_SCHED;
	v_mfma_f32_16x16x32_bf16 v[72:75], v[174:177], v[182:185], v[72:75]
	v_mfma_f32_16x16x32_bf16 v[72:75], v[170:173], v[178:181], v[72:75]
	v_mfma_f32_16x16x32_bf16 v[96:99], v[170:173], v[186:189], v[96:99]
	v_mfma_f32_16x16x32_bf16 v[96:99], v[174:177], v[190:193], v[96:99]
	v_mfma_f32_16x16x32_bf16 v[56:59], v[174:177], v[198:201], v[56:59]
	v_mfma_f32_16x16x32_bf16 v[56:59], v[170:173], v[194:197], v[56:59]
	v_mfma_f32_16x16x32_bf16 v[44:47], v[170:173], v[214:217], v[44:47]
	v_mfma_f32_16x16x32_bf16 v[44:47], v[174:177], v[218:221], v[44:47]
	v_mfma_f32_16x16x32_bf16 v[12:15], v[166:169], v[218:221], v[12:15]
	v_mfma_f32_16x16x32_bf16 v[12:15], v[162:165], v[214:217], v[12:15]
	v_mfma_f32_16x16x32_bf16 v[20:23], v[162:165], v[194:197], v[20:23]
	v_mfma_f32_16x16x32_bf16 v[20:23], v[166:169], v[198:201], v[20:23]
	v_mfma_f32_16x16x32_bf16 v[28:31], v[166:169], v[190:193], v[28:31]
	v_mfma_f32_16x16x32_bf16 v[28:31], v[162:165], v[186:189], v[28:31]
	v_mfma_f32_16x16x32_bf16 v[32:35], v[162:165], v[178:181], v[32:35]
	v_mfma_f32_16x16x32_bf16 v[32:35], v[166:169], v[182:185], v[32:35]

; #define PG8_STAGE(bufoff, gbase, voff) do { _Pragma("unroll") for (int _i = 0; _i < 2; ++_i) \
;         __builtin_amdgcn_global_load_lds((const unsigned*)((const char*)(gbase) + (voff)[_i]), (LAS unsigned*)(lds + (bufoff) + ldsw + _i * 8192), 16, 0, 0); } while (0)
; #define PG8_LDA(dst, b, h) do { _Pragma("unroll") for (int m = 0; m < 4; ++m) _Pragma("unroll") for (int k = 0; k < 2; ++k) dst[m][k] = *(const LAS bf16x8*)(lds + PG8_SA(b, h) + aoff + m * 2048 + k * 1024); } while (0)
; #define PG8_LDB(dst, b, h) do { _Pragma("unroll") for (int n = 0; n < 2; ++n) _Pragma("unroll") for (int k = 0; k < 2; ++k) dst[n][k] = *(const LAS bf16x8*)(lds + PG8_SB(b, h) + boff + n * 2048 + k * 1024); } while (0)
; #define PG8_BAR __builtin_amdgcn_s_barrier()
; template <class Epi, bool ALIGN_EPI>
; __device__ __forceinline__ void gemm_phase(LAS unsigned char* lds, const Gemm g, const StaticOrder& S, const Epi& E, const int tid) {
;     ...
;         for (int t = 0; t < nt; t += 2) {
;             const bool last = (t == nt - 2);
;             const char* a1 = cA + (size_t)(t + 1) * kstepA;
;             const char* a2 = last ? nA : cA + (size_t)(t + 2) * kstepA; const char* b2 = last ? nB : cB + (size_t)(t + 2) * kstepB;
;             const char* a3 = a2 + kstepA; const char* b3 = b2 + kstepB;
;             PG8_LDB(B0, 0, 0); PG8_LDB(B1, 0, 1); PG8_SCHED; PG8_LDA(At, 0, 0); PG8_STAGE(PG8_SA(1, 1), a1 + hstepA, voffA);
;             PG8_WAIT_V(8); PG8_WAIT_L(0); PG8_BAR; PG8_MMA(0, 0, At, B0); PG8_MMA(0, 1, At, B1); PG8_BAR; PG8_SCHED;
;             PG8_LDA(At, 0, 1); PG8_STAGE(PG8_SB(0, 0), b2, voffB); PG8_STAGE(PG8_SB(0, 1), b2 + hstepB, voffB); PG8_STAGE(PG8_SA(0, 0), a2, voffA);
;             PG8_WAIT_V(8); PG8_WAIT_L(0); PG8_BAR; PG8_MMA(1, 0, At, B0); PG8_MMA(1, 1, At, B1); PG8_BAR; PG8_SCHED;
;             PG8_LDB(B0, 1, 0); PG8_LDB(B1, 1, 1); PG8_SCHED; PG8_LDA(At, 1, 0); PG8_STAGE(PG8_SA(0, 1), a2 + hstepA, voffA);
;             PG8_WAIT_V(8); PG8_WAIT_L(0); PG8_BAR; PG8_MMA(0, 0, At, B0); PG8_MMA(0, 1, At, B1); PG8_BAR; PG8_SCHED;
;             PG8_LDA(At, 1, 1); PG8_STAGE(PG8_SB(1, 0), b3, voffB); PG8_STAGE(PG8_SB(1, 1), b3 + hstepB, voffB); PG8_STAGE(PG8_SA(1, 0), a3, voffA);
;             PG8_WAIT_V(8); PG8_WAIT_L(0); PG8_BAR; PG8_MMA(1, 0, At, B0); PG8_MMA(1, 1, At, B1); PG8_BAR; PG8_SCHED;
;         }
;         if constexpr (ALIGN_EPI) { if (wr == 0) PG8_BAR; }
	s_barrier
	s_add_i32 s89, s89, 2
	s_add_u32 s48, s48, 0x10000
	s_addc_u32 s49, s49, 0
	s_add_u32 vcc_hi, vcc_hi, 0x10000
	s_addc_u32 s88, s88, 0
	s_cmp_gt_u32 s89, 29
	s_cbranch_scc0 .LBB0_211
	s_and_b64 vcc, exec, s[22:23]
	s_cbranch_vccz .LBB0_214
	s_barrier

; #define PG8_STAGE(bufoff, gbase, voff) do { _Pragma("unroll") for (int _i = 0; _i < 2; ++_i) \
;         __builtin_amdgcn_global_load_lds((const unsigned*)((const char*)(gbase) + (voff)[_i]), (LAS unsigned*)(lds + (bufoff) + ldsw + _i * 8192), 16, 0, 0); } while (0)
; #define PG8_LDA(dst, b, h) do { _Pragma("unroll") for (int m = 0; m < 4; ++m) _Pragma("unroll") for (int k = 0; k < 2; ++k) dst[m][k] = *(const LAS bf16x8*)(lds + PG8_SA(b, h) + aoff + m * 2048 + k * 1024); } while (0)
; #define PG8_LDB(dst, b, h) do { _Pragma("unroll") for (int n = 0; n < 2; ++n) _Pragma("unroll") for (int k = 0; k < 2; ++k) dst[n][k] = *(const LAS bf16x8*)(lds + PG8_SB(b, h) + boff + n * 2048 + k * 1024); } while (0)
; #define PG8_SCHED __builtin_amdgcn_sched_barrier(0)
; template <class Epi, bool ALIGN_EPI>
; __device__ __forceinline__ void gemm_phase(LAS unsigned char* lds, const Gemm g, const StaticOrder& S, const Epi& E, const int tid) {
;     ...
;             PG8_LDB(B0, 0, 0); PG8_LDB(B1, 0, 1); PG8_SCHED; PG8_LDA(At, 0, 0); PG8_STAGE(PG8_SA(1, 1), a1 + hstepA, voffA);
.LBB0_294:
	s_add_u32 s22, s10, 0x4000
	s_addc_u32 s23, s11, 0
	s_cmpk_eq_i32 s86, 0x54
	s_cselect_b32 s42, s48, s22
	s_cselect_b32 s43, s49, s23
	s_cselect_b32 s34, s50, s84
	s_cselect_b32 s35, s51, s85
	s_add_u32 s22, s42, 0x8000
	s_addc_u32 s23, s43, 0
	s_add_i32 s87, 0, 0x10000
	v_add_u32_e32 v0, s87, v154
	s_add_i32 s90, 0, 0x14000
	s_waitcnt lgkmcnt(0)
	ds_read_b128 v[132:135], v0
	ds_read_b128 v[148:151], v0 offset:1024
	ds_read_b128 v[156:159], v0 offset:2048
	ds_read_b128 v[160:163], v0 offset:3072
	v_add_u32_e32 v0, s90, v154
	ds_read_b128 v[164:167], v0
	ds_read_b128 v[168:171], v0 offset:1024
	ds_read_b128 v[172:175], v0 offset:2048
	ds_read_b128 v[176:179], v0 offset:3072
	s_add_i32 m0, s57, 0xc000
	ds_read_b128 v[180:183], v155
	ds_read_b128 v[184:187], v155 offset:1024
	ds_read_b128 v[188:191], v155 offset:2048
	ds_read_b128 v[192:195], v155 offset:3072
	ds_read_b128 v[196:199], v155 offset:4096
	ds_read_b128 v[214:217], v155 offset:5120
	ds_read_b128 v[218:221], v155 offset:6144

; #define PG8_STAGE(bufoff, gbase, voff) do { _Pragma("unroll") for (int _i = 0; _i < 2; ++_i) \
;         __builtin_amdgcn_global_load_lds((const unsigned*)((const char*)(gbase) + (voff)[_i]), (LAS unsigned*)(lds + (bufoff) + ldsw + _i * 8192), 16, 0, 0); } while (0)
; #define PG8_LDA(dst, b, h) do { _Pragma("unroll") for (int m = 0; m < 4; ++m) _Pragma("unroll") for (int k = 0; k < 2; ++k) dst[m][k] = *(const LAS bf16x8*)(lds + PG8_SA(b, h) + aoff + m * 2048 + k * 1024); } while (0)
; #define PG8_LDB(dst, b, h) do { _Pragma("unroll") for (int n = 0; n < 2; ++n) _Pragma("unroll") for (int k = 0; k < 2; ++k) dst[n][k] = *(const LAS bf16x8*)(lds + PG8_SB(b, h) + boff + n * 2048 + k * 1024); } while (0)
; #define PG8_MMA(ai, bj, At, Bt) do { __builtin_amdgcn_s_setprio(1); _Pragma("unroll") for (int m = 0; m < 4; ++m) _Pragma("unroll") for (int n = 0; n < 2; ++n) _Pragma("unroll") for (int k = 0; k < 2; ++k) \
;         acc[ai][bj][m][n] = __builtin_amdgcn_mfma_f32_16x16x32_bf16(Bt[n][k], At[m][k], acc[ai][bj][m][n], 0, 0, 0); __builtin_amdgcn_s_setprio(0); } while (0)
; #define PG8_WAIT_V(n) asm volatile("s_waitcnt vmcnt(" #n ")" ::: "memory")
; #define PG8_WAIT_L(n) asm volatile("s_waitcnt lgkmcnt(" #n ")" ::: "memory")
; #define PG8_BAR __builtin_amdgcn_s_barrier()
; #define PG8_SCHED __builtin_amdgcn_sched_barrier(0)
; template <class Epi, bool ALIGN_EPI>
; __device__ __forceinline__ void gemm_phase(LAS unsigned char* lds, const Gemm g, const StaticOrder& S, const Epi& E, const int tid) {
;     ...
;             PG8_LDB(B0, 0, 0); PG8_LDB(B1, 0, 1); PG8_SCHED; PG8_LDA(At, 0, 0); PG8_STAGE(PG8_SA(1, 1), a1 + hstepA, voffA);
;             PG8_WAIT_V(8); PG8_WAIT_L(0); PG8_BAR; PG8_MMA(0, 0, At, B0); PG8_MMA(0, 1, At, B1); PG8_BAR; PG8_SCHED;
	global_load_lds_dwordx4 v144, s[10:11]
	s_add_i32 m0, s57, 0xe000
	ds_read_b128 v[222:225], v155 offset:7168
	global_load_lds_dwordx4 v146, s[10:11]
	s_waitcnt vmcnt(8)
	s_waitcnt lgkmcnt(0)
	s_barrier


; #define PG8_MMA(ai, bj, At, Bt) do { __builtin_amdgcn_s_setprio(1); _Pragma("unroll") for (int m = 0; m < 4; ++m) _Pragma("unroll") for (int n = 0; n < 2; ++n) _Pragma("unroll") for (int k = 0; k < 2; ++k) \
;         acc[ai][bj][m][n] = __builtin_amdgcn_mfma_f32_16x16x32_bf16(Bt[n][k], At[m][k], acc[ai][bj][m][n], 0, 0, 0); __builtin_amdgcn_s_setprio(0); } while (0)
; #define PG8_WAIT_V(n) asm volatile("s_waitcnt vmcnt(" #n ")" ::: "memory")
; #define PG8_WAIT_L(n) asm volatile("s_waitcnt lgkmcnt(" #n ")" ::: "memory")
; #define PG8_BAR __builtin_amdgcn_s_barrier()
; #define PG8_SCHED __builtin_amdgcn_sched_barrier(0)
; template <class Epi, bool ALIGN_EPI>
; __device__ __forceinline__ void gemm_phase(LAS unsigned char* lds, const Gemm g, const StaticOrder& S, const Epi& E, const int tid) {
;     ...
;             PG8_WAIT_V(8); PG8_WAIT_L(0); PG8_BAR; PG8_MMA(0, 0, At, B0); PG8_MMA(0, 1, At, B1); PG8_BAR; PG8_SCHED;
	v_mfma_f32_16x16x32_bf16 v[8:11], v[132:135], v[180:183], v[8:11]
	v_mfma_f32_16x16x32_bf16 v[8:11], v[148:151], v[184:187], v[8:11]
	v_mfma_f32_16x16x32_bf16 v[52:55], v[148:151], v[192:195], v[52:55]
	v_mfma_f32_16x16x32_bf16 v[52:55], v[132:135], v[188:191], v[52:55]
	v_mfma_f32_16x16x32_bf16 v[44:47], v[132:135], v[196:199], v[44:47]
	v_mfma_f32_16x16x32_bf16 v[44:47], v[148:151], v[214:217], v[44:47]
	v_mfma_f32_16x16x32_bf16 v[36:39], v[148:151], v[222:225], v[36:39]
	v_mfma_f32_16x16x32_bf16 v[36:39], v[132:135], v[218:221], v[36:39]
	v_mfma_f32_16x16x32_bf16 v[32:35], v[156:159], v[218:221], v[32:35]
	v_mfma_f32_16x16x32_bf16 v[32:35], v[160:163], v[222:225], v[32:35]
	v_mfma_f32_16x16x32_bf16 v[40:43], v[160:163], v[214:217], v[40:43]
	v_mfma_f32_16x16x32_bf16 v[40:43], v[156:159], v[196:199], v[40:43]
	v_mfma_f32_16x16x32_bf16 v[48:51], v[156:159], v[188:191], v[48:51]
	v_mfma_f32_16x16x32_bf16 v[48:51], v[160:163], v[192:195], v[48:51]
	v_mfma_f32_16x16x32_bf16 v[56:59], v[160:163], v[184:187], v[56:59]
	v_mfma_f32_16x16x32_bf16 v[56:59], v[156:159], v[180:183], v[56:59]


; #define PG8_MMA(ai, bj, At, Bt) do { __builtin_amdgcn_s_setprio(1); _Pragma("unroll") for (int m = 0; m < 4; ++m) _Pragma("unroll") for (int n = 0; n < 2; ++n) _Pragma("unroll") for (int k = 0; k < 2; ++k) \
;         acc[ai][bj][m][n] = __builtin_amdgcn_mfma_f32_16x16x32_bf16(Bt[n][k], At[m][k], acc[ai][bj][m][n], 0, 0, 0); __builtin_amdgcn_s_setprio(0); } while (0)
; #define PG8_WAIT_V(n) asm volatile("s_waitcnt vmcnt(" #n ")" ::: "memory")
; #define PG8_WAIT_L(n) asm volatile("s_waitcnt lgkmcnt(" #n ")" ::: "memory")
; #define PG8_BAR __builtin_amdgcn_s_barrier()
; #define PG8_SCHED __builtin_amdgcn_sched_barrier(0)
; template <class Epi, bool ALIGN_EPI>
; __device__ __forceinline__ void gemm_phase(LAS unsigned char* lds, const Gemm g, const StaticOrder& S, const Epi& E, const int tid) {
;     ...
;             PG8_WAIT_V(8); PG8_WAIT_L(0); PG8_BAR; PG8_MMA(0, 0, At, B0); PG8_MMA(0, 1, At, B1); PG8_BAR; PG8_SCHED;
	v_mfma_f32_16x16x32_bf16 v[28:31], v[172:175], v[180:183], v[28:31]
	v_mfma_f32_16x16x32_bf16 v[28:31], v[176:179], v[184:187], v[28:31]
	v_mfma_f32_16x16x32_bf16 v[92:95], v[176:179], v[192:195], v[92:95]
	v_mfma_f32_16x16x32_bf16 v[92:95], v[172:175], v[188:191], v[92:95]
	v_mfma_f32_16x16x32_bf16 v[84:87], v[172:175], v[196:199], v[84:87]
	v_mfma_f32_16x16x32_bf16 v[84:87], v[176:179], v[214:217], v[84:87]
	v_mfma_f32_16x16x32_bf16 v[76:79], v[176:179], v[222:225], v[76:79]
	v_mfma_f32_16x16x32_bf16 v[76:79], v[172:175], v[218:221], v[76:79]
	v_mfma_f32_16x16x32_bf16 v[80:83], v[164:167], v[218:221], v[80:83]
	v_mfma_f32_16x16x32_bf16 v[80:83], v[168:171], v[222:225], v[80:83]
	v_mfma_f32_16x16x32_bf16 v[88:91], v[168:171], v[214:217], v[88:91]
	v_mfma_f32_16x16x32_bf16 v[88:91], v[164:167], v[196:199], v[88:91]
	v_mfma_f32_16x16x32_bf16 v[96:99], v[164:167], v[188:191], v[96:99]
	v_mfma_f32_16x16x32_bf16 v[96:99], v[168:171], v[192:195], v[96:99]
	v_mfma_f32_16x16x32_bf16 v[2:5], v[164:167], v[180:183], v[4:7]
	v_mfma_f32_16x16x32_bf16 v[2:5], v[168:171], v[184:187], v[2:5]

; #define PG8_STAGE(bufoff, gbase, voff) do { _Pragma("unroll") for (int _i = 0; _i < 2; ++_i) \
;         __builtin_amdgcn_global_load_lds((const unsigned*)((const char*)(gbase) + (voff)[_i]), (LAS unsigned*)(lds + (bufoff) + ldsw + _i * 8192), 16, 0, 0); } while (0)
; #define PG8_LDA(dst, b, h) do { _Pragma("unroll") for (int m = 0; m < 4; ++m) _Pragma("unroll") for (int k = 0; k < 2; ++k) dst[m][k] = *(const LAS bf16x8*)(lds + PG8_SA(b, h) + aoff + m * 2048 + k * 1024); } while (0)
; #define PG8_MMA(ai, bj, At, Bt) do { __builtin_amdgcn_s_setprio(1); _Pragma("unroll") for (int m = 0; m < 4; ++m) _Pragma("unroll") for (int n = 0; n < 2; ++n) _Pragma("unroll") for (int k = 0; k < 2; ++k) \
;         acc[ai][bj][m][n] = __builtin_amdgcn_mfma_f32_16x16x32_bf16(Bt[n][k], At[m][k], acc[ai][bj][m][n], 0, 0, 0); __builtin_amdgcn_s_setprio(0); } while (0)
; #define PG8_WAIT_V(n) asm volatile("s_waitcnt vmcnt(" #n ")" ::: "memory")
; #define PG8_WAIT_L(n) asm volatile("s_waitcnt lgkmcnt(" #n ")" ::: "memory")
; #define PG8_BAR __builtin_amdgcn_s_barrier()
; #define PG8_SCHED __builtin_amdgcn_sched_barrier(0)
; template <class Epi, bool ALIGN_EPI>
; __device__ __forceinline__ void gemm_phase(LAS unsigned char* lds, const Gemm g, const StaticOrder& S, const Epi& E, const int tid) {
;     ...
;             PG8_WAIT_V(8); PG8_WAIT_L(0); PG8_BAR; PG8_MMA(0, 0, At, B0); PG8_MMA(0, 1, At, B1); PG8_BAR; PG8_SCHED;
;             PG8_LDA(At, 0, 1); PG8_STAGE(PG8_SB(0, 0), b2, voffB); PG8_STAGE(PG8_SB(0, 1), b2 + hstepB, voffB); PG8_STAGE(PG8_SA(0, 0), a2, voffA);
	s_barrier
	s_add_i32 s87, s87, s56
	s_mov_b32 m0, s87
	ds_read_b128 v[180:183], v155 offset:16384
	ds_read_b128 v[184:187], v155 offset:17408
	ds_read_b128 v[188:191], v155 offset:18432
	ds_read_b128 v[192:195], v155 offset:19456


; #define PG8_STAGE(bufoff, gbase, voff) do { _Pragma("unroll") for (int _i = 0; _i < 2; ++_i) \
;         __builtin_amdgcn_global_load_lds((const unsigned*)((const char*)(gbase) + (voff)[_i]), (LAS unsigned*)(lds + (bufoff) + ldsw + _i * 8192), 16, 0, 0); } while (0)
; #define PG8_LDA(dst, b, h) do { _Pragma("unroll") for (int m = 0; m < 4; ++m) _Pragma("unroll") for (int k = 0; k < 2; ++k) dst[m][k] = *(const LAS bf16x8*)(lds + PG8_SA(b, h) + aoff + m * 2048 + k * 1024); } while (0)
; #define PG8_MMA(ai, bj, At, Bt) do { __builtin_amdgcn_s_setprio(1); _Pragma("unroll") for (int m = 0; m < 4; ++m) _Pragma("unroll") for (int n = 0; n < 2; ++n) _Pragma("unroll") for (int k = 0; k < 2; ++k) \
;         acc[ai][bj][m][n] = __builtin_amdgcn_mfma_f32_16x16x32_bf16(Bt[n][k], At[m][k], acc[ai][bj][m][n], 0, 0, 0); __builtin_amdgcn_s_setprio(0); } while (0)
; #define PG8_WAIT_V(n) asm volatile("s_waitcnt vmcnt(" #n ")" ::: "memory")
; #define PG8_WAIT_L(n) asm volatile("s_waitcnt lgkmcnt(" #n ")" ::: "memory")
; #define PG8_BAR __builtin_amdgcn_s_barrier()
; #define PG8_SCHED __builtin_amdgcn_sched_barrier(0)
; template <class Epi, bool ALIGN_EPI>
; __device__ __forceinline__ void gemm_phase(LAS unsigned char* lds, const Gemm g, const StaticOrder& S, const Epi& E, const int tid) {
;     ...
;             PG8_LDA(At, 0, 1); PG8_STAGE(PG8_SB(0, 0), b2, voffB); PG8_STAGE(PG8_SB(0, 1), b2 + hstepB, voffB); PG8_STAGE(PG8_SA(0, 0), a2, voffA);
;             PG8_WAIT_V(8); PG8_WAIT_L(0); PG8_BAR; PG8_MMA(1, 0, At, B0); PG8_MMA(1, 1, At, B1); PG8_BAR; PG8_SCHED;
	global_load_lds_dwordx4 v140, s[34:35]
	s_add_i32 m0, s87, 0x2000
	s_add_u32 s88, s34, 0x4000
	s_addc_u32 s89, s35, 0
	s_add_i32 s87, s90, s56
	global_load_lds_dwordx4 v136, s[34:35]
	s_mov_b32 m0, s87
	ds_read_b128 v[222:225], v155 offset:23552
	global_load_lds_dwordx4 v140, s[88:89]
	s_add_i32 m0, s87, 0x2000
	ds_read_b128 v[218:221], v155 offset:22528
	global_load_lds_dwordx4 v136, s[88:89]
	s_mov_b32 m0, s57
	ds_read_b128 v[214:217], v155 offset:21504
	global_load_lds_dwordx4 v142, s[42:43]
	s_mov_b32 m0, s60
	ds_read_b128 v[196:199], v155 offset:20480
	global_load_lds_dwordx4 v138, s[42:43]
	s_waitcnt vmcnt(8)
	s_waitcnt lgkmcnt(0)
	s_barrier


; #define PG8_MMA(ai, bj, At, Bt) do { __builtin_amdgcn_s_setprio(1); _Pragma("unroll") for (int m = 0; m < 4; ++m) _Pragma("unroll") for (int n = 0; n < 2; ++n) _Pragma("unroll") for (int k = 0; k < 2; ++k) \
;         acc[ai][bj][m][n] = __builtin_amdgcn_mfma_f32_16x16x32_bf16(Bt[n][k], At[m][k], acc[ai][bj][m][n], 0, 0, 0); __builtin_amdgcn_s_setprio(0); } while (0)
; #define PG8_WAIT_V(n) asm volatile("s_waitcnt vmcnt(" #n ")" ::: "memory")
; #define PG8_WAIT_L(n) asm volatile("s_waitcnt lgkmcnt(" #n ")" ::: "memory")
; #define PG8_BAR __builtin_amdgcn_s_barrier()
; #define PG8_SCHED __builtin_amdgcn_sched_barrier(0)
; template <class Epi, bool ALIGN_EPI>
; __device__ __forceinline__ void gemm_phase(LAS unsigned char* lds, const Gemm g, const StaticOrder& S, const Epi& E, const int tid) {
;     ...
;             PG8_WAIT_V(8); PG8_WAIT_L(0); PG8_BAR; PG8_MMA(1, 0, At, B0); PG8_MMA(1, 1, At, B1); PG8_BAR; PG8_SCHED;
	v_mfma_f32_16x16x32_bf16 v[24:27], v[132:135], v[180:183], v[24:27]
	v_mfma_f32_16x16x32_bf16 v[24:27], v[148:151], v[184:187], v[24:27]
	v_mfma_f32_16x16x32_bf16 v[64:67], v[148:151], v[192:195], v[64:67]
	v_mfma_f32_16x16x32_bf16 v[64:67], v[132:135], v[188:191], v[64:67]
	v_mfma_f32_16x16x32_bf16 v[16:19], v[132:135], v[196:199], v[16:19]
	v_mfma_f32_16x16x32_bf16 v[16:19], v[148:151], v[214:217], v[16:19]
	v_mfma_f32_16x16x32_bf16 v[60:63], v[148:151], v[222:225], v[60:63]
	v_mfma_f32_16x16x32_bf16 v[60:63], v[132:135], v[218:221], v[60:63]
	v_mfma_f32_16x16x32_bf16 v[68:71], v[156:159], v[218:221], v[68:71]
	v_mfma_f32_16x16x32_bf16 v[68:71], v[160:163], v[222:225], v[68:71]
	v_mfma_f32_16x16x32_bf16 v[12:15], v[160:163], v[214:217], v[12:15]
	v_mfma_f32_16x16x32_bf16 v[12:15], v[156:159], v[196:199], v[12:15]
	v_mfma_f32_16x16x32_bf16 v[72:75], v[156:159], v[188:191], v[72:75]
	v_mfma_f32_16x16x32_bf16 v[72:75], v[160:163], v[192:195], v[72:75]
	v_mfma_f32_16x16x32_bf16 v[20:23], v[160:163], v[184:187], v[20:23]
	v_mfma_f32_16x16x32_bf16 v[20:23], v[156:159], v[180:183], v[20:23]


; #define PG8_MMA(ai, bj, At, Bt) do { __builtin_amdgcn_s_setprio(1); _Pragma("unroll") for (int m = 0; m < 4; ++m) _Pragma("unroll") for (int n = 0; n < 2; ++n) _Pragma("unroll") for (int k = 0; k < 2; ++k) \
;         acc[ai][bj][m][n] = __builtin_amdgcn_mfma_f32_16x16x32_bf16(Bt[n][k], At[m][k], acc[ai][bj][m][n], 0, 0, 0); __builtin_amdgcn_s_setprio(0); } while (0)
; #define PG8_WAIT_V(n) asm volatile("s_waitcnt vmcnt(" #n ")" ::: "memory")
; #define PG8_WAIT_L(n) asm volatile("s_waitcnt lgkmcnt(" #n ")" ::: "memory")
; #define PG8_BAR __builtin_amdgcn_s_barrier()
; #define PG8_SCHED __builtin_amdgcn_sched_barrier(0)
; template <class Epi, bool ALIGN_EPI>
; __device__ __forceinline__ void gemm_phase(LAS unsigned char* lds, const Gemm g, const StaticOrder& S, const Epi& E, const int tid) {
;     ...
;             PG8_WAIT_V(8); PG8_WAIT_L(0); PG8_BAR; PG8_MMA(1, 0, At, B0); PG8_MMA(1, 1, At, B1); PG8_BAR; PG8_SCHED;
	v_mfma_f32_16x16x32_bf16 v[124:127], v[172:175], v[180:183], v[124:127]
	v_mfma_f32_16x16x32_bf16 v[124:127], v[176:179], v[184:187], v[124:127]
	v_mfma_f32_16x16x32_bf16 v[116:119], v[176:179], v[192:195], v[116:119]
	v_mfma_f32_16x16x32_bf16 v[116:119], v[172:175], v[188:191], v[116:119]
	v_mfma_f32_16x16x32_bf16 v[108:111], v[172:175], v[196:199], v[108:111]
	v_mfma_f32_16x16x32_bf16 v[108:111], v[176:179], v[214:217], v[108:111]
	v_mfma_f32_16x16x32_bf16 v[100:103], v[176:179], v[222:225], v[100:103]
	v_mfma_f32_16x16x32_bf16 v[100:103], v[172:175], v[218:221], v[100:103]
	v_mfma_f32_16x16x32_bf16 v[104:107], v[164:167], v[218:221], v[104:107]
	v_mfma_f32_16x16x32_bf16 v[104:107], v[168:171], v[222:225], v[104:107]
	v_mfma_f32_16x16x32_bf16 v[112:115], v[168:171], v[214:217], v[112:115]
	v_mfma_f32_16x16x32_bf16 v[112:115], v[164:167], v[196:199], v[112:115]
	v_mfma_f32_16x16x32_bf16 v[120:123], v[164:167], v[188:191], v[120:123]
	v_mfma_f32_16x16x32_bf16 v[120:123], v[168:171], v[192:195], v[120:123]
	v_mfma_f32_16x16x32_bf16 v[128:131], v[168:171], v[184:187], v[128:131]
	v_mfma_f32_16x16x32_bf16 v[128:131], v[164:167], v[180:183], v[128:131]

; #define PG8_STAGE(bufoff, gbase, voff) do { _Pragma("unroll") for (int _i = 0; _i < 2; ++_i) \
;         __builtin_amdgcn_global_load_lds((const unsigned*)((const char*)(gbase) + (voff)[_i]), (LAS unsigned*)(lds + (bufoff) + ldsw + _i * 8192), 16, 0, 0); } while (0)
; #define PG8_LDA(dst, b, h) do { _Pragma("unroll") for (int m = 0; m < 4; ++m) _Pragma("unroll") for (int k = 0; k < 2; ++k) dst[m][k] = *(const LAS bf16x8*)(lds + PG8_SA(b, h) + aoff + m * 2048 + k * 1024); } while (0)
; #define PG8_LDB(dst, b, h) do { _Pragma("unroll") for (int n = 0; n < 2; ++n) _Pragma("unroll") for (int k = 0; k < 2; ++k) dst[n][k] = *(const LAS bf16x8*)(lds + PG8_SB(b, h) + boff + n * 2048 + k * 1024); } while (0)
; #define PG8_SCHED __builtin_amdgcn_sched_barrier(0)
; template <class Epi, bool ALIGN_EPI>
; __device__ __forceinline__ void gemm_phase(LAS unsigned char* lds, const Gemm g, const StaticOrder& S, const Epi& E, const int tid) {
;     ...
;             PG8_LDB(B0, 1, 0); PG8_LDB(B1, 1, 1); PG8_SCHED; PG8_LDA(At, 1, 0); PG8_STAGE(PG8_SA(0, 1), a2 + hstepA, voffA);
	s_barrier
	s_add_i32 s87, 0, 0x18000
	v_add_u32_e32 v0, s87, v154
	s_add_i32 s88, 0, 0x1c000
	ds_read_b128 v[132:135], v0
	ds_read_b128 v[148:151], v0 offset:1024
	ds_read_b128 v[156:159], v0 offset:2048
	ds_read_b128 v[160:163], v0 offset:3072
	v_add_u32_e32 v0, s88, v154
	ds_read_b128 v[164:167], v0
	ds_read_b128 v[168:171], v0 offset:1024
	ds_read_b128 v[172:175], v0 offset:2048
	ds_read_b128 v[176:179], v0 offset:3072
	s_add_u32 s42, s42, 0x4000
	s_addc_u32 s43, s43, 0
	s_mov_b32 m0, s61
	ds_read_b128 v[180:183], v155 offset:32768
	ds_read_b128 v[184:187], v155 offset:33792
	ds_read_b128 v[188:191], v155 offset:34816
	ds_read_b128 v[192:195], v155 offset:35840
	ds_read_b128 v[196:199], v155 offset:36864
	ds_read_b128 v[214:217], v155 offset:37888
	ds_read_b128 v[218:221], v155 offset:38912

; #define PG8_STAGE(bufoff, gbase, voff) do { _Pragma("unroll") for (int _i = 0; _i < 2; ++_i) \
;         __builtin_amdgcn_global_load_lds((const unsigned*)((const char*)(gbase) + (voff)[_i]), (LAS unsigned*)(lds + (bufoff) + ldsw + _i * 8192), 16, 0, 0); } while (0)
; #define PG8_LDA(dst, b, h) do { _Pragma("unroll") for (int m = 0; m < 4; ++m) _Pragma("unroll") for (int k = 0; k < 2; ++k) dst[m][k] = *(const LAS bf16x8*)(lds + PG8_SA(b, h) + aoff + m * 2048 + k * 1024); } while (0)
; #define PG8_LDB(dst, b, h) do { _Pragma("unroll") for (int n = 0; n < 2; ++n) _Pragma("unroll") for (int k = 0; k < 2; ++k) dst[n][k] = *(const LAS bf16x8*)(lds + PG8_SB(b, h) + boff + n * 2048 + k * 1024); } while (0)
; #define PG8_MMA(ai, bj, At, Bt) do { __builtin_amdgcn_s_setprio(1); _Pragma("unroll") for (int m = 0; m < 4; ++m) _Pragma("unroll") for (int n = 0; n < 2; ++n) _Pragma("unroll") for (int k = 0; k < 2; ++k) \
;         acc[ai][bj][m][n] = __builtin_amdgcn_mfma_f32_16x16x32_bf16(Bt[n][k], At[m][k], acc[ai][bj][m][n], 0, 0, 0); __builtin_amdgcn_s_setprio(0); } while (0)
; #define PG8_WAIT_V(n) asm volatile("s_waitcnt vmcnt(" #n ")" ::: "memory")
; #define PG8_WAIT_L(n) asm volatile("s_waitcnt lgkmcnt(" #n ")" ::: "memory")
; #define PG8_BAR __builtin_amdgcn_s_barrier()
; #define PG8_SCHED __builtin_amdgcn_sched_barrier(0)
; template <class Epi, bool ALIGN_EPI>
; __device__ __forceinline__ void gemm_phase(LAS unsigned char* lds, const Gemm g, const StaticOrder& S, const Epi& E, const int tid) {
;     ...
;             PG8_LDB(B0, 1, 0); PG8_LDB(B1, 1, 1); PG8_SCHED; PG8_LDA(At, 1, 0); PG8_STAGE(PG8_SA(0, 1), a2 + hstepA, voffA);
;             PG8_WAIT_V(8); PG8_WAIT_L(0); PG8_BAR; PG8_MMA(0, 0, At, B0); PG8_MMA(0, 1, At, B1); PG8_BAR; PG8_SCHED;
	global_load_lds_dwordx4 v142, s[42:43]
	s_mov_b32 m0, s71
	ds_read_b128 v[222:225], v155 offset:39936
	global_load_lds_dwordx4 v138, s[42:43]
	s_waitcnt vmcnt(8)
	s_waitcnt lgkmcnt(0)
	s_barrier


; #define PG8_MMA(ai, bj, At, Bt) do { __builtin_amdgcn_s_setprio(1); _Pragma("unroll") for (int m = 0; m < 4; ++m) _Pragma("unroll") for (int n = 0; n < 2; ++n) _Pragma("unroll") for (int k = 0; k < 2; ++k) \
;         acc[ai][bj][m][n] = __builtin_amdgcn_mfma_f32_16x16x32_bf16(Bt[n][k], At[m][k], acc[ai][bj][m][n], 0, 0, 0); __builtin_amdgcn_s_setprio(0); } while (0)
; #define PG8_WAIT_V(n) asm volatile("s_waitcnt vmcnt(" #n ")" ::: "memory")
; #define PG8_WAIT_L(n) asm volatile("s_waitcnt lgkmcnt(" #n ")" ::: "memory")
; #define PG8_BAR __builtin_amdgcn_s_barrier()
; #define PG8_SCHED __builtin_amdgcn_sched_barrier(0)
; template <class Epi, bool ALIGN_EPI>
; __device__ __forceinline__ void gemm_phase(LAS unsigned char* lds, const Gemm g, const StaticOrder& S, const Epi& E, const int tid) {
;     ...
;             PG8_WAIT_V(8); PG8_WAIT_L(0); PG8_BAR; PG8_MMA(0, 0, At, B0); PG8_MMA(0, 1, At, B1); PG8_BAR; PG8_SCHED;
	v_mfma_f32_16x16x32_bf16 v[6:9], v[132:135], v[180:183], v[8:11]
	v_mfma_f32_16x16x32_bf16 v[8:11], v[148:151], v[184:187], v[6:9]
	v_mfma_f32_16x16x32_bf16 v[52:55], v[148:151], v[192:195], v[52:55]
	v_mfma_f32_16x16x32_bf16 v[52:55], v[132:135], v[188:191], v[52:55]
	v_mfma_f32_16x16x32_bf16 v[44:47], v[132:135], v[196:199], v[44:47]
	v_mfma_f32_16x16x32_bf16 v[44:47], v[148:151], v[214:217], v[44:47]
	v_mfma_f32_16x16x32_bf16 v[36:39], v[148:151], v[222:225], v[36:39]
	v_mfma_f32_16x16x32_bf16 v[36:39], v[132:135], v[218:221], v[36:39]
	v_mfma_f32_16x16x32_bf16 v[32:35], v[156:159], v[218:221], v[32:35]
	v_mfma_f32_16x16x32_bf16 v[32:35], v[160:163], v[222:225], v[32:35]
	v_mfma_f32_16x16x32_bf16 v[40:43], v[160:163], v[214:217], v[40:43]
	v_mfma_f32_16x16x32_bf16 v[40:43], v[156:159], v[196:199], v[40:43]
	v_mfma_f32_16x16x32_bf16 v[48:51], v[156:159], v[188:191], v[48:51]
	v_mfma_f32_16x16x32_bf16 v[48:51], v[160:163], v[192:195], v[48:51]
	v_mfma_f32_16x16x32_bf16 v[56:59], v[160:163], v[184:187], v[56:59]
	v_mfma_f32_16x16x32_bf16 v[56:59], v[156:159], v[180:183], v[56:59]


; #define PG8_MMA(ai, bj, At, Bt) do { __builtin_amdgcn_s_setprio(1); _Pragma("unroll") for (int m = 0; m < 4; ++m) _Pragma("unroll") for (int n = 0; n < 2; ++n) _Pragma("unroll") for (int k = 0; k < 2; ++k) \
;         acc[ai][bj][m][n] = __builtin_amdgcn_mfma_f32_16x16x32_bf16(Bt[n][k], At[m][k], acc[ai][bj][m][n], 0, 0, 0); __builtin_amdgcn_s_setprio(0); } while (0)
; #define PG8_WAIT_V(n) asm volatile("s_waitcnt vmcnt(" #n ")" ::: "memory")
; #define PG8_WAIT_L(n) asm volatile("s_waitcnt lgkmcnt(" #n ")" ::: "memory")
; #define PG8_BAR __builtin_amdgcn_s_barrier()
; #define PG8_SCHED __builtin_amdgcn_sched_barrier(0)
; template <class Epi, bool ALIGN_EPI>
; __device__ __forceinline__ void gemm_phase(LAS unsigned char* lds, const Gemm g, const StaticOrder& S, const Epi& E, const int tid) {
;     ...
;             PG8_WAIT_V(8); PG8_WAIT_L(0); PG8_BAR; PG8_MMA(0, 0, At, B0); PG8_MMA(0, 1, At, B1); PG8_BAR; PG8_SCHED;
	v_mfma_f32_16x16x32_bf16 v[28:31], v[172:175], v[180:183], v[28:31]
	v_mfma_f32_16x16x32_bf16 v[28:31], v[176:179], v[184:187], v[28:31]
	v_mfma_f32_16x16x32_bf16 v[92:95], v[176:179], v[192:195], v[92:95]
	v_mfma_f32_16x16x32_bf16 v[92:95], v[172:175], v[188:191], v[92:95]
	v_mfma_f32_16x16x32_bf16 v[84:87], v[172:175], v[196:199], v[84:87]
	v_mfma_f32_16x16x32_bf16 v[84:87], v[176:179], v[214:217], v[84:87]
	v_mfma_f32_16x16x32_bf16 v[76:79], v[176:179], v[222:225], v[76:79]
	v_mfma_f32_16x16x32_bf16 v[76:79], v[172:175], v[218:221], v[76:79]
	v_mfma_f32_16x16x32_bf16 v[80:83], v[164:167], v[218:221], v[80:83]
	v_mfma_f32_16x16x32_bf16 v[80:83], v[168:171], v[222:225], v[80:83]
	v_mfma_f32_16x16x32_bf16 v[88:91], v[168:171], v[214:217], v[88:91]
	v_mfma_f32_16x16x32_bf16 v[88:91], v[164:167], v[196:199], v[88:91]
	v_mfma_f32_16x16x32_bf16 v[96:99], v[164:167], v[188:191], v[96:99]
	v_mfma_f32_16x16x32_bf16 v[96:99], v[168:171], v[192:195], v[96:99]
	v_mfma_f32_16x16x32_bf16 v[2:5], v[164:167], v[180:183], v[2:5]
	v_mfma_f32_16x16x32_bf16 v[4:7], v[168:171], v[184:187], v[2:5]

; #define PG8_STAGE(bufoff, gbase, voff) do { _Pragma("unroll") for (int _i = 0; _i < 2; ++_i) \
;         __builtin_amdgcn_global_load_lds((const unsigned*)((const char*)(gbase) + (voff)[_i]), (LAS unsigned*)(lds + (bufoff) + ldsw + _i * 8192), 16, 0, 0); } while (0)
; #define PG8_LDA(dst, b, h) do { _Pragma("unroll") for (int m = 0; m < 4; ++m) _Pragma("unroll") for (int k = 0; k < 2; ++k) dst[m][k] = *(const LAS bf16x8*)(lds + PG8_SA(b, h) + aoff + m * 2048 + k * 1024); } while (0)
; #define PG8_MMA(ai, bj, At, Bt) do { __builtin_amdgcn_s_setprio(1); _Pragma("unroll") for (int m = 0; m < 4; ++m) _Pragma("unroll") for (int n = 0; n < 2; ++n) _Pragma("unroll") for (int k = 0; k < 2; ++k) \
;         acc[ai][bj][m][n] = __builtin_amdgcn_mfma_f32_16x16x32_bf16(Bt[n][k], At[m][k], acc[ai][bj][m][n], 0, 0, 0); __builtin_amdgcn_s_setprio(0); } while (0)
; #define PG8_WAIT_V(n) asm volatile("s_waitcnt vmcnt(" #n ")" ::: "memory")
; #define PG8_WAIT_L(n) asm volatile("s_waitcnt lgkmcnt(" #n ")" ::: "memory")
; #define PG8_BAR __builtin_amdgcn_s_barrier()
; #define PG8_SCHED __builtin_amdgcn_sched_barrier(0)
; template <class Epi, bool ALIGN_EPI>
; __device__ __forceinline__ void gemm_phase(LAS unsigned char* lds, const Gemm g, const StaticOrder& S, const Epi& E, const int tid) {
;     ...
;             PG8_WAIT_V(8); PG8_WAIT_L(0); PG8_BAR; PG8_MMA(0, 0, At, B0); PG8_MMA(0, 1, At, B1); PG8_BAR; PG8_SCHED;
;             PG8_LDA(At, 1, 1); PG8_STAGE(PG8_SB(1, 0), b3, voffB); PG8_STAGE(PG8_SB(1, 1), b3 + hstepB, voffB); PG8_STAGE(PG8_SA(1, 0), a3, voffA);
	s_barrier
	s_add_u32 s42, s34, 0x8000
	s_addc_u32 s43, s35, 0
	s_add_i32 s87, s87, s56
	s_mov_b32 m0, s87
	ds_read_b128 v[180:183], v155 offset:49152
	ds_read_b128 v[184:187], v155 offset:50176
	ds_read_b128 v[188:191], v155 offset:51200
	ds_read_b128 v[192:195], v155 offset:52224


; #define PG8_STAGE(bufoff, gbase, voff) do { _Pragma("unroll") for (int _i = 0; _i < 2; ++_i) \
;         __builtin_amdgcn_global_load_lds((const unsigned*)((const char*)(gbase) + (voff)[_i]), (LAS unsigned*)(lds + (bufoff) + ldsw + _i * 8192), 16, 0, 0); } while (0)
; #define PG8_LDA(dst, b, h) do { _Pragma("unroll") for (int m = 0; m < 4; ++m) _Pragma("unroll") for (int k = 0; k < 2; ++k) dst[m][k] = *(const LAS bf16x8*)(lds + PG8_SA(b, h) + aoff + m * 2048 + k * 1024); } while (0)
; #define PG8_MMA(ai, bj, At, Bt) do { __builtin_amdgcn_s_setprio(1); _Pragma("unroll") for (int m = 0; m < 4; ++m) _Pragma("unroll") for (int n = 0; n < 2; ++n) _Pragma("unroll") for (int k = 0; k < 2; ++k) \
;         acc[ai][bj][m][n] = __builtin_amdgcn_mfma_f32_16x16x32_bf16(Bt[n][k], At[m][k], acc[ai][bj][m][n], 0, 0, 0); __builtin_amdgcn_s_setprio(0); } while (0)
; #define PG8_WAIT_V(n) asm volatile("s_waitcnt vmcnt(" #n ")" ::: "memory")
; #define PG8_WAIT_L(n) asm volatile("s_waitcnt lgkmcnt(" #n ")" ::: "memory")
; #define PG8_BAR __builtin_amdgcn_s_barrier()
; #define PG8_SCHED __builtin_amdgcn_sched_barrier(0)
; template <class Epi, bool ALIGN_EPI>
; __device__ __forceinline__ void gemm_phase(LAS unsigned char* lds, const Gemm g, const StaticOrder& S, const Epi& E, const int tid) {
;     ...
;             PG8_LDA(At, 1, 1); PG8_STAGE(PG8_SB(1, 0), b3, voffB); PG8_STAGE(PG8_SB(1, 1), b3 + hstepB, voffB); PG8_STAGE(PG8_SA(1, 0), a3, voffA);
;             PG8_WAIT_V(8); PG8_WAIT_L(0); PG8_BAR; PG8_MMA(1, 0, At, B0); PG8_MMA(1, 1, At, B1); PG8_BAR; PG8_SCHED;
	global_load_lds_dwordx4 v140, s[42:43]
	s_add_i32 m0, s87, 0x2000
	s_add_u32 s34, s34, 0xc000
	s_addc_u32 s35, s35, 0
	global_load_lds_dwordx4 v136, s[42:43]
	s_add_i32 s42, s88, s56
	s_mov_b32 m0, s42
	ds_read_b128 v[222:225], v155 offset:56320
	global_load_lds_dwordx4 v140, s[34:35]
	s_add_i32 m0, s42, 0x2000
	ds_read_b128 v[218:221], v155 offset:55296
	global_load_lds_dwordx4 v136, s[34:35]
	s_mov_b32 m0, s76
	ds_read_b128 v[214:217], v155 offset:54272
	global_load_lds_dwordx4 v142, s[22:23]
	s_mov_b32 m0, s77
	ds_read_b128 v[196:199], v155 offset:53248
	global_load_lds_dwordx4 v138, s[22:23]
	s_waitcnt vmcnt(8)
	s_waitcnt lgkmcnt(0)
	s_barrier


; #define PG8_MMA(ai, bj, At, Bt) do { __builtin_amdgcn_s_setprio(1); _Pragma("unroll") for (int m = 0; m < 4; ++m) _Pragma("unroll") for (int n = 0; n < 2; ++n) _Pragma("unroll") for (int k = 0; k < 2; ++k) \
;         acc[ai][bj][m][n] = __builtin_amdgcn_mfma_f32_16x16x32_bf16(Bt[n][k], At[m][k], acc[ai][bj][m][n], 0, 0, 0); __builtin_amdgcn_s_setprio(0); } while (0)
; #define PG8_WAIT_V(n) asm volatile("s_waitcnt vmcnt(" #n ")" ::: "memory")
; #define PG8_WAIT_L(n) asm volatile("s_waitcnt lgkmcnt(" #n ")" ::: "memory")
; #define PG8_BAR __builtin_amdgcn_s_barrier()
; #define PG8_SCHED __builtin_amdgcn_sched_barrier(0)
; template <class Epi, bool ALIGN_EPI>
; __device__ __forceinline__ void gemm_phase(LAS unsigned char* lds, const Gemm g, const StaticOrder& S, const Epi& E, const int tid) {
;     ...
;             PG8_WAIT_V(8); PG8_WAIT_L(0); PG8_BAR; PG8_MMA(1, 0, At, B0); PG8_MMA(1, 1, At, B1); PG8_BAR; PG8_SCHED;
	v_mfma_f32_16x16x32_bf16 v[24:27], v[132:135], v[180:183], v[24:27]
	v_mfma_f32_16x16x32_bf16 v[24:27], v[148:151], v[184:187], v[24:27]
	v_mfma_f32_16x16x32_bf16 v[64:67], v[148:151], v[192:195], v[64:67]
	v_mfma_f32_16x16x32_bf16 v[64:67], v[132:135], v[188:191], v[64:67]
	v_mfma_f32_16x16x32_bf16 v[16:19], v[132:135], v[196:199], v[16:19]
	v_mfma_f32_16x16x32_bf16 v[16:19], v[148:151], v[214:217], v[16:19]
	v_mfma_f32_16x16x32_bf16 v[60:63], v[148:151], v[222:225], v[60:63]
	v_mfma_f32_16x16x32_bf16 v[60:63], v[132:135], v[218:221], v[60:63]
	v_mfma_f32_16x16x32_bf16 v[68:71], v[156:159], v[218:221], v[68:71]
	v_mfma_f32_16x16x32_bf16 v[68:71], v[160:163], v[222:225], v[68:71]
	v_mfma_f32_16x16x32_bf16 v[12:15], v[160:163], v[214:217], v[12:15]
	v_mfma_f32_16x16x32_bf16 v[12:15], v[156:159], v[196:199], v[12:15]
	v_mfma_f32_16x16x32_bf16 v[72:75], v[156:159], v[188:191], v[72:75]
	v_mfma_f32_16x16x32_bf16 v[72:75], v[160:163], v[192:195], v[72:75]
	v_mfma_f32_16x16x32_bf16 v[20:23], v[160:163], v[184:187], v[20:23]
	v_mfma_f32_16x16x32_bf16 v[20:23], v[156:159], v[180:183], v[20:23]


; #define PG8_MMA(ai, bj, At, Bt) do { __builtin_amdgcn_s_setprio(1); _Pragma("unroll") for (int m = 0; m < 4; ++m) _Pragma("unroll") for (int n = 0; n < 2; ++n) _Pragma("unroll") for (int k = 0; k < 2; ++k) \
;         acc[ai][bj][m][n] = __builtin_amdgcn_mfma_f32_16x16x32_bf16(Bt[n][k], At[m][k], acc[ai][bj][m][n], 0, 0, 0); __builtin_amdgcn_s_setprio(0); } while (0)
; #define PG8_WAIT_V(n) asm volatile("s_waitcnt vmcnt(" #n ")" ::: "memory")
; #define PG8_WAIT_L(n) asm volatile("s_waitcnt lgkmcnt(" #n ")" ::: "memory")
; #define PG8_BAR __builtin_amdgcn_s_barrier()
; #define PG8_SCHED __builtin_amdgcn_sched_barrier(0)
; template <class Epi, bool ALIGN_EPI>
; __device__ __forceinline__ void gemm_phase(LAS unsigned char* lds, const Gemm g, const StaticOrder& S, const Epi& E, const int tid) {
;     ...
;             PG8_WAIT_V(8); PG8_WAIT_L(0); PG8_BAR; PG8_MMA(1, 0, At, B0); PG8_MMA(1, 1, At, B1); PG8_BAR; PG8_SCHED;
	v_mfma_f32_16x16x32_bf16 v[124:127], v[172:175], v[180:183], v[124:127]
	v_mfma_f32_16x16x32_bf16 v[124:127], v[176:179], v[184:187], v[124:127]
	v_mfma_f32_16x16x32_bf16 v[116:119], v[176:179], v[192:195], v[116:119]
	v_mfma_f32_16x16x32_bf16 v[116:119], v[172:175], v[188:191], v[116:119]
	v_mfma_f32_16x16x32_bf16 v[108:111], v[172:175], v[196:199], v[108:111]
	v_mfma_f32_16x16x32_bf16 v[108:111], v[176:179], v[214:217], v[108:111]
	v_mfma_f32_16x16x32_bf16 v[100:103], v[176:179], v[222:225], v[100:103]
	v_mfma_f32_16x16x32_bf16 v[100:103], v[172:175], v[218:221], v[100:103]
	v_mfma_f32_16x16x32_bf16 v[104:107], v[164:167], v[218:221], v[104:107]
	v_mfma_f32_16x16x32_bf16 v[104:107], v[168:171], v[222:225], v[104:107]
	v_mfma_f32_16x16x32_bf16 v[112:115], v[168:171], v[214:217], v[112:115]
	v_mfma_f32_16x16x32_bf16 v[112:115], v[164:167], v[196:199], v[112:115]
	v_mfma_f32_16x16x32_bf16 v[120:123], v[164:167], v[188:191], v[120:123]
	v_mfma_f32_16x16x32_bf16 v[120:123], v[168:171], v[192:195], v[120:123]
	v_mfma_f32_16x16x32_bf16 v[128:131], v[168:171], v[184:187], v[128:131]
	v_mfma_f32_16x16x32_bf16 v[128:131], v[164:167], v[180:183], v[128:131]

; #define PG8_MMA(ai, bj, At, Bt) do { __builtin_amdgcn_s_setprio(1); _Pragma("unroll") for (int m = 0; m < 4; ++m) _Pragma("unroll") for (int n = 0; n < 2; ++n) _Pragma("unroll") for (int k = 0; k < 2; ++k) \
;         acc[ai][bj][m][n] = __builtin_amdgcn_mfma_f32_16x16x32_bf16(Bt[n][k], At[m][k], acc[ai][bj][m][n], 0, 0, 0); __builtin_amdgcn_s_setprio(0); } while (0)
; #define PG8_WAIT_V(n) asm volatile("s_waitcnt vmcnt(" #n ")" ::: "memory")
; #define PG8_WAIT_L(n) asm volatile("s_waitcnt lgkmcnt(" #n ")" ::: "memory")
; #define PG8_BAR __builtin_amdgcn_s_barrier()
; #define PG8_SCHED __builtin_amdgcn_sched_barrier(0)
; __device__ __forceinline__ u32x4 zero_frag() { unsigned z_ = 0u; asm volatile("" : "+v"(z_)); return (u32x4){z_, z_, z_, z_}; }
; __device__ __forceinline__ void epi_lane(int& fr, int& fq) { unsigned ones = ~0u; asm volatile("" : "+s"(ones)); const int ln = (int)__builtin_amdgcn_mbcnt_hi(ones, __builtin_amdgcn_mbcnt_lo(ones, 0u)); fr = ln & 15; fq = ln >> 4; }
; template <class Epi, bool ALIGN_EPI>
; __device__ __forceinline__ void gemm_phase(LAS unsigned char* lds, const Gemm g, const StaticOrder& S, const Epi& E, const int tid) {
;     ...
;             PG8_WAIT_V(8); PG8_WAIT_L(0); PG8_BAR; PG8_MMA(1, 0, At, B0); PG8_MMA(1, 1, At, B1); PG8_BAR; PG8_SCHED;
;         }
;         if constexpr (ALIGN_EPI) { if (wr == 0) PG8_BAR; }
;     __device__ __forceinline__ void operator()(f32x4 (&acc)[2][2][4][2], const Unit& u, int wr, int wc, LAS unsigned char* lds, int& rs_pm) const {
;         int fr, fq; epi_lane(fr, fq);
;         const int row0 = u.pm * BM + wr * 64 + fr, col0 = u.pn * BM + wc * 32 + 8 * fq; u32x4 zb = zero_frag();
; #pragma unroll
;         for (int ai = 0; ai < 2; ++ai)
; #pragma unroll
;             for (int m = 0; m < 4; ++m) { float ss = 0.f;
;                 bf16* const xrow = xb + (((size_t)(u.pm * 32 + u.pn * 4 + (wc >> 1)) * BM + (wr * 64 + fr + ai * HALF + m * 16)) * 64 + (wc & 1) * 32 + 8 * fq);
; #pragma unroll
;                 for (int bj = 0; bj < 2; ++bj) {
;                     const u32x4 xw = *(const u32x4*)(xrow + (size_t)bj * (2 * BM * 64));
	s_barrier
	s_add_i32 s86, s86, 2
	s_add_u32 s84, s84, 0x10000
	s_addc_u32 s85, s85, 0
	s_add_u32 s10, s10, 0x10000
	s_addc_u32 s11, s11, 0
	s_cmpk_gt_u32 s86, 0x55
	s_cbranch_scc0 .LBB0_294
	v_and_b32_e32 v222, 15, v238
	v_lshrrev_b32_e32 v156, 4, v238
	s_lshl_b32 s100, s82, 5
	s_lshl_b32 s101, s83, 2
	v_lshlrev_b32_e32 v222, 7, v222
	s_add_i32 s100, s100, s101
	s_or_b32 s100, s100, s78
	v_lshl_or_b32 v222, v156, 4, v222
	s_ashr_i32 s101, s100, 31
	s_lshl_b64 s[100:101], s[100:101], 15
	s_add_u32 s98, s72, s100
	s_addc_u32 s99, s73, s101
	s_add_u32 s98, s98, s30
	s_addc_u32 s99, s99, s31
	s_lshl_b32 s100, s75, 7
	s_add_u32 s98, s98, s100
	s_addc_u32 s99, s99, 0
	s_lshl_b32 s100, s82, 15
	s_lshl_b32 s101, s75, 7
	s_add_i32 s100, s100, s101
	s_lshl_b32 s101, s83, 4
	s_add_i32 s100, s100, s101
	s_lshl_b32 s101, s74, 2
	s_add_i32 s100, s100, s101
	s_add_u32 s22, s44, s100
	s_addc_u32 s23, s45, 0
	global_load_dwordx4 v[176:179], v222, s[98:99]
	s_add_u32 s100, s98, 0x10000
	s_addc_u32 s101, s99, 0
	global_load_dwordx4 v[180:183], v222, s[100:101]
	global_load_dwordx4 v[184:187], v222, s[98:99] offset:2048
	s_add_u32 s100, s98, 0x10000
	s_addc_u32 s101, s99, 0
	global_load_dwordx4 v[188:191], v222, s[100:101] offset:2048
	s_add_u32 s100, s98, 0x1000
	s_addc_u32 s101, s99, 0
	global_load_dwordx4 v[192:195], v222, s[100:101]
	s_add_u32 s100, s98, 0x11000
	s_addc_u32 s101, s99, 0
	global_load_dwordx4 v[196:199], v222, s[100:101]
	s_add_u32 s100, s98, 0x1000
	s_addc_u32 s101, s99, 0
	global_load_dwordx4 v[214:217], v222, s[100:101] offset:2048
	s_add_u32 s100, s98, 0x11000
	s_addc_u32 s101, s99, 0
	global_load_dwordx4 v[218:221], v222, s[100:101] offset:2048
	s_and_b64 vcc, exec, s[46:47]
	s_cbranch_vccz .LBB0_297
	s_barrier

; #define PG8_STAGE(bufoff, gbase, voff) do { _Pragma("unroll") for (int _i = 0; _i < 2; ++_i) \
;         __builtin_amdgcn_global_load_lds((const unsigned*)((const char*)(gbase) + (voff)[_i]), (LAS unsigned*)(lds + (bufoff) + ldsw + _i * 8192), 16, 0, 0); } while (0)
; #define PG8_LDA(dst, b, h) do { _Pragma("unroll") for (int m = 0; m < 4; ++m) _Pragma("unroll") for (int k = 0; k < 2; ++k) dst[m][k] = *(const LAS bf16x8*)(lds + PG8_SA(b, h) + aoff + m * 2048 + k * 1024); } while (0)
; #define PG8_LDB(dst, b, h) do { _Pragma("unroll") for (int n = 0; n < 2; ++n) _Pragma("unroll") for (int k = 0; k < 2; ++k) dst[n][k] = *(const LAS bf16x8*)(lds + PG8_SB(b, h) + boff + n * 2048 + k * 1024); } while (0)
; #define PG8_SCHED __builtin_amdgcn_sched_barrier(0)
; template <class Epi, bool ALIGN_EPI>
; __device__ __forceinline__ void gemm_phase(LAS unsigned char* lds, const Gemm g, const StaticOrder& S, const Epi& E, const int tid) {
;     ...
;             PG8_LDB(B0, 0, 0); PG8_LDB(B1, 0, 1); PG8_SCHED; PG8_LDA(At, 0, 0); PG8_STAGE(PG8_SA(1, 1), a1 + hstepA, voffA);
.LBB0_385:
	s_add_u32 s50, s48, 0x4000
	s_addc_u32 s51, s49, 0
	s_cmp_eq_u32 s88, 28
	s_cselect_b32 s54, s84, s50
	s_cselect_b32 s55, s43, s51
	s_cselect_b32 s52, s85, s86
	s_cselect_b32 s53, s41, s87
	s_add_u32 s50, s54, 0x8000
	s_addc_u32 s51, s55, 0
	s_add_i32 s89, 0, 0x10000
	v_add_u32_e32 v0, s89, v167
	s_add_i32 s92, 0, 0x14000
	ds_read_b128 v[132:135], v0
	ds_read_b128 v[136:139], v0 offset:1024
	ds_read_b128 v[152:155], v0 offset:2048
	ds_read_b128 v[156:159], v0 offset:3072
	v_add_u32_e32 v0, s92, v167
	ds_read_b128 v[160:163], v0
	ds_read_b128 v[172:175], v0 offset:1024
	ds_read_b128 v[176:179], v0 offset:2048
	ds_read_b128 v[180:183], v0 offset:3072
	s_add_i32 m0, s71, 0xc000
	ds_read_b128 v[184:187], v171
	ds_read_b128 v[188:191], v171 offset:1024
	ds_read_b128 v[192:195], v171 offset:2048
	ds_read_b128 v[196:199], v171 offset:3072
	ds_read_b128 v[214:217], v171 offset:4096
	ds_read_b128 v[218:221], v171 offset:5120
	ds_read_b128 v[222:225], v171 offset:6144

; #define PG8_STAGE(bufoff, gbase, voff) do { _Pragma("unroll") for (int _i = 0; _i < 2; ++_i) \
;         __builtin_amdgcn_global_load_lds((const unsigned*)((const char*)(gbase) + (voff)[_i]), (LAS unsigned*)(lds + (bufoff) + ldsw + _i * 8192), 16, 0, 0); } while (0)
; #define PG8_LDA(dst, b, h) do { _Pragma("unroll") for (int m = 0; m < 4; ++m) _Pragma("unroll") for (int k = 0; k < 2; ++k) dst[m][k] = *(const LAS bf16x8*)(lds + PG8_SA(b, h) + aoff + m * 2048 + k * 1024); } while (0)
; #define PG8_LDB(dst, b, h) do { _Pragma("unroll") for (int n = 0; n < 2; ++n) _Pragma("unroll") for (int k = 0; k < 2; ++k) dst[n][k] = *(const LAS bf16x8*)(lds + PG8_SB(b, h) + boff + n * 2048 + k * 1024); } while (0)
; #define PG8_MMA(ai, bj, At, Bt) do { __builtin_amdgcn_s_setprio(1); _Pragma("unroll") for (int m = 0; m < 4; ++m) _Pragma("unroll") for (int n = 0; n < 2; ++n) _Pragma("unroll") for (int k = 0; k < 2; ++k) \
;         acc[ai][bj][m][n] = __builtin_amdgcn_mfma_f32_16x16x32_bf16(Bt[n][k], At[m][k], acc[ai][bj][m][n], 0, 0, 0); __builtin_amdgcn_s_setprio(0); } while (0)
; #define PG8_WAIT_V(n) asm volatile("s_waitcnt vmcnt(" #n ")" ::: "memory")
; #define PG8_WAIT_L(n) asm volatile("s_waitcnt lgkmcnt(" #n ")" ::: "memory")
; #define PG8_BAR __builtin_amdgcn_s_barrier()
; #define PG8_SCHED __builtin_amdgcn_sched_barrier(0)
; template <class Epi, bool ALIGN_EPI>
; __device__ __forceinline__ void gemm_phase(LAS unsigned char* lds, const Gemm g, const StaticOrder& S, const Epi& E, const int tid) {
;     ...
;             PG8_LDB(B0, 0, 0); PG8_LDB(B1, 0, 1); PG8_SCHED; PG8_LDA(At, 0, 0); PG8_STAGE(PG8_SA(1, 1), a1 + hstepA, voffA);
;             PG8_WAIT_V(8); PG8_WAIT_L(0); PG8_BAR; PG8_MMA(0, 0, At, B0); PG8_MMA(0, 1, At, B1); PG8_BAR; PG8_SCHED;
	global_load_lds_dwordx4 v148, s[48:49]
	s_add_i32 m0, s71, 0xe000
	ds_read_b128 v[226:229], v171 offset:7168
	global_load_lds_dwordx4 v150, s[48:49]
	s_waitcnt vmcnt(8)
	s_waitcnt lgkmcnt(0)
	s_barrier


; #define PG8_MMA(ai, bj, At, Bt) do { __builtin_amdgcn_s_setprio(1); _Pragma("unroll") for (int m = 0; m < 4; ++m) _Pragma("unroll") for (int n = 0; n < 2; ++n) _Pragma("unroll") for (int k = 0; k < 2; ++k) \
;         acc[ai][bj][m][n] = __builtin_amdgcn_mfma_f32_16x16x32_bf16(Bt[n][k], At[m][k], acc[ai][bj][m][n], 0, 0, 0); __builtin_amdgcn_s_setprio(0); } while (0)
; #define PG8_WAIT_V(n) asm volatile("s_waitcnt vmcnt(" #n ")" ::: "memory")
; #define PG8_WAIT_L(n) asm volatile("s_waitcnt lgkmcnt(" #n ")" ::: "memory")
; #define PG8_BAR __builtin_amdgcn_s_barrier()
; #define PG8_SCHED __builtin_amdgcn_sched_barrier(0)
; template <class Epi, bool ALIGN_EPI>
; __device__ __forceinline__ void gemm_phase(LAS unsigned char* lds, const Gemm g, const StaticOrder& S, const Epi& E, const int tid) {
;     ...
;             PG8_WAIT_V(8); PG8_WAIT_L(0); PG8_BAR; PG8_MMA(0, 0, At, B0); PG8_MMA(0, 1, At, B1); PG8_BAR; PG8_SCHED;
	v_mfma_f32_16x16x32_bf16 v[128:131], v[132:135], v[184:187], v[128:131]
	v_mfma_f32_16x16x32_bf16 v[128:131], v[136:139], v[188:191], v[128:131]
	v_mfma_f32_16x16x32_bf16 v[124:127], v[136:139], v[196:199], v[124:127]
	v_mfma_f32_16x16x32_bf16 v[124:127], v[132:135], v[192:195], v[124:127]
	v_mfma_f32_16x16x32_bf16 v[120:123], v[132:135], v[214:217], v[120:123]
	v_mfma_f32_16x16x32_bf16 v[120:123], v[136:139], v[218:221], v[120:123]
	v_mfma_f32_16x16x32_bf16 v[112:115], v[136:139], v[226:229], v[112:115]
	v_mfma_f32_16x16x32_bf16 v[112:115], v[132:135], v[222:225], v[112:115]
	v_mfma_f32_16x16x32_bf16 v[92:95], v[152:155], v[222:225], v[92:95]
	v_mfma_f32_16x16x32_bf16 v[92:95], v[156:159], v[226:229], v[92:95]
	v_mfma_f32_16x16x32_bf16 v[100:103], v[156:159], v[218:221], v[100:103]
	v_mfma_f32_16x16x32_bf16 v[100:103], v[152:155], v[214:217], v[100:103]
	v_mfma_f32_16x16x32_bf16 v[108:111], v[152:155], v[192:195], v[108:111]
	v_mfma_f32_16x16x32_bf16 v[108:111], v[156:159], v[196:199], v[108:111]
	v_mfma_f32_16x16x32_bf16 v[116:119], v[156:159], v[188:191], v[116:119]
	v_mfma_f32_16x16x32_bf16 v[116:119], v[152:155], v[184:187], v[116:119]


; #define PG8_MMA(ai, bj, At, Bt) do { __builtin_amdgcn_s_setprio(1); _Pragma("unroll") for (int m = 0; m < 4; ++m) _Pragma("unroll") for (int n = 0; n < 2; ++n) _Pragma("unroll") for (int k = 0; k < 2; ++k) \
;         acc[ai][bj][m][n] = __builtin_amdgcn_mfma_f32_16x16x32_bf16(Bt[n][k], At[m][k], acc[ai][bj][m][n], 0, 0, 0); __builtin_amdgcn_s_setprio(0); } while (0)
; #define PG8_WAIT_V(n) asm volatile("s_waitcnt vmcnt(" #n ")" ::: "memory")
; #define PG8_WAIT_L(n) asm volatile("s_waitcnt lgkmcnt(" #n ")" ::: "memory")
; #define PG8_BAR __builtin_amdgcn_s_barrier()
; #define PG8_SCHED __builtin_amdgcn_sched_barrier(0)
; template <class Epi, bool ALIGN_EPI>
; __device__ __forceinline__ void gemm_phase(LAS unsigned char* lds, const Gemm g, const StaticOrder& S, const Epi& E, const int tid) {
;     ...
;             PG8_WAIT_V(8); PG8_WAIT_L(0); PG8_BAR; PG8_MMA(0, 0, At, B0); PG8_MMA(0, 1, At, B1); PG8_BAR; PG8_SCHED;
	v_mfma_f32_16x16x32_bf16 v[80:83], v[176:179], v[184:187], v[80:83]
	v_mfma_f32_16x16x32_bf16 v[80:83], v[180:183], v[188:191], v[80:83]
	v_mfma_f32_16x16x32_bf16 v[68:71], v[180:183], v[196:199], v[68:71]
	v_mfma_f32_16x16x32_bf16 v[68:71], v[176:179], v[192:195], v[68:71]
	v_mfma_f32_16x16x32_bf16 v[60:63], v[176:179], v[214:217], v[60:63]
	v_mfma_f32_16x16x32_bf16 v[60:63], v[180:183], v[218:221], v[60:63]
	v_mfma_f32_16x16x32_bf16 v[48:51], v[180:183], v[226:229], v[48:51]
	v_mfma_f32_16x16x32_bf16 v[48:51], v[176:179], v[222:225], v[48:51]
	v_mfma_f32_16x16x32_bf16 v[76:79], v[160:163], v[222:225], v[76:79]
	v_mfma_f32_16x16x32_bf16 v[76:79], v[172:175], v[226:229], v[76:79]
	v_mfma_f32_16x16x32_bf16 v[88:91], v[172:175], v[218:221], v[88:91]
	v_mfma_f32_16x16x32_bf16 v[88:91], v[160:163], v[214:217], v[88:91]
	v_mfma_f32_16x16x32_bf16 v[96:99], v[160:163], v[192:195], v[96:99]
	v_mfma_f32_16x16x32_bf16 v[96:99], v[172:175], v[196:199], v[96:99]
	v_mfma_f32_16x16x32_bf16 v[104:107], v[172:175], v[188:191], v[104:107]
	v_mfma_f32_16x16x32_bf16 v[104:107], v[160:163], v[184:187], v[104:107]

; #define PG8_STAGE(bufoff, gbase, voff) do { _Pragma("unroll") for (int _i = 0; _i < 2; ++_i) \
;         __builtin_amdgcn_global_load_lds((const unsigned*)((const char*)(gbase) + (voff)[_i]), (LAS unsigned*)(lds + (bufoff) + ldsw + _i * 8192), 16, 0, 0); } while (0)
; #define PG8_LDA(dst, b, h) do { _Pragma("unroll") for (int m = 0; m < 4; ++m) _Pragma("unroll") for (int k = 0; k < 2; ++k) dst[m][k] = *(const LAS bf16x8*)(lds + PG8_SA(b, h) + aoff + m * 2048 + k * 1024); } while (0)
; #define PG8_MMA(ai, bj, At, Bt) do { __builtin_amdgcn_s_setprio(1); _Pragma("unroll") for (int m = 0; m < 4; ++m) _Pragma("unroll") for (int n = 0; n < 2; ++n) _Pragma("unroll") for (int k = 0; k < 2; ++k) \
;         acc[ai][bj][m][n] = __builtin_amdgcn_mfma_f32_16x16x32_bf16(Bt[n][k], At[m][k], acc[ai][bj][m][n], 0, 0, 0); __builtin_amdgcn_s_setprio(0); } while (0)
; #define PG8_WAIT_V(n) asm volatile("s_waitcnt vmcnt(" #n ")" ::: "memory")
; #define PG8_WAIT_L(n) asm volatile("s_waitcnt lgkmcnt(" #n ")" ::: "memory")
; #define PG8_BAR __builtin_amdgcn_s_barrier()
; #define PG8_SCHED __builtin_amdgcn_sched_barrier(0)
; template <class Epi, bool ALIGN_EPI>
; __device__ __forceinline__ void gemm_phase(LAS unsigned char* lds, const Gemm g, const StaticOrder& S, const Epi& E, const int tid) {
;     ...
;             PG8_WAIT_V(8); PG8_WAIT_L(0); PG8_BAR; PG8_MMA(0, 0, At, B0); PG8_MMA(0, 1, At, B1); PG8_BAR; PG8_SCHED;
;             PG8_LDA(At, 0, 1); PG8_STAGE(PG8_SB(0, 0), b2, voffB); PG8_STAGE(PG8_SB(0, 1), b2 + hstepB, voffB); PG8_STAGE(PG8_SA(0, 0), a2, voffA);
	s_barrier
	s_add_i32 s89, s89, s61
	s_mov_b32 m0, s89
	ds_read_b128 v[184:187], v171 offset:16384
	ds_read_b128 v[188:191], v171 offset:17408
	ds_read_b128 v[192:195], v171 offset:18432
	ds_read_b128 v[196:199], v171 offset:19456


; #define PG8_STAGE(bufoff, gbase, voff) do { _Pragma("unroll") for (int _i = 0; _i < 2; ++_i) \
;         __builtin_amdgcn_global_load_lds((const unsigned*)((const char*)(gbase) + (voff)[_i]), (LAS unsigned*)(lds + (bufoff) + ldsw + _i * 8192), 16, 0, 0); } while (0)
; #define PG8_LDA(dst, b, h) do { _Pragma("unroll") for (int m = 0; m < 4; ++m) _Pragma("unroll") for (int k = 0; k < 2; ++k) dst[m][k] = *(const LAS bf16x8*)(lds + PG8_SA(b, h) + aoff + m * 2048 + k * 1024); } while (0)
; #define PG8_MMA(ai, bj, At, Bt) do { __builtin_amdgcn_s_setprio(1); _Pragma("unroll") for (int m = 0; m < 4; ++m) _Pragma("unroll") for (int n = 0; n < 2; ++n) _Pragma("unroll") for (int k = 0; k < 2; ++k) \
;         acc[ai][bj][m][n] = __builtin_amdgcn_mfma_f32_16x16x32_bf16(Bt[n][k], At[m][k], acc[ai][bj][m][n], 0, 0, 0); __builtin_amdgcn_s_setprio(0); } while (0)
; #define PG8_WAIT_V(n) asm volatile("s_waitcnt vmcnt(" #n ")" ::: "memory")
; #define PG8_WAIT_L(n) asm volatile("s_waitcnt lgkmcnt(" #n ")" ::: "memory")
; #define PG8_BAR __builtin_amdgcn_s_barrier()
; #define PG8_SCHED __builtin_amdgcn_sched_barrier(0)
; template <class Epi, bool ALIGN_EPI>
; __device__ __forceinline__ void gemm_phase(LAS unsigned char* lds, const Gemm g, const StaticOrder& S, const Epi& E, const int tid) {
;     ...
;             PG8_LDA(At, 0, 1); PG8_STAGE(PG8_SB(0, 0), b2, voffB); PG8_STAGE(PG8_SB(0, 1), b2 + hstepB, voffB); PG8_STAGE(PG8_SA(0, 0), a2, voffA);
;             PG8_WAIT_V(8); PG8_WAIT_L(0); PG8_BAR; PG8_MMA(1, 0, At, B0); PG8_MMA(1, 1, At, B1); PG8_BAR; PG8_SCHED;
	global_load_lds_dwordx4 v144, s[52:53]
	s_add_i32 m0, s89, 0x2000
	s_add_u32 s90, s52, 0x4000
	s_addc_u32 s91, s53, 0
	s_add_i32 s89, s92, s61
	global_load_lds_dwordx4 v140, s[52:53]
	s_mov_b32 m0, s89
	ds_read_b128 v[226:229], v171 offset:23552
	global_load_lds_dwordx4 v144, s[90:91]
	s_add_i32 m0, s89, 0x2000
	ds_read_b128 v[222:225], v171 offset:22528
	global_load_lds_dwordx4 v140, s[90:91]
	s_mov_b32 m0, s71
	ds_read_b128 v[218:221], v171 offset:21504
	global_load_lds_dwordx4 v146, s[54:55]
	s_mov_b32 m0, s72
	ds_read_b128 v[214:217], v171 offset:20480
	global_load_lds_dwordx4 v142, s[54:55]
	s_waitcnt vmcnt(8)
	s_waitcnt lgkmcnt(0)
	s_barrier


; #define PG8_MMA(ai, bj, At, Bt) do { __builtin_amdgcn_s_setprio(1); _Pragma("unroll") for (int m = 0; m < 4; ++m) _Pragma("unroll") for (int n = 0; n < 2; ++n) _Pragma("unroll") for (int k = 0; k < 2; ++k) \
;         acc[ai][bj][m][n] = __builtin_amdgcn_mfma_f32_16x16x32_bf16(Bt[n][k], At[m][k], acc[ai][bj][m][n], 0, 0, 0); __builtin_amdgcn_s_setprio(0); } while (0)
; #define PG8_WAIT_V(n) asm volatile("s_waitcnt vmcnt(" #n ")" ::: "memory")
; #define PG8_WAIT_L(n) asm volatile("s_waitcnt lgkmcnt(" #n ")" ::: "memory")
; #define PG8_BAR __builtin_amdgcn_s_barrier()
; #define PG8_SCHED __builtin_amdgcn_sched_barrier(0)
; template <class Epi, bool ALIGN_EPI>
; __device__ __forceinline__ void gemm_phase(LAS unsigned char* lds, const Gemm g, const StaticOrder& S, const Epi& E, const int tid) {
;     ...
;             PG8_WAIT_V(8); PG8_WAIT_L(0); PG8_BAR; PG8_MMA(1, 0, At, B0); PG8_MMA(1, 1, At, B1); PG8_BAR; PG8_SCHED;
	v_mfma_f32_16x16x32_bf16 v[84:87], v[132:135], v[184:187], v[84:87]
	v_mfma_f32_16x16x32_bf16 v[84:87], v[136:139], v[188:191], v[84:87]
	v_mfma_f32_16x16x32_bf16 v[72:75], v[136:139], v[196:199], v[72:75]
	v_mfma_f32_16x16x32_bf16 v[72:75], v[132:135], v[192:195], v[72:75]
	v_mfma_f32_16x16x32_bf16 v[64:67], v[132:135], v[214:217], v[64:67]
	v_mfma_f32_16x16x32_bf16 v[64:67], v[136:139], v[218:221], v[64:67]
	v_mfma_f32_16x16x32_bf16 v[52:55], v[136:139], v[226:229], v[52:55]
	v_mfma_f32_16x16x32_bf16 v[52:55], v[132:135], v[222:225], v[52:55]
	v_mfma_f32_16x16x32_bf16 v[28:31], v[152:155], v[222:225], v[28:31]
	v_mfma_f32_16x16x32_bf16 v[28:31], v[156:159], v[226:229], v[28:31]
	v_mfma_f32_16x16x32_bf16 v[36:39], v[156:159], v[218:221], v[36:39]
	v_mfma_f32_16x16x32_bf16 v[36:39], v[152:155], v[214:217], v[36:39]
	v_mfma_f32_16x16x32_bf16 v[44:47], v[152:155], v[192:195], v[44:47]
	v_mfma_f32_16x16x32_bf16 v[44:47], v[156:159], v[196:199], v[44:47]
	v_mfma_f32_16x16x32_bf16 v[56:59], v[156:159], v[188:191], v[56:59]
	v_mfma_f32_16x16x32_bf16 v[56:59], v[152:155], v[184:187], v[56:59]


; #define PG8_MMA(ai, bj, At, Bt) do { __builtin_amdgcn_s_setprio(1); _Pragma("unroll") for (int m = 0; m < 4; ++m) _Pragma("unroll") for (int n = 0; n < 2; ++n) _Pragma("unroll") for (int k = 0; k < 2; ++k) \
;         acc[ai][bj][m][n] = __builtin_amdgcn_mfma_f32_16x16x32_bf16(Bt[n][k], At[m][k], acc[ai][bj][m][n], 0, 0, 0); __builtin_amdgcn_s_setprio(0); } while (0)
; #define PG8_WAIT_V(n) asm volatile("s_waitcnt vmcnt(" #n ")" ::: "memory")
; #define PG8_WAIT_L(n) asm volatile("s_waitcnt lgkmcnt(" #n ")" ::: "memory")
; #define PG8_BAR __builtin_amdgcn_s_barrier()
; #define PG8_SCHED __builtin_amdgcn_sched_barrier(0)
; template <class Epi, bool ALIGN_EPI>
; __device__ __forceinline__ void gemm_phase(LAS unsigned char* lds, const Gemm g, const StaticOrder& S, const Epi& E, const int tid) {
;     ...
;             PG8_WAIT_V(8); PG8_WAIT_L(0); PG8_BAR; PG8_MMA(1, 0, At, B0); PG8_MMA(1, 1, At, B1); PG8_BAR; PG8_SCHED;
	v_mfma_f32_16x16x32_bf16 v[20:23], v[176:179], v[184:187], v[20:23]
	v_mfma_f32_16x16x32_bf16 v[20:23], v[180:183], v[188:191], v[20:23]
	v_mfma_f32_16x16x32_bf16 v[12:15], v[180:183], v[196:199], v[12:15]
	v_mfma_f32_16x16x32_bf16 v[12:15], v[176:179], v[192:195], v[12:15]
	v_mfma_f32_16x16x32_bf16 v[8:11], v[176:179], v[214:217], v[8:11]
	v_mfma_f32_16x16x32_bf16 v[8:11], v[180:183], v[218:221], v[8:11]
	v_mfma_f32_16x16x32_bf16 v[2:5], v[176:179], v[222:225], v[4:7]
	v_mfma_f32_16x16x32_bf16 v[2:5], v[180:183], v[226:229], v[2:5]
	v_mfma_f32_16x16x32_bf16 v[16:19], v[172:175], v[226:229], v[16:19]
	v_mfma_f32_16x16x32_bf16 v[16:19], v[160:163], v[222:225], v[16:19]
	v_mfma_f32_16x16x32_bf16 v[24:27], v[160:163], v[214:217], v[24:27]
	v_mfma_f32_16x16x32_bf16 v[24:27], v[172:175], v[218:221], v[24:27]
	v_mfma_f32_16x16x32_bf16 v[32:35], v[172:175], v[196:199], v[32:35]
	v_mfma_f32_16x16x32_bf16 v[32:35], v[160:163], v[192:195], v[32:35]
	v_mfma_f32_16x16x32_bf16 v[40:43], v[160:163], v[184:187], v[40:43]
	v_mfma_f32_16x16x32_bf16 v[40:43], v[172:175], v[188:191], v[40:43]

; #define PG8_STAGE(bufoff, gbase, voff) do { _Pragma("unroll") for (int _i = 0; _i < 2; ++_i) \
;         __builtin_amdgcn_global_load_lds((const unsigned*)((const char*)(gbase) + (voff)[_i]), (LAS unsigned*)(lds + (bufoff) + ldsw + _i * 8192), 16, 0, 0); } while (0)
; #define PG8_LDA(dst, b, h) do { _Pragma("unroll") for (int m = 0; m < 4; ++m) _Pragma("unroll") for (int k = 0; k < 2; ++k) dst[m][k] = *(const LAS bf16x8*)(lds + PG8_SA(b, h) + aoff + m * 2048 + k * 1024); } while (0)
; #define PG8_LDB(dst, b, h) do { _Pragma("unroll") for (int n = 0; n < 2; ++n) _Pragma("unroll") for (int k = 0; k < 2; ++k) dst[n][k] = *(const LAS bf16x8*)(lds + PG8_SB(b, h) + boff + n * 2048 + k * 1024); } while (0)
; #define PG8_SCHED __builtin_amdgcn_sched_barrier(0)
; template <class Epi, bool ALIGN_EPI>
; __device__ __forceinline__ void gemm_phase(LAS unsigned char* lds, const Gemm g, const StaticOrder& S, const Epi& E, const int tid) {
;     ...
;             PG8_LDB(B0, 1, 0); PG8_LDB(B1, 1, 1); PG8_SCHED; PG8_LDA(At, 1, 0); PG8_STAGE(PG8_SA(0, 1), a2 + hstepA, voffA);
	s_barrier
	s_add_i32 s89, 0, 0x18000
	v_add_u32_e32 v0, s89, v167
	s_add_i32 s90, 0, 0x1c000
	ds_read_b128 v[132:135], v0
	ds_read_b128 v[136:139], v0 offset:1024
	ds_read_b128 v[152:155], v0 offset:2048
	ds_read_b128 v[156:159], v0 offset:3072
	v_add_u32_e32 v0, s90, v167
	ds_read_b128 v[160:163], v0
	ds_read_b128 v[172:175], v0 offset:1024
	ds_read_b128 v[176:179], v0 offset:2048
	ds_read_b128 v[180:183], v0 offset:3072
	s_add_u32 s54, s54, 0x4000
	s_addc_u32 s55, s55, 0
	s_mov_b32 m0, s73
	ds_read_b128 v[184:187], v171 offset:32768
	ds_read_b128 v[188:191], v171 offset:33792
	ds_read_b128 v[192:195], v171 offset:34816
	ds_read_b128 v[196:199], v171 offset:35840
	ds_read_b128 v[214:217], v171 offset:36864
	ds_read_b128 v[218:221], v171 offset:37888
	ds_read_b128 v[222:225], v171 offset:38912

; #define PG8_STAGE(bufoff, gbase, voff) do { _Pragma("unroll") for (int _i = 0; _i < 2; ++_i) \
;         __builtin_amdgcn_global_load_lds((const unsigned*)((const char*)(gbase) + (voff)[_i]), (LAS unsigned*)(lds + (bufoff) + ldsw + _i * 8192), 16, 0, 0); } while (0)
; #define PG8_LDA(dst, b, h) do { _Pragma("unroll") for (int m = 0; m < 4; ++m) _Pragma("unroll") for (int k = 0; k < 2; ++k) dst[m][k] = *(const LAS bf16x8*)(lds + PG8_SA(b, h) + aoff + m * 2048 + k * 1024); } while (0)
; #define PG8_LDB(dst, b, h) do { _Pragma("unroll") for (int n = 0; n < 2; ++n) _Pragma("unroll") for (int k = 0; k < 2; ++k) dst[n][k] = *(const LAS bf16x8*)(lds + PG8_SB(b, h) + boff + n * 2048 + k * 1024); } while (0)
; #define PG8_MMA(ai, bj, At, Bt) do { __builtin_amdgcn_s_setprio(1); _Pragma("unroll") for (int m = 0; m < 4; ++m) _Pragma("unroll") for (int n = 0; n < 2; ++n) _Pragma("unroll") for (int k = 0; k < 2; ++k) \
;         acc[ai][bj][m][n] = __builtin_amdgcn_mfma_f32_16x16x32_bf16(Bt[n][k], At[m][k], acc[ai][bj][m][n], 0, 0, 0); __builtin_amdgcn_s_setprio(0); } while (0)
; #define PG8_WAIT_V(n) asm volatile("s_waitcnt vmcnt(" #n ")" ::: "memory")
; #define PG8_WAIT_L(n) asm volatile("s_waitcnt lgkmcnt(" #n ")" ::: "memory")
; #define PG8_BAR __builtin_amdgcn_s_barrier()
; #define PG8_SCHED __builtin_amdgcn_sched_barrier(0)
; template <class Epi, bool ALIGN_EPI>
; __device__ __forceinline__ void gemm_phase(LAS unsigned char* lds, const Gemm g, const StaticOrder& S, const Epi& E, const int tid) {
;     ...
;             PG8_LDB(B0, 1, 0); PG8_LDB(B1, 1, 1); PG8_SCHED; PG8_LDA(At, 1, 0); PG8_STAGE(PG8_SA(0, 1), a2 + hstepA, voffA);
;             PG8_WAIT_V(8); PG8_WAIT_L(0); PG8_BAR; PG8_MMA(0, 0, At, B0); PG8_MMA(0, 1, At, B1); PG8_BAR; PG8_SCHED;
	global_load_lds_dwordx4 v146, s[54:55]
	s_mov_b32 m0, s74
	ds_read_b128 v[226:229], v171 offset:39936
	global_load_lds_dwordx4 v142, s[54:55]
	s_waitcnt vmcnt(8)
	s_waitcnt lgkmcnt(0)
	s_barrier


; #define PG8_MMA(ai, bj, At, Bt) do { __builtin_amdgcn_s_setprio(1); _Pragma("unroll") for (int m = 0; m < 4; ++m) _Pragma("unroll") for (int n = 0; n < 2; ++n) _Pragma("unroll") for (int k = 0; k < 2; ++k) \
;         acc[ai][bj][m][n] = __builtin_amdgcn_mfma_f32_16x16x32_bf16(Bt[n][k], At[m][k], acc[ai][bj][m][n], 0, 0, 0); __builtin_amdgcn_s_setprio(0); } while (0)
; #define PG8_WAIT_V(n) asm volatile("s_waitcnt vmcnt(" #n ")" ::: "memory")
; #define PG8_WAIT_L(n) asm volatile("s_waitcnt lgkmcnt(" #n ")" ::: "memory")
; #define PG8_BAR __builtin_amdgcn_s_barrier()
; #define PG8_SCHED __builtin_amdgcn_sched_barrier(0)
; template <class Epi, bool ALIGN_EPI>
; __device__ __forceinline__ void gemm_phase(LAS unsigned char* lds, const Gemm g, const StaticOrder& S, const Epi& E, const int tid) {
;     ...
;             PG8_WAIT_V(8); PG8_WAIT_L(0); PG8_BAR; PG8_MMA(0, 0, At, B0); PG8_MMA(0, 1, At, B1); PG8_BAR; PG8_SCHED;
	v_mfma_f32_16x16x32_bf16 v[128:131], v[132:135], v[184:187], v[128:131]
	v_mfma_f32_16x16x32_bf16 v[128:131], v[136:139], v[188:191], v[128:131]
	v_mfma_f32_16x16x32_bf16 v[124:127], v[136:139], v[196:199], v[124:127]
	v_mfma_f32_16x16x32_bf16 v[124:127], v[132:135], v[192:195], v[124:127]
	v_mfma_f32_16x16x32_bf16 v[120:123], v[132:135], v[214:217], v[120:123]
	v_mfma_f32_16x16x32_bf16 v[120:123], v[136:139], v[218:221], v[120:123]
	v_mfma_f32_16x16x32_bf16 v[112:115], v[136:139], v[226:229], v[112:115]
	v_mfma_f32_16x16x32_bf16 v[112:115], v[132:135], v[222:225], v[112:115]
	v_mfma_f32_16x16x32_bf16 v[92:95], v[152:155], v[222:225], v[92:95]
	v_mfma_f32_16x16x32_bf16 v[92:95], v[156:159], v[226:229], v[92:95]
	v_mfma_f32_16x16x32_bf16 v[100:103], v[156:159], v[218:221], v[100:103]
	v_mfma_f32_16x16x32_bf16 v[100:103], v[152:155], v[214:217], v[100:103]
	v_mfma_f32_16x16x32_bf16 v[108:111], v[152:155], v[192:195], v[108:111]
	v_mfma_f32_16x16x32_bf16 v[108:111], v[156:159], v[196:199], v[108:111]
	v_mfma_f32_16x16x32_bf16 v[116:119], v[156:159], v[188:191], v[116:119]
	v_mfma_f32_16x16x32_bf16 v[116:119], v[152:155], v[184:187], v[116:119]


; #define PG8_MMA(ai, bj, At, Bt) do { __builtin_amdgcn_s_setprio(1); _Pragma("unroll") for (int m = 0; m < 4; ++m) _Pragma("unroll") for (int n = 0; n < 2; ++n) _Pragma("unroll") for (int k = 0; k < 2; ++k) \
;         acc[ai][bj][m][n] = __builtin_amdgcn_mfma_f32_16x16x32_bf16(Bt[n][k], At[m][k], acc[ai][bj][m][n], 0, 0, 0); __builtin_amdgcn_s_setprio(0); } while (0)
; #define PG8_WAIT_V(n) asm volatile("s_waitcnt vmcnt(" #n ")" ::: "memory")
; #define PG8_WAIT_L(n) asm volatile("s_waitcnt lgkmcnt(" #n ")" ::: "memory")
; #define PG8_BAR __builtin_amdgcn_s_barrier()
; #define PG8_SCHED __builtin_amdgcn_sched_barrier(0)
; template <class Epi, bool ALIGN_EPI>
; __device__ __forceinline__ void gemm_phase(LAS unsigned char* lds, const Gemm g, const StaticOrder& S, const Epi& E, const int tid) {
;     ...
;             PG8_WAIT_V(8); PG8_WAIT_L(0); PG8_BAR; PG8_MMA(0, 0, At, B0); PG8_MMA(0, 1, At, B1); PG8_BAR; PG8_SCHED;
	v_mfma_f32_16x16x32_bf16 v[80:83], v[176:179], v[184:187], v[80:83]
	v_mfma_f32_16x16x32_bf16 v[80:83], v[180:183], v[188:191], v[80:83]
	v_mfma_f32_16x16x32_bf16 v[68:71], v[180:183], v[196:199], v[68:71]
	v_mfma_f32_16x16x32_bf16 v[68:71], v[176:179], v[192:195], v[68:71]
	v_mfma_f32_16x16x32_bf16 v[60:63], v[176:179], v[214:217], v[60:63]
	v_mfma_f32_16x16x32_bf16 v[60:63], v[180:183], v[218:221], v[60:63]
	v_mfma_f32_16x16x32_bf16 v[48:51], v[180:183], v[226:229], v[48:51]
	v_mfma_f32_16x16x32_bf16 v[48:51], v[176:179], v[222:225], v[48:51]
	v_mfma_f32_16x16x32_bf16 v[76:79], v[160:163], v[222:225], v[76:79]
	v_mfma_f32_16x16x32_bf16 v[76:79], v[172:175], v[226:229], v[76:79]
	v_mfma_f32_16x16x32_bf16 v[88:91], v[172:175], v[218:221], v[88:91]
	v_mfma_f32_16x16x32_bf16 v[88:91], v[160:163], v[214:217], v[88:91]
	v_mfma_f32_16x16x32_bf16 v[96:99], v[160:163], v[192:195], v[96:99]
	v_mfma_f32_16x16x32_bf16 v[96:99], v[172:175], v[196:199], v[96:99]
	v_mfma_f32_16x16x32_bf16 v[104:107], v[172:175], v[188:191], v[104:107]
	v_mfma_f32_16x16x32_bf16 v[104:107], v[160:163], v[184:187], v[104:107]

; #define PG8_STAGE(bufoff, gbase, voff) do { _Pragma("unroll") for (int _i = 0; _i < 2; ++_i) \
;         __builtin_amdgcn_global_load_lds((const unsigned*)((const char*)(gbase) + (voff)[_i]), (LAS unsigned*)(lds + (bufoff) + ldsw + _i * 8192), 16, 0, 0); } while (0)
; #define PG8_LDA(dst, b, h) do { _Pragma("unroll") for (int m = 0; m < 4; ++m) _Pragma("unroll") for (int k = 0; k < 2; ++k) dst[m][k] = *(const LAS bf16x8*)(lds + PG8_SA(b, h) + aoff + m * 2048 + k * 1024); } while (0)
; #define PG8_MMA(ai, bj, At, Bt) do { __builtin_amdgcn_s_setprio(1); _Pragma("unroll") for (int m = 0; m < 4; ++m) _Pragma("unroll") for (int n = 0; n < 2; ++n) _Pragma("unroll") for (int k = 0; k < 2; ++k) \
;         acc[ai][bj][m][n] = __builtin_amdgcn_mfma_f32_16x16x32_bf16(Bt[n][k], At[m][k], acc[ai][bj][m][n], 0, 0, 0); __builtin_amdgcn_s_setprio(0); } while (0)
; #define PG8_WAIT_V(n) asm volatile("s_waitcnt vmcnt(" #n ")" ::: "memory")
; #define PG8_WAIT_L(n) asm volatile("s_waitcnt lgkmcnt(" #n ")" ::: "memory")
; #define PG8_BAR __builtin_amdgcn_s_barrier()
; #define PG8_SCHED __builtin_amdgcn_sched_barrier(0)
; template <class Epi, bool ALIGN_EPI>
; __device__ __forceinline__ void gemm_phase(LAS unsigned char* lds, const Gemm g, const StaticOrder& S, const Epi& E, const int tid) {
;     ...
;             PG8_WAIT_V(8); PG8_WAIT_L(0); PG8_BAR; PG8_MMA(0, 0, At, B0); PG8_MMA(0, 1, At, B1); PG8_BAR; PG8_SCHED;
;             PG8_LDA(At, 1, 1); PG8_STAGE(PG8_SB(1, 0), b3, voffB); PG8_STAGE(PG8_SB(1, 1), b3 + hstepB, voffB); PG8_STAGE(PG8_SA(1, 0), a3, voffA);
	s_barrier
	s_add_u32 s54, s52, 0x8000
	s_addc_u32 s55, s53, 0
	s_add_i32 s89, s89, s61
	s_mov_b32 m0, s89
	ds_read_b128 v[184:187], v171 offset:49152
	ds_read_b128 v[188:191], v171 offset:50176
	ds_read_b128 v[192:195], v171 offset:51200
	ds_read_b128 v[196:199], v171 offset:52224


; #define PG8_STAGE(bufoff, gbase, voff) do { _Pragma("unroll") for (int _i = 0; _i < 2; ++_i) \
;         __builtin_amdgcn_global_load_lds((const unsigned*)((const char*)(gbase) + (voff)[_i]), (LAS unsigned*)(lds + (bufoff) + ldsw + _i * 8192), 16, 0, 0); } while (0)
; #define PG8_LDA(dst, b, h) do { _Pragma("unroll") for (int m = 0; m < 4; ++m) _Pragma("unroll") for (int k = 0; k < 2; ++k) dst[m][k] = *(const LAS bf16x8*)(lds + PG8_SA(b, h) + aoff + m * 2048 + k * 1024); } while (0)
; #define PG8_MMA(ai, bj, At, Bt) do { __builtin_amdgcn_s_setprio(1); _Pragma("unroll") for (int m = 0; m < 4; ++m) _Pragma("unroll") for (int n = 0; n < 2; ++n) _Pragma("unroll") for (int k = 0; k < 2; ++k) \
;         acc[ai][bj][m][n] = __builtin_amdgcn_mfma_f32_16x16x32_bf16(Bt[n][k], At[m][k], acc[ai][bj][m][n], 0, 0, 0); __builtin_amdgcn_s_setprio(0); } while (0)
; #define PG8_WAIT_V(n) asm volatile("s_waitcnt vmcnt(" #n ")" ::: "memory")
; #define PG8_WAIT_L(n) asm volatile("s_waitcnt lgkmcnt(" #n ")" ::: "memory")
; #define PG8_BAR __builtin_amdgcn_s_barrier()
; #define PG8_SCHED __builtin_amdgcn_sched_barrier(0)
; template <class Epi, bool ALIGN_EPI>
; __device__ __forceinline__ void gemm_phase(LAS unsigned char* lds, const Gemm g, const StaticOrder& S, const Epi& E, const int tid) {
;     ...
;             PG8_LDA(At, 1, 1); PG8_STAGE(PG8_SB(1, 0), b3, voffB); PG8_STAGE(PG8_SB(1, 1), b3 + hstepB, voffB); PG8_STAGE(PG8_SA(1, 0), a3, voffA);
;             PG8_WAIT_V(8); PG8_WAIT_L(0); PG8_BAR; PG8_MMA(1, 0, At, B0); PG8_MMA(1, 1, At, B1); PG8_BAR; PG8_SCHED;
	global_load_lds_dwordx4 v144, s[54:55]
	s_add_i32 m0, s89, 0x2000
	s_add_u32 s52, s52, 0xc000
	s_addc_u32 s53, s53, 0
	global_load_lds_dwordx4 v140, s[54:55]
	s_add_i32 s54, s90, s61
	s_mov_b32 m0, s54
	ds_read_b128 v[226:229], v171 offset:56320
	global_load_lds_dwordx4 v144, s[52:53]
	s_add_i32 m0, s54, 0x2000
	ds_read_b128 v[222:225], v171 offset:55296
	global_load_lds_dwordx4 v140, s[52:53]
	s_mov_b32 m0, s77
	ds_read_b128 v[218:221], v171 offset:54272
	global_load_lds_dwordx4 v146, s[50:51]
	s_mov_b32 m0, s78
	ds_read_b128 v[214:217], v171 offset:53248
	global_load_lds_dwordx4 v142, s[50:51]
	s_waitcnt vmcnt(8)
	s_waitcnt lgkmcnt(0)
	s_barrier


; #define PG8_MMA(ai, bj, At, Bt) do { __builtin_amdgcn_s_setprio(1); _Pragma("unroll") for (int m = 0; m < 4; ++m) _Pragma("unroll") for (int n = 0; n < 2; ++n) _Pragma("unroll") for (int k = 0; k < 2; ++k) \
;         acc[ai][bj][m][n] = __builtin_amdgcn_mfma_f32_16x16x32_bf16(Bt[n][k], At[m][k], acc[ai][bj][m][n], 0, 0, 0); __builtin_amdgcn_s_setprio(0); } while (0)
; #define PG8_WAIT_V(n) asm volatile("s_waitcnt vmcnt(" #n ")" ::: "memory")
; #define PG8_WAIT_L(n) asm volatile("s_waitcnt lgkmcnt(" #n ")" ::: "memory")
; #define PG8_BAR __builtin_amdgcn_s_barrier()
; #define PG8_SCHED __builtin_amdgcn_sched_barrier(0)
; template <class Epi, bool ALIGN_EPI>
; __device__ __forceinline__ void gemm_phase(LAS unsigned char* lds, const Gemm g, const StaticOrder& S, const Epi& E, const int tid) {
;     ...
;             PG8_WAIT_V(8); PG8_WAIT_L(0); PG8_BAR; PG8_MMA(1, 0, At, B0); PG8_MMA(1, 1, At, B1); PG8_BAR; PG8_SCHED;
	v_mfma_f32_16x16x32_bf16 v[84:87], v[132:135], v[184:187], v[84:87]
	v_mfma_f32_16x16x32_bf16 v[84:87], v[136:139], v[188:191], v[84:87]
	v_mfma_f32_16x16x32_bf16 v[72:75], v[136:139], v[196:199], v[72:75]
	v_mfma_f32_16x16x32_bf16 v[72:75], v[132:135], v[192:195], v[72:75]
	v_mfma_f32_16x16x32_bf16 v[64:67], v[132:135], v[214:217], v[64:67]
	v_mfma_f32_16x16x32_bf16 v[64:67], v[136:139], v[218:221], v[64:67]
	v_mfma_f32_16x16x32_bf16 v[52:55], v[136:139], v[226:229], v[52:55]
	v_mfma_f32_16x16x32_bf16 v[52:55], v[132:135], v[222:225], v[52:55]
	v_mfma_f32_16x16x32_bf16 v[28:31], v[152:155], v[222:225], v[28:31]
	v_mfma_f32_16x16x32_bf16 v[28:31], v[156:159], v[226:229], v[28:31]
	v_mfma_f32_16x16x32_bf16 v[36:39], v[156:159], v[218:221], v[36:39]
	v_mfma_f32_16x16x32_bf16 v[36:39], v[152:155], v[214:217], v[36:39]
	v_mfma_f32_16x16x32_bf16 v[44:47], v[152:155], v[192:195], v[44:47]
	v_mfma_f32_16x16x32_bf16 v[44:47], v[156:159], v[196:199], v[44:47]
	v_mfma_f32_16x16x32_bf16 v[56:59], v[156:159], v[188:191], v[56:59]
	v_mfma_f32_16x16x32_bf16 v[56:59], v[152:155], v[184:187], v[56:59]


; #define PG8_MMA(ai, bj, At, Bt) do { __builtin_amdgcn_s_setprio(1); _Pragma("unroll") for (int m = 0; m < 4; ++m) _Pragma("unroll") for (int n = 0; n < 2; ++n) _Pragma("unroll") for (int k = 0; k < 2; ++k) \
;         acc[ai][bj][m][n] = __builtin_amdgcn_mfma_f32_16x16x32_bf16(Bt[n][k], At[m][k], acc[ai][bj][m][n], 0, 0, 0); __builtin_amdgcn_s_setprio(0); } while (0)
; #define PG8_WAIT_V(n) asm volatile("s_waitcnt vmcnt(" #n ")" ::: "memory")
; #define PG8_WAIT_L(n) asm volatile("s_waitcnt lgkmcnt(" #n ")" ::: "memory")
; #define PG8_BAR __builtin_amdgcn_s_barrier()
; #define PG8_SCHED __builtin_amdgcn_sched_barrier(0)
; template <class Epi, bool ALIGN_EPI>
; __device__ __forceinline__ void gemm_phase(LAS unsigned char* lds, const Gemm g, const StaticOrder& S, const Epi& E, const int tid) {
;     ...
;             PG8_WAIT_V(8); PG8_WAIT_L(0); PG8_BAR; PG8_MMA(1, 0, At, B0); PG8_MMA(1, 1, At, B1); PG8_BAR; PG8_SCHED;
	v_mfma_f32_16x16x32_bf16 v[20:23], v[176:179], v[184:187], v[20:23]
	v_mfma_f32_16x16x32_bf16 v[20:23], v[180:183], v[188:191], v[20:23]
	v_mfma_f32_16x16x32_bf16 v[12:15], v[180:183], v[196:199], v[12:15]
	v_mfma_f32_16x16x32_bf16 v[12:15], v[176:179], v[192:195], v[12:15]
	v_mfma_f32_16x16x32_bf16 v[6:9], v[176:179], v[214:217], v[8:11]
	v_mfma_f32_16x16x32_bf16 v[8:11], v[180:183], v[218:221], v[6:9]
	v_mfma_f32_16x16x32_bf16 v[2:5], v[176:179], v[222:225], v[2:5]
	v_mfma_f32_16x16x32_bf16 v[4:7], v[180:183], v[226:229], v[2:5]
	v_mfma_f32_16x16x32_bf16 v[16:19], v[172:175], v[226:229], v[16:19]
	v_mfma_f32_16x16x32_bf16 v[16:19], v[160:163], v[222:225], v[16:19]
	v_mfma_f32_16x16x32_bf16 v[24:27], v[160:163], v[214:217], v[24:27]
	v_mfma_f32_16x16x32_bf16 v[24:27], v[172:175], v[218:221], v[24:27]
	v_mfma_f32_16x16x32_bf16 v[32:35], v[172:175], v[196:199], v[32:35]
	v_mfma_f32_16x16x32_bf16 v[32:35], v[160:163], v[192:195], v[32:35]
	v_mfma_f32_16x16x32_bf16 v[40:43], v[160:163], v[184:187], v[40:43]
	v_mfma_f32_16x16x32_bf16 v[40:43], v[172:175], v[188:191], v[40:43]

; #define PG8_STAGE(bufoff, gbase, voff) do { _Pragma("unroll") for (int _i = 0; _i < 2; ++_i) \
;         __builtin_amdgcn_global_load_lds((const unsigned*)((const char*)(gbase) + (voff)[_i]), (LAS unsigned*)(lds + (bufoff) + ldsw + _i * 8192), 16, 0, 0); } while (0)
; #define PG8_LDA(dst, b, h) do { _Pragma("unroll") for (int m = 0; m < 4; ++m) _Pragma("unroll") for (int k = 0; k < 2; ++k) dst[m][k] = *(const LAS bf16x8*)(lds + PG8_SA(b, h) + aoff + m * 2048 + k * 1024); } while (0)
; #define PG8_LDB(dst, b, h) do { _Pragma("unroll") for (int n = 0; n < 2; ++n) _Pragma("unroll") for (int k = 0; k < 2; ++k) dst[n][k] = *(const LAS bf16x8*)(lds + PG8_SB(b, h) + boff + n * 2048 + k * 1024); } while (0)
; #define PG8_BAR __builtin_amdgcn_s_barrier()
; template <class Epi, bool ALIGN_EPI>
; __device__ __forceinline__ void gemm_phase(LAS unsigned char* lds, const Gemm g, const StaticOrder& S, const Epi& E, const int tid) {
;     ...
;         for (int t = 0; t < nt; t += 2) {
;             const bool last = (t == nt - 2);
;             const char* a1 = cA + (size_t)(t + 1) * kstepA;
;             const char* a2 = last ? nA : cA + (size_t)(t + 2) * kstepA; const char* b2 = last ? nB : cB + (size_t)(t + 2) * kstepB;
;             const char* a3 = a2 + kstepA; const char* b3 = b2 + kstepB;
;             PG8_LDB(B0, 0, 0); PG8_LDB(B1, 0, 1); PG8_SCHED; PG8_LDA(At, 0, 0); PG8_STAGE(PG8_SA(1, 1), a1 + hstepA, voffA);
;             PG8_WAIT_V(8); PG8_WAIT_L(0); PG8_BAR; PG8_MMA(0, 0, At, B0); PG8_MMA(0, 1, At, B1); PG8_BAR; PG8_SCHED;
;             PG8_LDA(At, 0, 1); PG8_STAGE(PG8_SB(0, 0), b2, voffB); PG8_STAGE(PG8_SB(0, 1), b2 + hstepB, voffB); PG8_STAGE(PG8_SA(0, 0), a2, voffA);
;             PG8_WAIT_V(8); PG8_WAIT_L(0); PG8_BAR; PG8_MMA(1, 0, At, B0); PG8_MMA(1, 1, At, B1); PG8_BAR; PG8_SCHED;
;             PG8_LDB(B0, 1, 0); PG8_LDB(B1, 1, 1); PG8_SCHED; PG8_LDA(At, 1, 0); PG8_STAGE(PG8_SA(0, 1), a2 + hstepA, voffA);
;             PG8_WAIT_V(8); PG8_WAIT_L(0); PG8_BAR; PG8_MMA(0, 0, At, B0); PG8_MMA(0, 1, At, B1); PG8_BAR; PG8_SCHED;
;             PG8_LDA(At, 1, 1); PG8_STAGE(PG8_SB(1, 0), b3, voffB); PG8_STAGE(PG8_SB(1, 1), b3 + hstepB, voffB); PG8_STAGE(PG8_SA(1, 0), a3, voffA);
;             PG8_WAIT_V(8); PG8_WAIT_L(0); PG8_BAR; PG8_MMA(1, 0, At, B0); PG8_MMA(1, 1, At, B1); PG8_BAR; PG8_SCHED;
;         }
;         if constexpr (ALIGN_EPI) { if (wr == 0) PG8_BAR; }
	s_barrier
	s_add_i32 s88, s88, 2
	s_add_u32 s48, s48, 0x10000
	s_addc_u32 s49, s49, 0
	s_add_u32 s86, s86, 0x10000
	s_addc_u32 s87, s87, 0
	s_cmp_gt_u32 s88, 29
	s_cbranch_scc0 .LBB0_385
	s_and_b64 vcc, exec, s[34:35]
	s_cbranch_vccz .LBB0_388
	s_barrier

; #define PG8_STAGE(bufoff, gbase, voff) do { _Pragma("unroll") for (int _i = 0; _i < 2; ++_i) \
;         __builtin_amdgcn_global_load_lds((const unsigned*)((const char*)(gbase) + (voff)[_i]), (LAS unsigned*)(lds + (bufoff) + ldsw + _i * 8192), 16, 0, 0); } while (0)
; #define PG8_LDA(dst, b, h) do { _Pragma("unroll") for (int m = 0; m < 4; ++m) _Pragma("unroll") for (int k = 0; k < 2; ++k) dst[m][k] = *(const LAS bf16x8*)(lds + PG8_SA(b, h) + aoff + m * 2048 + k * 1024); } while (0)
; #define PG8_LDB(dst, b, h) do { _Pragma("unroll") for (int n = 0; n < 2; ++n) _Pragma("unroll") for (int k = 0; k < 2; ++k) dst[n][k] = *(const LAS bf16x8*)(lds + PG8_SB(b, h) + boff + n * 2048 + k * 1024); } while (0)
; #define PG8_SCHED __builtin_amdgcn_sched_barrier(0)
; template <class Epi, bool ALIGN_EPI>
; __device__ __forceinline__ void gemm_phase(LAS unsigned char* lds, const Gemm g, const StaticOrder& S, const Epi& E, const int tid) {
;     ...
;             PG8_LDB(B0, 0, 0); PG8_LDB(B1, 0, 1); PG8_SCHED; PG8_LDA(At, 0, 0); PG8_STAGE(PG8_SA(1, 1), a1 + hstepA, voffA);
.LBB0_847:
	s_add_u32 s22, s10, 0xfff80080
	s_addc_u32 s23, s11, -1
	s_add_i32 s87, 0, 0x10000
	s_cmp_eq_u32 s86, 28
	s_cselect_b32 s35, s49, s23
	s_cselect_b32 s34, s82, s22
	v_add_u32_e32 v0, s87, v154
	s_cselect_b32 s23, s47, s85
	s_cselect_b32 s22, s83, s84
	s_add_i32 s90, 0, 0x14000
	s_waitcnt lgkmcnt(0)
	ds_read_b128 v[132:135], v0
	ds_read_b128 v[148:151], v0 offset:1024
	ds_read_b128 v[156:159], v0 offset:2048
	ds_read_b128 v[160:163], v0 offset:3072
	v_add_u32_e32 v0, s90, v154
	ds_read_b128 v[164:167], v0
	ds_read_b128 v[168:171], v0 offset:1024
	ds_read_b128 v[172:175], v0 offset:2048
	ds_read_b128 v[176:179], v0 offset:3072
	s_add_i32 m0, s70, 0xc000
	ds_read_b128 v[180:183], v155
	ds_read_b128 v[184:187], v155 offset:1024
	ds_read_b128 v[188:191], v155 offset:2048
	ds_read_b128 v[192:195], v155 offset:3072
	ds_read_b128 v[196:199], v155 offset:4096
	ds_read_b128 v[214:217], v155 offset:5120
	ds_read_b128 v[218:221], v155 offset:6144

; #define PG8_STAGE(bufoff, gbase, voff) do { _Pragma("unroll") for (int _i = 0; _i < 2; ++_i) \
;         __builtin_amdgcn_global_load_lds((const unsigned*)((const char*)(gbase) + (voff)[_i]), (LAS unsigned*)(lds + (bufoff) + ldsw + _i * 8192), 16, 0, 0); } while (0)
; #define PG8_LDA(dst, b, h) do { _Pragma("unroll") for (int m = 0; m < 4; ++m) _Pragma("unroll") for (int k = 0; k < 2; ++k) dst[m][k] = *(const LAS bf16x8*)(lds + PG8_SA(b, h) + aoff + m * 2048 + k * 1024); } while (0)
; #define PG8_LDB(dst, b, h) do { _Pragma("unroll") for (int n = 0; n < 2; ++n) _Pragma("unroll") for (int k = 0; k < 2; ++k) dst[n][k] = *(const LAS bf16x8*)(lds + PG8_SB(b, h) + boff + n * 2048 + k * 1024); } while (0)
; #define PG8_MMA(ai, bj, At, Bt) do { __builtin_amdgcn_s_setprio(1); _Pragma("unroll") for (int m = 0; m < 4; ++m) _Pragma("unroll") for (int n = 0; n < 2; ++n) _Pragma("unroll") for (int k = 0; k < 2; ++k) \
;         acc[ai][bj][m][n] = __builtin_amdgcn_mfma_f32_16x16x32_bf16(Bt[n][k], At[m][k], acc[ai][bj][m][n], 0, 0, 0); __builtin_amdgcn_s_setprio(0); } while (0)
; #define PG8_WAIT_V(n) asm volatile("s_waitcnt vmcnt(" #n ")" ::: "memory")
; #define PG8_WAIT_L(n) asm volatile("s_waitcnt lgkmcnt(" #n ")" ::: "memory")
; #define PG8_BAR __builtin_amdgcn_s_barrier()
; #define PG8_SCHED __builtin_amdgcn_sched_barrier(0)
; template <class Epi, bool ALIGN_EPI>
; __device__ __forceinline__ void gemm_phase(LAS unsigned char* lds, const Gemm g, const StaticOrder& S, const Epi& E, const int tid) {
;     ...
;             PG8_LDB(B0, 0, 0); PG8_LDB(B1, 0, 1); PG8_SCHED; PG8_LDA(At, 0, 0); PG8_STAGE(PG8_SA(1, 1), a1 + hstepA, voffA);
;             PG8_WAIT_V(8); PG8_WAIT_L(0); PG8_BAR; PG8_MMA(0, 0, At, B0); PG8_MMA(0, 1, At, B1); PG8_BAR; PG8_SCHED;
	global_load_lds_dwordx4 v144, s[10:11]
	s_add_i32 m0, s70, 0xe000
	ds_read_b128 v[222:225], v155 offset:7168
	global_load_lds_dwordx4 v146, s[10:11]
	s_waitcnt vmcnt(8)
	s_waitcnt lgkmcnt(0)
	s_barrier


; #define PG8_MMA(ai, bj, At, Bt) do { __builtin_amdgcn_s_setprio(1); _Pragma("unroll") for (int m = 0; m < 4; ++m) _Pragma("unroll") for (int n = 0; n < 2; ++n) _Pragma("unroll") for (int k = 0; k < 2; ++k) \
;         acc[ai][bj][m][n] = __builtin_amdgcn_mfma_f32_16x16x32_bf16(Bt[n][k], At[m][k], acc[ai][bj][m][n], 0, 0, 0); __builtin_amdgcn_s_setprio(0); } while (0)
; #define PG8_WAIT_V(n) asm volatile("s_waitcnt vmcnt(" #n ")" ::: "memory")
; #define PG8_WAIT_L(n) asm volatile("s_waitcnt lgkmcnt(" #n ")" ::: "memory")
; #define PG8_BAR __builtin_amdgcn_s_barrier()
; #define PG8_SCHED __builtin_amdgcn_sched_barrier(0)
; template <class Epi, bool ALIGN_EPI>
; __device__ __forceinline__ void gemm_phase(LAS unsigned char* lds, const Gemm g, const StaticOrder& S, const Epi& E, const int tid) {
;     ...
;             PG8_WAIT_V(8); PG8_WAIT_L(0); PG8_BAR; PG8_MMA(0, 0, At, B0); PG8_MMA(0, 1, At, B1); PG8_BAR; PG8_SCHED;
	v_mfma_f32_16x16x32_bf16 v[8:11], v[132:135], v[180:183], v[8:11]
	v_mfma_f32_16x16x32_bf16 v[8:11], v[148:151], v[184:187], v[8:11]
	v_mfma_f32_16x16x32_bf16 v[52:55], v[148:151], v[192:195], v[52:55]
	v_mfma_f32_16x16x32_bf16 v[52:55], v[132:135], v[188:191], v[52:55]
	v_mfma_f32_16x16x32_bf16 v[44:47], v[132:135], v[196:199], v[44:47]
	v_mfma_f32_16x16x32_bf16 v[44:47], v[148:151], v[214:217], v[44:47]
	v_mfma_f32_16x16x32_bf16 v[36:39], v[148:151], v[222:225], v[36:39]
	v_mfma_f32_16x16x32_bf16 v[36:39], v[132:135], v[218:221], v[36:39]
	v_mfma_f32_16x16x32_bf16 v[32:35], v[156:159], v[218:221], v[32:35]
	v_mfma_f32_16x16x32_bf16 v[32:35], v[160:163], v[222:225], v[32:35]
	v_mfma_f32_16x16x32_bf16 v[40:43], v[160:163], v[214:217], v[40:43]
	v_mfma_f32_16x16x32_bf16 v[40:43], v[156:159], v[196:199], v[40:43]
	v_mfma_f32_16x16x32_bf16 v[48:51], v[156:159], v[188:191], v[48:51]
	v_mfma_f32_16x16x32_bf16 v[48:51], v[160:163], v[192:195], v[48:51]
	v_mfma_f32_16x16x32_bf16 v[56:59], v[160:163], v[184:187], v[56:59]
	v_mfma_f32_16x16x32_bf16 v[56:59], v[156:159], v[180:183], v[56:59]


; #define PG8_MMA(ai, bj, At, Bt) do { __builtin_amdgcn_s_setprio(1); _Pragma("unroll") for (int m = 0; m < 4; ++m) _Pragma("unroll") for (int n = 0; n < 2; ++n) _Pragma("unroll") for (int k = 0; k < 2; ++k) \
;         acc[ai][bj][m][n] = __builtin_amdgcn_mfma_f32_16x16x32_bf16(Bt[n][k], At[m][k], acc[ai][bj][m][n], 0, 0, 0); __builtin_amdgcn_s_setprio(0); } while (0)
; #define PG8_WAIT_V(n) asm volatile("s_waitcnt vmcnt(" #n ")" ::: "memory")
; #define PG8_WAIT_L(n) asm volatile("s_waitcnt lgkmcnt(" #n ")" ::: "memory")
; #define PG8_BAR __builtin_amdgcn_s_barrier()
; #define PG8_SCHED __builtin_amdgcn_sched_barrier(0)
; template <class Epi, bool ALIGN_EPI>
; __device__ __forceinline__ void gemm_phase(LAS unsigned char* lds, const Gemm g, const StaticOrder& S, const Epi& E, const int tid) {
;     ...
;             PG8_WAIT_V(8); PG8_WAIT_L(0); PG8_BAR; PG8_MMA(0, 0, At, B0); PG8_MMA(0, 1, At, B1); PG8_BAR; PG8_SCHED;
	v_mfma_f32_16x16x32_bf16 v[28:31], v[172:175], v[180:183], v[28:31]
	v_mfma_f32_16x16x32_bf16 v[28:31], v[176:179], v[184:187], v[28:31]
	v_mfma_f32_16x16x32_bf16 v[92:95], v[176:179], v[192:195], v[92:95]
	v_mfma_f32_16x16x32_bf16 v[92:95], v[172:175], v[188:191], v[92:95]
	v_mfma_f32_16x16x32_bf16 v[84:87], v[172:175], v[196:199], v[84:87]
	v_mfma_f32_16x16x32_bf16 v[84:87], v[176:179], v[214:217], v[84:87]
	v_mfma_f32_16x16x32_bf16 v[76:79], v[176:179], v[222:225], v[76:79]
	v_mfma_f32_16x16x32_bf16 v[76:79], v[172:175], v[218:221], v[76:79]
	v_mfma_f32_16x16x32_bf16 v[80:83], v[164:167], v[218:221], v[80:83]
	v_mfma_f32_16x16x32_bf16 v[80:83], v[168:171], v[222:225], v[80:83]
	v_mfma_f32_16x16x32_bf16 v[88:91], v[168:171], v[214:217], v[88:91]
	v_mfma_f32_16x16x32_bf16 v[88:91], v[164:167], v[196:199], v[88:91]
	v_mfma_f32_16x16x32_bf16 v[96:99], v[164:167], v[188:191], v[96:99]
	v_mfma_f32_16x16x32_bf16 v[96:99], v[168:171], v[192:195], v[96:99]
	v_mfma_f32_16x16x32_bf16 v[2:5], v[164:167], v[180:183], v[4:7]
	v_mfma_f32_16x16x32_bf16 v[2:5], v[168:171], v[184:187], v[2:5]

; #define PG8_STAGE(bufoff, gbase, voff) do { _Pragma("unroll") for (int _i = 0; _i < 2; ++_i) \
;         __builtin_amdgcn_global_load_lds((const unsigned*)((const char*)(gbase) + (voff)[_i]), (LAS unsigned*)(lds + (bufoff) + ldsw + _i * 8192), 16, 0, 0); } while (0)
; #define PG8_LDA(dst, b, h) do { _Pragma("unroll") for (int m = 0; m < 4; ++m) _Pragma("unroll") for (int k = 0; k < 2; ++k) dst[m][k] = *(const LAS bf16x8*)(lds + PG8_SA(b, h) + aoff + m * 2048 + k * 1024); } while (0)
; template <class Epi, bool ALIGN_EPI>
; __device__ __forceinline__ void gemm_phase(LAS unsigned char* lds, const Gemm g, const StaticOrder& S, const Epi& E, const int tid) {
;     ...
;             PG8_LDA(At, 0, 1); PG8_STAGE(PG8_SB(0, 0), b2, voffB); PG8_STAGE(PG8_SB(0, 1), b2 + hstepB, voffB); PG8_STAGE(PG8_SA(0, 0), a2, voffA);
	s_barrier
	s_add_i32 s87, s87, s61
	s_mov_b32 m0, s87
	ds_read_b128 v[180:183], v155 offset:16384
	ds_read_b128 v[184:187], v155 offset:17408
	ds_read_b128 v[188:191], v155 offset:18432
	ds_read_b128 v[192:195], v155 offset:19456
	ds_read_b128 v[196:199], v155 offset:20480
	ds_read_b128 v[214:217], v155 offset:21504


; #define PG8_STAGE(bufoff, gbase, voff) do { _Pragma("unroll") for (int _i = 0; _i < 2; ++_i) \
;         __builtin_amdgcn_global_load_lds((const unsigned*)((const char*)(gbase) + (voff)[_i]), (LAS unsigned*)(lds + (bufoff) + ldsw + _i * 8192), 16, 0, 0); } while (0)
; #define PG8_LDA(dst, b, h) do { _Pragma("unroll") for (int m = 0; m < 4; ++m) _Pragma("unroll") for (int k = 0; k < 2; ++k) dst[m][k] = *(const LAS bf16x8*)(lds + PG8_SA(b, h) + aoff + m * 2048 + k * 1024); } while (0)
; #define PG8_MMA(ai, bj, At, Bt) do { __builtin_amdgcn_s_setprio(1); _Pragma("unroll") for (int m = 0; m < 4; ++m) _Pragma("unroll") for (int n = 0; n < 2; ++n) _Pragma("unroll") for (int k = 0; k < 2; ++k) \
;         acc[ai][bj][m][n] = __builtin_amdgcn_mfma_f32_16x16x32_bf16(Bt[n][k], At[m][k], acc[ai][bj][m][n], 0, 0, 0); __builtin_amdgcn_s_setprio(0); } while (0)
; #define PG8_WAIT_V(n) asm volatile("s_waitcnt vmcnt(" #n ")" ::: "memory")
; #define PG8_WAIT_L(n) asm volatile("s_waitcnt lgkmcnt(" #n ")" ::: "memory")
; #define PG8_BAR __builtin_amdgcn_s_barrier()
; #define PG8_SCHED __builtin_amdgcn_sched_barrier(0)
; template <class Epi, bool ALIGN_EPI>
; __device__ __forceinline__ void gemm_phase(LAS unsigned char* lds, const Gemm g, const StaticOrder& S, const Epi& E, const int tid) {
;     ...
;             PG8_LDA(At, 0, 1); PG8_STAGE(PG8_SB(0, 0), b2, voffB); PG8_STAGE(PG8_SB(0, 1), b2 + hstepB, voffB); PG8_STAGE(PG8_SA(0, 0), a2, voffA);
;             PG8_WAIT_V(8); PG8_WAIT_L(0); PG8_BAR; PG8_MMA(1, 0, At, B0); PG8_MMA(1, 1, At, B1); PG8_BAR; PG8_SCHED;
	global_load_lds_dwordx4 v140, s[22:23]
	s_add_i32 m0, s87, 0x2000
	s_add_u32 s88, s22, 0x4000
	s_addc_u32 s89, s23, 0
	s_add_i32 s87, s90, s61
	global_load_lds_dwordx4 v136, s[22:23]
	s_mov_b32 m0, s87
	v_lshl_add_u64 v[152:153], s[34:35], 0, v[142:143]
	global_load_lds_dwordx4 v140, s[88:89]
	s_add_i32 m0, s87, 0x2000
	v_lshl_add_u64 v[200:201], s[34:35], 0, v[138:139]
	global_load_lds_dwordx4 v136, s[88:89]
	s_mov_b32 m0, s70
	ds_read_b128 v[222:225], v155 offset:23552
	global_load_lds_dwordx4 v[152:153], off
	s_mov_b32 m0, s71
	ds_read_b128 v[218:221], v155 offset:22528
	global_load_lds_dwordx4 v[200:201], off
	s_waitcnt vmcnt(8)
	s_waitcnt lgkmcnt(0)
	s_barrier


; #define PG8_MMA(ai, bj, At, Bt) do { __builtin_amdgcn_s_setprio(1); _Pragma("unroll") for (int m = 0; m < 4; ++m) _Pragma("unroll") for (int n = 0; n < 2; ++n) _Pragma("unroll") for (int k = 0; k < 2; ++k) \
;         acc[ai][bj][m][n] = __builtin_amdgcn_mfma_f32_16x16x32_bf16(Bt[n][k], At[m][k], acc[ai][bj][m][n], 0, 0, 0); __builtin_amdgcn_s_setprio(0); } while (0)
; #define PG8_WAIT_V(n) asm volatile("s_waitcnt vmcnt(" #n ")" ::: "memory")
; #define PG8_WAIT_L(n) asm volatile("s_waitcnt lgkmcnt(" #n ")" ::: "memory")
; #define PG8_BAR __builtin_amdgcn_s_barrier()
; #define PG8_SCHED __builtin_amdgcn_sched_barrier(0)
; template <class Epi, bool ALIGN_EPI>
; __device__ __forceinline__ void gemm_phase(LAS unsigned char* lds, const Gemm g, const StaticOrder& S, const Epi& E, const int tid) {
;     ...
;             PG8_WAIT_V(8); PG8_WAIT_L(0); PG8_BAR; PG8_MMA(1, 0, At, B0); PG8_MMA(1, 1, At, B1); PG8_BAR; PG8_SCHED;
	v_mfma_f32_16x16x32_bf16 v[24:27], v[132:135], v[180:183], v[24:27]
	v_mfma_f32_16x16x32_bf16 v[24:27], v[148:151], v[184:187], v[24:27]
	v_mfma_f32_16x16x32_bf16 v[64:67], v[148:151], v[192:195], v[64:67]
	v_mfma_f32_16x16x32_bf16 v[64:67], v[132:135], v[188:191], v[64:67]
	v_mfma_f32_16x16x32_bf16 v[16:19], v[132:135], v[196:199], v[16:19]
	v_mfma_f32_16x16x32_bf16 v[16:19], v[148:151], v[214:217], v[16:19]
	v_mfma_f32_16x16x32_bf16 v[60:63], v[148:151], v[222:225], v[60:63]
	v_mfma_f32_16x16x32_bf16 v[60:63], v[132:135], v[218:221], v[60:63]
	v_mfma_f32_16x16x32_bf16 v[68:71], v[156:159], v[218:221], v[68:71]
	v_mfma_f32_16x16x32_bf16 v[68:71], v[160:163], v[222:225], v[68:71]
	v_mfma_f32_16x16x32_bf16 v[12:15], v[160:163], v[214:217], v[12:15]
	v_mfma_f32_16x16x32_bf16 v[12:15], v[156:159], v[196:199], v[12:15]
	v_mfma_f32_16x16x32_bf16 v[72:75], v[156:159], v[188:191], v[72:75]
	v_mfma_f32_16x16x32_bf16 v[72:75], v[160:163], v[192:195], v[72:75]
	v_mfma_f32_16x16x32_bf16 v[20:23], v[160:163], v[184:187], v[20:23]
	v_mfma_f32_16x16x32_bf16 v[20:23], v[156:159], v[180:183], v[20:23]


; #define PG8_MMA(ai, bj, At, Bt) do { __builtin_amdgcn_s_setprio(1); _Pragma("unroll") for (int m = 0; m < 4; ++m) _Pragma("unroll") for (int n = 0; n < 2; ++n) _Pragma("unroll") for (int k = 0; k < 2; ++k) \
;         acc[ai][bj][m][n] = __builtin_amdgcn_mfma_f32_16x16x32_bf16(Bt[n][k], At[m][k], acc[ai][bj][m][n], 0, 0, 0); __builtin_amdgcn_s_setprio(0); } while (0)
; #define PG8_WAIT_V(n) asm volatile("s_waitcnt vmcnt(" #n ")" ::: "memory")
; #define PG8_WAIT_L(n) asm volatile("s_waitcnt lgkmcnt(" #n ")" ::: "memory")
; #define PG8_BAR __builtin_amdgcn_s_barrier()
; #define PG8_SCHED __builtin_amdgcn_sched_barrier(0)
; template <class Epi, bool ALIGN_EPI>
; __device__ __forceinline__ void gemm_phase(LAS unsigned char* lds, const Gemm g, const StaticOrder& S, const Epi& E, const int tid) {
;     ...
;             PG8_WAIT_V(8); PG8_WAIT_L(0); PG8_BAR; PG8_MMA(1, 0, At, B0); PG8_MMA(1, 1, At, B1); PG8_BAR; PG8_SCHED;
	v_mfma_f32_16x16x32_bf16 v[124:127], v[172:175], v[180:183], v[124:127]
	v_mfma_f32_16x16x32_bf16 v[124:127], v[176:179], v[184:187], v[124:127]
	v_mfma_f32_16x16x32_bf16 v[116:119], v[176:179], v[192:195], v[116:119]
	v_mfma_f32_16x16x32_bf16 v[116:119], v[172:175], v[188:191], v[116:119]
	v_mfma_f32_16x16x32_bf16 v[108:111], v[172:175], v[196:199], v[108:111]
	v_mfma_f32_16x16x32_bf16 v[108:111], v[176:179], v[214:217], v[108:111]
	v_mfma_f32_16x16x32_bf16 v[100:103], v[176:179], v[222:225], v[100:103]
	v_mfma_f32_16x16x32_bf16 v[100:103], v[172:175], v[218:221], v[100:103]
	v_mfma_f32_16x16x32_bf16 v[104:107], v[164:167], v[218:221], v[104:107]
	v_mfma_f32_16x16x32_bf16 v[104:107], v[168:171], v[222:225], v[104:107]
	v_mfma_f32_16x16x32_bf16 v[112:115], v[168:171], v[214:217], v[112:115]
	v_mfma_f32_16x16x32_bf16 v[112:115], v[164:167], v[196:199], v[112:115]
	v_mfma_f32_16x16x32_bf16 v[120:123], v[164:167], v[188:191], v[120:123]
	v_mfma_f32_16x16x32_bf16 v[120:123], v[168:171], v[192:195], v[120:123]
	v_mfma_f32_16x16x32_bf16 v[128:131], v[168:171], v[184:187], v[128:131]
	v_mfma_f32_16x16x32_bf16 v[128:131], v[164:167], v[180:183], v[128:131]

; #define PG8_STAGE(bufoff, gbase, voff) do { _Pragma("unroll") for (int _i = 0; _i < 2; ++_i) \
;         __builtin_amdgcn_global_load_lds((const unsigned*)((const char*)(gbase) + (voff)[_i]), (LAS unsigned*)(lds + (bufoff) + ldsw + _i * 8192), 16, 0, 0); } while (0)
; #define PG8_LDA(dst, b, h) do { _Pragma("unroll") for (int m = 0; m < 4; ++m) _Pragma("unroll") for (int k = 0; k < 2; ++k) dst[m][k] = *(const LAS bf16x8*)(lds + PG8_SA(b, h) + aoff + m * 2048 + k * 1024); } while (0)
; #define PG8_LDB(dst, b, h) do { _Pragma("unroll") for (int n = 0; n < 2; ++n) _Pragma("unroll") for (int k = 0; k < 2; ++k) dst[n][k] = *(const LAS bf16x8*)(lds + PG8_SB(b, h) + boff + n * 2048 + k * 1024); } while (0)
; #define PG8_SCHED __builtin_amdgcn_sched_barrier(0)
; template <class Epi, bool ALIGN_EPI>
; __device__ __forceinline__ void gemm_phase(LAS unsigned char* lds, const Gemm g, const StaticOrder& S, const Epi& E, const int tid) {
;     ...
;             PG8_LDB(B0, 1, 0); PG8_LDB(B1, 1, 1); PG8_SCHED; PG8_LDA(At, 1, 0); PG8_STAGE(PG8_SA(0, 1), a2 + hstepA, voffA);
	s_barrier
	s_add_i32 s87, 0, 0x18000
	v_add_u32_e32 v0, s87, v154
	s_add_i32 s88, 0, 0x1c000
	ds_read_b128 v[132:135], v0
	ds_read_b128 v[148:151], v0 offset:1024
	ds_read_b128 v[156:159], v0 offset:2048
	ds_read_b128 v[160:163], v0 offset:3072
	v_add_u32_e32 v0, s88, v154
	ds_read_b128 v[164:167], v0
	ds_read_b128 v[168:171], v0 offset:1024
	ds_read_b128 v[172:175], v0 offset:2048
	ds_read_b128 v[176:179], v0 offset:3072
	s_add_u32 s34, s34, 0x80000
	s_addc_u32 s35, s35, 0
	s_mov_b32 m0, s72
	ds_read_b128 v[180:183], v155 offset:32768
	ds_read_b128 v[184:187], v155 offset:33792
	ds_read_b128 v[188:191], v155 offset:34816
	ds_read_b128 v[192:195], v155 offset:35840
	ds_read_b128 v[196:199], v155 offset:36864
	ds_read_b128 v[214:217], v155 offset:37888
	ds_read_b128 v[218:221], v155 offset:38912

; #define PG8_STAGE(bufoff, gbase, voff) do { _Pragma("unroll") for (int _i = 0; _i < 2; ++_i) \
;         __builtin_amdgcn_global_load_lds((const unsigned*)((const char*)(gbase) + (voff)[_i]), (LAS unsigned*)(lds + (bufoff) + ldsw + _i * 8192), 16, 0, 0); } while (0)
; #define PG8_LDA(dst, b, h) do { _Pragma("unroll") for (int m = 0; m < 4; ++m) _Pragma("unroll") for (int k = 0; k < 2; ++k) dst[m][k] = *(const LAS bf16x8*)(lds + PG8_SA(b, h) + aoff + m * 2048 + k * 1024); } while (0)
; #define PG8_LDB(dst, b, h) do { _Pragma("unroll") for (int n = 0; n < 2; ++n) _Pragma("unroll") for (int k = 0; k < 2; ++k) dst[n][k] = *(const LAS bf16x8*)(lds + PG8_SB(b, h) + boff + n * 2048 + k * 1024); } while (0)
; #define PG8_MMA(ai, bj, At, Bt) do { __builtin_amdgcn_s_setprio(1); _Pragma("unroll") for (int m = 0; m < 4; ++m) _Pragma("unroll") for (int n = 0; n < 2; ++n) _Pragma("unroll") for (int k = 0; k < 2; ++k) \
;         acc[ai][bj][m][n] = __builtin_amdgcn_mfma_f32_16x16x32_bf16(Bt[n][k], At[m][k], acc[ai][bj][m][n], 0, 0, 0); __builtin_amdgcn_s_setprio(0); } while (0)
; #define PG8_WAIT_V(n) asm volatile("s_waitcnt vmcnt(" #n ")" ::: "memory")
; #define PG8_WAIT_L(n) asm volatile("s_waitcnt lgkmcnt(" #n ")" ::: "memory")
; #define PG8_BAR __builtin_amdgcn_s_barrier()
; #define PG8_SCHED __builtin_amdgcn_sched_barrier(0)
; template <class Epi, bool ALIGN_EPI>
; __device__ __forceinline__ void gemm_phase(LAS unsigned char* lds, const Gemm g, const StaticOrder& S, const Epi& E, const int tid) {
;     ...
;             PG8_LDB(B0, 1, 0); PG8_LDB(B1, 1, 1); PG8_SCHED; PG8_LDA(At, 1, 0); PG8_STAGE(PG8_SA(0, 1), a2 + hstepA, voffA);
;             PG8_WAIT_V(8); PG8_WAIT_L(0); PG8_BAR; PG8_MMA(0, 0, At, B0); PG8_MMA(0, 1, At, B1); PG8_BAR; PG8_SCHED;
	global_load_lds_dwordx4 v142, s[34:35]
	s_mov_b32 m0, s73
	ds_read_b128 v[222:225], v155 offset:39936
	global_load_lds_dwordx4 v138, s[34:35]
	s_waitcnt vmcnt(8)
	s_waitcnt lgkmcnt(0)
	s_barrier


; #define PG8_MMA(ai, bj, At, Bt) do { __builtin_amdgcn_s_setprio(1); _Pragma("unroll") for (int m = 0; m < 4; ++m) _Pragma("unroll") for (int n = 0; n < 2; ++n) _Pragma("unroll") for (int k = 0; k < 2; ++k) \
;         acc[ai][bj][m][n] = __builtin_amdgcn_mfma_f32_16x16x32_bf16(Bt[n][k], At[m][k], acc[ai][bj][m][n], 0, 0, 0); __builtin_amdgcn_s_setprio(0); } while (0)
; #define PG8_WAIT_V(n) asm volatile("s_waitcnt vmcnt(" #n ")" ::: "memory")
; #define PG8_WAIT_L(n) asm volatile("s_waitcnt lgkmcnt(" #n ")" ::: "memory")
; #define PG8_BAR __builtin_amdgcn_s_barrier()
; #define PG8_SCHED __builtin_amdgcn_sched_barrier(0)
; template <class Epi, bool ALIGN_EPI>
; __device__ __forceinline__ void gemm_phase(LAS unsigned char* lds, const Gemm g, const StaticOrder& S, const Epi& E, const int tid) {
;     ...
;             PG8_WAIT_V(8); PG8_WAIT_L(0); PG8_BAR; PG8_MMA(0, 0, At, B0); PG8_MMA(0, 1, At, B1); PG8_BAR; PG8_SCHED;
	v_mfma_f32_16x16x32_bf16 v[6:9], v[132:135], v[180:183], v[8:11]
	v_mfma_f32_16x16x32_bf16 v[8:11], v[148:151], v[184:187], v[6:9]
	v_mfma_f32_16x16x32_bf16 v[52:55], v[148:151], v[192:195], v[52:55]
	v_mfma_f32_16x16x32_bf16 v[52:55], v[132:135], v[188:191], v[52:55]
	v_mfma_f32_16x16x32_bf16 v[44:47], v[132:135], v[196:199], v[44:47]
	v_mfma_f32_16x16x32_bf16 v[44:47], v[148:151], v[214:217], v[44:47]
	v_mfma_f32_16x16x32_bf16 v[36:39], v[148:151], v[222:225], v[36:39]
	v_mfma_f32_16x16x32_bf16 v[36:39], v[132:135], v[218:221], v[36:39]
	v_mfma_f32_16x16x32_bf16 v[32:35], v[156:159], v[218:221], v[32:35]
	v_mfma_f32_16x16x32_bf16 v[32:35], v[160:163], v[222:225], v[32:35]
	v_mfma_f32_16x16x32_bf16 v[40:43], v[160:163], v[214:217], v[40:43]
	v_mfma_f32_16x16x32_bf16 v[40:43], v[156:159], v[196:199], v[40:43]
	v_mfma_f32_16x16x32_bf16 v[48:51], v[156:159], v[188:191], v[48:51]
	v_mfma_f32_16x16x32_bf16 v[48:51], v[160:163], v[192:195], v[48:51]
	v_mfma_f32_16x16x32_bf16 v[56:59], v[160:163], v[184:187], v[56:59]
	v_mfma_f32_16x16x32_bf16 v[56:59], v[156:159], v[180:183], v[56:59]


; #define PG8_MMA(ai, bj, At, Bt) do { __builtin_amdgcn_s_setprio(1); _Pragma("unroll") for (int m = 0; m < 4; ++m) _Pragma("unroll") for (int n = 0; n < 2; ++n) _Pragma("unroll") for (int k = 0; k < 2; ++k) \
;         acc[ai][bj][m][n] = __builtin_amdgcn_mfma_f32_16x16x32_bf16(Bt[n][k], At[m][k], acc[ai][bj][m][n], 0, 0, 0); __builtin_amdgcn_s_setprio(0); } while (0)
; #define PG8_WAIT_V(n) asm volatile("s_waitcnt vmcnt(" #n ")" ::: "memory")
; #define PG8_WAIT_L(n) asm volatile("s_waitcnt lgkmcnt(" #n ")" ::: "memory")
; #define PG8_BAR __builtin_amdgcn_s_barrier()
; #define PG8_SCHED __builtin_amdgcn_sched_barrier(0)
; template <class Epi, bool ALIGN_EPI>
; __device__ __forceinline__ void gemm_phase(LAS unsigned char* lds, const Gemm g, const StaticOrder& S, const Epi& E, const int tid) {
;     ...
;             PG8_WAIT_V(8); PG8_WAIT_L(0); PG8_BAR; PG8_MMA(0, 0, At, B0); PG8_MMA(0, 1, At, B1); PG8_BAR; PG8_SCHED;
	v_mfma_f32_16x16x32_bf16 v[28:31], v[172:175], v[180:183], v[28:31]
	v_mfma_f32_16x16x32_bf16 v[28:31], v[176:179], v[184:187], v[28:31]
	v_mfma_f32_16x16x32_bf16 v[92:95], v[176:179], v[192:195], v[92:95]
	v_mfma_f32_16x16x32_bf16 v[92:95], v[172:175], v[188:191], v[92:95]
	v_mfma_f32_16x16x32_bf16 v[84:87], v[172:175], v[196:199], v[84:87]
	v_mfma_f32_16x16x32_bf16 v[84:87], v[176:179], v[214:217], v[84:87]
	v_mfma_f32_16x16x32_bf16 v[76:79], v[176:179], v[222:225], v[76:79]
	v_mfma_f32_16x16x32_bf16 v[76:79], v[172:175], v[218:221], v[76:79]
	v_mfma_f32_16x16x32_bf16 v[80:83], v[164:167], v[218:221], v[80:83]
	v_mfma_f32_16x16x32_bf16 v[80:83], v[168:171], v[222:225], v[80:83]
	v_mfma_f32_16x16x32_bf16 v[88:91], v[168:171], v[214:217], v[88:91]
	v_mfma_f32_16x16x32_bf16 v[88:91], v[164:167], v[196:199], v[88:91]
	v_mfma_f32_16x16x32_bf16 v[96:99], v[164:167], v[188:191], v[96:99]
	v_mfma_f32_16x16x32_bf16 v[96:99], v[168:171], v[192:195], v[96:99]
	v_mfma_f32_16x16x32_bf16 v[2:5], v[164:167], v[180:183], v[2:5]
	v_mfma_f32_16x16x32_bf16 v[4:7], v[168:171], v[184:187], v[2:5]

; #define PG8_STAGE(bufoff, gbase, voff) do { _Pragma("unroll") for (int _i = 0; _i < 2; ++_i) \
;         __builtin_amdgcn_global_load_lds((const unsigned*)((const char*)(gbase) + (voff)[_i]), (LAS unsigned*)(lds + (bufoff) + ldsw + _i * 8192), 16, 0, 0); } while (0)
; #define PG8_LDA(dst, b, h) do { _Pragma("unroll") for (int m = 0; m < 4; ++m) _Pragma("unroll") for (int k = 0; k < 2; ++k) dst[m][k] = *(const LAS bf16x8*)(lds + PG8_SA(b, h) + aoff + m * 2048 + k * 1024); } while (0)
; template <class Epi, bool ALIGN_EPI>
; __device__ __forceinline__ void gemm_phase(LAS unsigned char* lds, const Gemm g, const StaticOrder& S, const Epi& E, const int tid) {
;     ...
;             PG8_LDA(At, 1, 1); PG8_STAGE(PG8_SB(1, 0), b3, voffB); PG8_STAGE(PG8_SB(1, 1), b3 + hstepB, voffB); PG8_STAGE(PG8_SA(1, 0), a3, voffA);
	s_barrier
	s_add_u32 s34, s22, 0x8000
	s_addc_u32 s35, s23, 0
	s_add_i32 s87, s87, s61
	s_mov_b32 m0, s87
	ds_read_b128 v[180:183], v155 offset:49152
	ds_read_b128 v[184:187], v155 offset:50176
	ds_read_b128 v[188:191], v155 offset:51200
	ds_read_b128 v[192:195], v155 offset:52224


; #define PG8_STAGE(bufoff, gbase, voff) do { _Pragma("unroll") for (int _i = 0; _i < 2; ++_i) \
;         __builtin_amdgcn_global_load_lds((const unsigned*)((const char*)(gbase) + (voff)[_i]), (LAS unsigned*)(lds + (bufoff) + ldsw + _i * 8192), 16, 0, 0); } while (0)
; #define PG8_LDA(dst, b, h) do { _Pragma("unroll") for (int m = 0; m < 4; ++m) _Pragma("unroll") for (int k = 0; k < 2; ++k) dst[m][k] = *(const LAS bf16x8*)(lds + PG8_SA(b, h) + aoff + m * 2048 + k * 1024); } while (0)
; #define PG8_MMA(ai, bj, At, Bt) do { __builtin_amdgcn_s_setprio(1); _Pragma("unroll") for (int m = 0; m < 4; ++m) _Pragma("unroll") for (int n = 0; n < 2; ++n) _Pragma("unroll") for (int k = 0; k < 2; ++k) \
;         acc[ai][bj][m][n] = __builtin_amdgcn_mfma_f32_16x16x32_bf16(Bt[n][k], At[m][k], acc[ai][bj][m][n], 0, 0, 0); __builtin_amdgcn_s_setprio(0); } while (0)
; #define PG8_WAIT_V(n) asm volatile("s_waitcnt vmcnt(" #n ")" ::: "memory")
; #define PG8_WAIT_L(n) asm volatile("s_waitcnt lgkmcnt(" #n ")" ::: "memory")
; #define PG8_BAR __builtin_amdgcn_s_barrier()
; #define PG8_SCHED __builtin_amdgcn_sched_barrier(0)
; template <class Epi, bool ALIGN_EPI>
; __device__ __forceinline__ void gemm_phase(LAS unsigned char* lds, const Gemm g, const StaticOrder& S, const Epi& E, const int tid) {
;     ...
;             PG8_LDA(At, 1, 1); PG8_STAGE(PG8_SB(1, 0), b3, voffB); PG8_STAGE(PG8_SB(1, 1), b3 + hstepB, voffB); PG8_STAGE(PG8_SA(1, 0), a3, voffA);
;             PG8_WAIT_V(8); PG8_WAIT_L(0); PG8_BAR; PG8_MMA(1, 0, At, B0); PG8_MMA(1, 1, At, B1); PG8_BAR; PG8_SCHED;
	global_load_lds_dwordx4 v140, s[34:35]
	s_add_i32 m0, s87, 0x2000
	s_add_u32 s22, s22, 0xc000
	s_addc_u32 s23, s23, 0
	global_load_lds_dwordx4 v136, s[34:35]
	s_add_i32 s34, s88, s61
	s_mov_b32 m0, s34
	ds_read_b128 v[222:225], v155 offset:56320
	global_load_lds_dwordx4 v140, s[22:23]
	s_add_i32 m0, s34, 0x2000
	ds_read_b128 v[218:221], v155 offset:55296
	global_load_lds_dwordx4 v136, s[22:23]
	v_lshl_add_u64 v[2:3], v[152:153], 0, s[6:7]
	s_mov_b32 m0, s78
	ds_read_b128 v[214:217], v155 offset:54272
	global_load_lds_dwordx4 v[2:3], off
	v_lshl_add_u64 v[2:3], v[200:201], 0, s[6:7]
	s_mov_b32 m0, s79
	ds_read_b128 v[196:199], v155 offset:53248
	global_load_lds_dwordx4 v[2:3], off
	s_waitcnt vmcnt(8)
	s_waitcnt lgkmcnt(0)
	s_barrier


; #define PG8_MMA(ai, bj, At, Bt) do { __builtin_amdgcn_s_setprio(1); _Pragma("unroll") for (int m = 0; m < 4; ++m) _Pragma("unroll") for (int n = 0; n < 2; ++n) _Pragma("unroll") for (int k = 0; k < 2; ++k) \
;         acc[ai][bj][m][n] = __builtin_amdgcn_mfma_f32_16x16x32_bf16(Bt[n][k], At[m][k], acc[ai][bj][m][n], 0, 0, 0); __builtin_amdgcn_s_setprio(0); } while (0)
; #define PG8_WAIT_V(n) asm volatile("s_waitcnt vmcnt(" #n ")" ::: "memory")
; #define PG8_WAIT_L(n) asm volatile("s_waitcnt lgkmcnt(" #n ")" ::: "memory")
; #define PG8_BAR __builtin_amdgcn_s_barrier()
; #define PG8_SCHED __builtin_amdgcn_sched_barrier(0)
; template <class Epi, bool ALIGN_EPI>
; __device__ __forceinline__ void gemm_phase(LAS unsigned char* lds, const Gemm g, const StaticOrder& S, const Epi& E, const int tid) {
;     ...
;             PG8_WAIT_V(8); PG8_WAIT_L(0); PG8_BAR; PG8_MMA(1, 0, At, B0); PG8_MMA(1, 1, At, B1); PG8_BAR; PG8_SCHED;
	v_mfma_f32_16x16x32_bf16 v[24:27], v[132:135], v[180:183], v[24:27]
	v_mfma_f32_16x16x32_bf16 v[24:27], v[148:151], v[184:187], v[24:27]
	v_mfma_f32_16x16x32_bf16 v[64:67], v[148:151], v[192:195], v[64:67]
	v_mfma_f32_16x16x32_bf16 v[64:67], v[132:135], v[188:191], v[64:67]
	v_mfma_f32_16x16x32_bf16 v[16:19], v[132:135], v[196:199], v[16:19]
	v_mfma_f32_16x16x32_bf16 v[16:19], v[148:151], v[214:217], v[16:19]
	v_mfma_f32_16x16x32_bf16 v[60:63], v[148:151], v[222:225], v[60:63]
	v_mfma_f32_16x16x32_bf16 v[60:63], v[132:135], v[218:221], v[60:63]
	v_mfma_f32_16x16x32_bf16 v[68:71], v[156:159], v[218:221], v[68:71]
	v_mfma_f32_16x16x32_bf16 v[68:71], v[160:163], v[222:225], v[68:71]
	v_mfma_f32_16x16x32_bf16 v[12:15], v[160:163], v[214:217], v[12:15]
	v_mfma_f32_16x16x32_bf16 v[12:15], v[156:159], v[196:199], v[12:15]
	v_mfma_f32_16x16x32_bf16 v[72:75], v[156:159], v[188:191], v[72:75]
	v_mfma_f32_16x16x32_bf16 v[72:75], v[160:163], v[192:195], v[72:75]
	v_mfma_f32_16x16x32_bf16 v[20:23], v[160:163], v[184:187], v[20:23]
	v_mfma_f32_16x16x32_bf16 v[20:23], v[156:159], v[180:183], v[20:23]


; #define PG8_MMA(ai, bj, At, Bt) do { __builtin_amdgcn_s_setprio(1); _Pragma("unroll") for (int m = 0; m < 4; ++m) _Pragma("unroll") for (int n = 0; n < 2; ++n) _Pragma("unroll") for (int k = 0; k < 2; ++k) \
;         acc[ai][bj][m][n] = __builtin_amdgcn_mfma_f32_16x16x32_bf16(Bt[n][k], At[m][k], acc[ai][bj][m][n], 0, 0, 0); __builtin_amdgcn_s_setprio(0); } while (0)
; #define PG8_WAIT_V(n) asm volatile("s_waitcnt vmcnt(" #n ")" ::: "memory")
; #define PG8_WAIT_L(n) asm volatile("s_waitcnt lgkmcnt(" #n ")" ::: "memory")
; #define PG8_BAR __builtin_amdgcn_s_barrier()
; #define PG8_SCHED __builtin_amdgcn_sched_barrier(0)
; template <class Epi, bool ALIGN_EPI>
; __device__ __forceinline__ void gemm_phase(LAS unsigned char* lds, const Gemm g, const StaticOrder& S, const Epi& E, const int tid) {
;     ...
;             PG8_WAIT_V(8); PG8_WAIT_L(0); PG8_BAR; PG8_MMA(1, 0, At, B0); PG8_MMA(1, 1, At, B1); PG8_BAR; PG8_SCHED;
	v_mfma_f32_16x16x32_bf16 v[124:127], v[172:175], v[180:183], v[124:127]
	v_mfma_f32_16x16x32_bf16 v[124:127], v[176:179], v[184:187], v[124:127]
	v_mfma_f32_16x16x32_bf16 v[116:119], v[176:179], v[192:195], v[116:119]
	v_mfma_f32_16x16x32_bf16 v[116:119], v[172:175], v[188:191], v[116:119]
	v_mfma_f32_16x16x32_bf16 v[108:111], v[172:175], v[196:199], v[108:111]
	v_mfma_f32_16x16x32_bf16 v[108:111], v[176:179], v[214:217], v[108:111]
	v_mfma_f32_16x16x32_bf16 v[100:103], v[176:179], v[222:225], v[100:103]
	v_mfma_f32_16x16x32_bf16 v[100:103], v[172:175], v[218:221], v[100:103]
	v_mfma_f32_16x16x32_bf16 v[104:107], v[164:167], v[218:221], v[104:107]
	v_mfma_f32_16x16x32_bf16 v[104:107], v[168:171], v[222:225], v[104:107]
	v_mfma_f32_16x16x32_bf16 v[112:115], v[168:171], v[214:217], v[112:115]
	v_mfma_f32_16x16x32_bf16 v[112:115], v[164:167], v[196:199], v[112:115]
	v_mfma_f32_16x16x32_bf16 v[120:123], v[164:167], v[188:191], v[120:123]
	v_mfma_f32_16x16x32_bf16 v[120:123], v[168:171], v[192:195], v[120:123]
	v_mfma_f32_16x16x32_bf16 v[128:131], v[168:171], v[184:187], v[128:131]
	v_mfma_f32_16x16x32_bf16 v[128:131], v[164:167], v[180:183], v[128:131]

; template <class Epi, bool ALIGN_EPI>
; __device__ __forceinline__ void gemm_phase(LAS unsigned char* lds, const Gemm g, const StaticOrder& S, const Epi& E, const int tid) {
;     ...
;         for (int t = 0; t < nt; t += 2) {
;             const bool last = (t == nt - 2);
;             const char* a1 = cA + (size_t)(t + 1) * kstepA;
;             const char* a2 = last ? nA : cA + (size_t)(t + 2) * kstepA; const char* b2 = last ? nB : cB + (size_t)(t + 2) * kstepB;
;             const char* a3 = a2 + kstepA; const char* b3 = b2 + kstepB;
;             PG8_LDB(B0, 0, 0); PG8_LDB(B1, 0, 1); PG8_SCHED; PG8_LDA(At, 0, 0); PG8_STAGE(PG8_SA(1, 1), a1 + hstepA, voffA);
;             PG8_WAIT_V(8); PG8_WAIT_L(0); PG8_BAR; PG8_MMA(0, 0, At, B0); PG8_MMA(0, 1, At, B1); PG8_BAR; PG8_SCHED;
;             PG8_LDA(At, 0, 1); PG8_STAGE(PG8_SB(0, 0), b2, voffB); PG8_STAGE(PG8_SB(0, 1), b2 + hstepB, voffB); PG8_STAGE(PG8_SA(0, 0), a2, voffA);
;             PG8_WAIT_V(8); PG8_WAIT_L(0); PG8_BAR; PG8_MMA(1, 0, At, B0); PG8_MMA(1, 1, At, B1); PG8_BAR; PG8_SCHED;
;             PG8_LDB(B0, 1, 0); PG8_LDB(B1, 1, 1); PG8_SCHED; PG8_LDA(At, 1, 0); PG8_STAGE(PG8_SA(0, 1), a2 + hstepA, voffA);
;             PG8_WAIT_V(8); PG8_WAIT_L(0); PG8_BAR; PG8_MMA(0, 0, At, B0); PG8_MMA(0, 1, At, B1); PG8_BAR; PG8_SCHED;
;             PG8_LDA(At, 1, 1); PG8_STAGE(PG8_SB(1, 0), b3, voffB); PG8_STAGE(PG8_SB(1, 1), b3 + hstepB, voffB); PG8_STAGE(PG8_SA(1, 0), a3, voffA);
;             PG8_WAIT_V(8); PG8_WAIT_L(0); PG8_BAR; PG8_MMA(1, 0, At, B0); PG8_MMA(1, 1, At, B1); PG8_BAR; PG8_SCHED;
;         }
;         if constexpr (ALIGN_EPI) { if (wr == 0) PG8_BAR; }
;     __device__ __forceinline__ void operator()(f32x4 (&acc)[2][2][4][2], const Unit& u, int wr, int wc, LAS unsigned char* lds, int& rs_pm) const {
;         int fr, fq; epi_lane(fr, fq);
;         const int row0 = u.pm * BM + wr * 64 + fr, col0 = u.pn * BM + wc * 32 + 8 * fq; u32x4 zb = zero_frag();
; #pragma unroll
;         for (int ai = 0; ai < 2; ++ai)
; #pragma unroll
;             for (int m = 0; m < 4; ++m) { float ss = 0.f;
;                 bf16* const xrow = xb + (((size_t)(u.pm * 32 + u.pn * 4 + (wc >> 1)) * BM + (wr * 64 + fr + ai * HALF + m * 16)) * 64 + (wc & 1) * 32 + 8 * fq);
; #pragma unroll
;                 for (int bj = 0; bj < 2; ++bj) {
;                     const u32x4 xw = *(const u32x4*)(xrow + (size_t)bj * (2 * BM * 64));
	s_barrier
	s_add_i32 s86, s86, 2
	s_add_u32 s10, s10, 0x100
	s_addc_u32 s11, s11, 0
	s_add_u32 s84, s84, 0x10000
	s_addc_u32 s85, s85, 0
	s_cmp_gt_u32 s86, 29
	s_cbranch_scc0 .LBB0_847
	v_and_b32_e32 v222, 15, v238
	v_lshrrev_b32_e32 v156, 4, v238
	s_lshl_b32 s100, s40, 5
	s_lshl_b32 s101, s41, 2
	v_lshlrev_b32_e32 v222, 7, v222
	s_add_i32 s100, s100, s101
	s_or_b32 s100, s100, s80
	v_lshl_or_b32 v222, v156, 4, v222
	s_ashr_i32 s101, s100, 31
	s_lshl_b64 s[100:101], s[100:101], 15
	s_add_u32 s98, s74, s100
	s_addc_u32 s99, s75, s101
	s_add_u32 s98, s98, s30
	s_addc_u32 s99, s99, s31
	s_lshl_b32 s100, s77, 7
	s_add_u32 s98, s98, s100
	s_addc_u32 s99, s99, 0
	s_lshl_b32 s100, s40, 15
	s_lshl_b32 s101, s77, 7
	s_add_i32 s100, s100, s101
	s_lshl_b32 s101, s41, 4
	s_add_i32 s100, s100, s101
	s_lshl_b32 s101, s76, 2
	s_add_i32 s100, s100, s101
	s_add_u32 s22, s42, s100
	s_addc_u32 s23, s43, 0
	global_load_dwordx4 v[176:179], v222, s[98:99]
	s_add_u32 s100, s98, 0x10000
	s_addc_u32 s101, s99, 0
	global_load_dwordx4 v[180:183], v222, s[100:101]
	global_load_dwordx4 v[184:187], v222, s[98:99] offset:2048
	s_add_u32 s100, s98, 0x10000
	s_addc_u32 s101, s99, 0
	global_load_dwordx4 v[188:191], v222, s[100:101] offset:2048
	s_add_u32 s100, s98, 0x1000
	s_addc_u32 s101, s99, 0
	global_load_dwordx4 v[192:195], v222, s[100:101]
	s_add_u32 s100, s98, 0x11000
	s_addc_u32 s101, s99, 0
	global_load_dwordx4 v[196:199], v222, s[100:101]
	s_add_u32 s100, s98, 0x1000
	s_addc_u32 s101, s99, 0
	global_load_dwordx4 v[214:217], v222, s[100:101] offset:2048
	s_add_u32 s100, s98, 0x11000
	s_addc_u32 s101, s99, 0
	global_load_dwordx4 v[218:221], v222, s[100:101] offset:2048
	s_and_b64 vcc, exec, s[44:45]
	s_cbranch_vccz .LBB0_850
	s_barrier
